# K-loop: rendezvous directly after the last MFMA and the duplicate lgkmcnt(0) before each MFMA cluster removed
# baseline (speedup 1.0000x reference)
.LBB0_151:
	s_add_i32 s43, s8, 2
	s_add_u32 s9, s6, 0x4000
	s_addc_u32 s10, s7, 0
	s_cmp_eq_u32 s30, s8
	s_cselect_b32 s12, s0, s9
	s_cselect_b32 s13, s1, s10
	s_cselect_b32 s8, s2, s41
	s_cselect_b32 s9, s3, s42
	s_add_u32 s10, s12, 0x8000
	s_addc_u32 s11, s13, 0
	s_add_i32 s44, 0, 0x10000
	v_add_u32_e32 v154, s44, v174
	ds_read_b128 v[142:145], v154
	ds_read_b128 v[146:149], v154 offset:1024
	ds_read_b128 v[150:153], v154 offset:2048
	ds_read_b128 v[154:157], v154 offset:3072
	v_lshl_add_u64 v[168:169], s[6:7], 0, v[138:139]
	s_add_i32 m0, s19, 0xc000
	ds_read_b128 v[158:161], v175
	ds_read_b128 v[176:179], v175 offset:1024
	ds_read_b128 v[180:183], v175 offset:2048
	ds_read_b128 v[184:187], v175 offset:3072
	ds_read_b128 v[188:191], v175 offset:4096
	ds_read_b128 v[192:195], v175 offset:5120
	ds_read_b128 v[196:199], v175 offset:6144
	ds_read_b128 v[200:203], v175 offset:7168
	global_load_lds_dwordx4 v[168:169], off
	v_lshl_add_u64 v[168:169], s[6:7], 0, v[140:141]
	s_add_i32 m0, s19, 0xe000
	s_nop 0
	global_load_lds_dwordx4 v[168:169], off
	s_waitcnt lgkmcnt(8)
	s_barrier
	s_waitcnt lgkmcnt(0)
	v_mfma_f32_16x16x32_bf16 v[126:129], v[142:145], v[158:161], v[126:129]
	v_mfma_f32_16x16x32_bf16 v[122:125], v[150:153], v[158:161], v[122:125]
	v_mfma_f32_16x16x32_bf16 v[110:113], v[142:145], v[180:183], v[110:113]
	v_mfma_f32_16x16x32_bf16 v[106:109], v[150:153], v[180:183], v[106:109]
	v_mfma_f32_16x16x32_bf16 v[94:97], v[142:145], v[188:191], v[94:97]
	v_mfma_f32_16x16x32_bf16 v[90:93], v[150:153], v[188:191], v[90:93]
	v_mfma_f32_16x16x32_bf16 v[78:81], v[142:145], v[196:199], v[78:81]
	v_mfma_f32_16x16x32_bf16 v[74:77], v[150:153], v[196:199], v[74:77]
	v_mfma_f32_16x16x32_bf16 v[126:129], v[146:149], v[176:179], v[126:129]
	v_mfma_f32_16x16x32_bf16 v[122:125], v[154:157], v[176:179], v[122:125]
	v_mfma_f32_16x16x32_bf16 v[110:113], v[146:149], v[184:187], v[110:113]
	v_mfma_f32_16x16x32_bf16 v[106:109], v[154:157], v[184:187], v[106:109]
	v_mfma_f32_16x16x32_bf16 v[94:97], v[146:149], v[192:195], v[94:97]
	v_mfma_f32_16x16x32_bf16 v[90:93], v[154:157], v[192:195], v[90:93]
	v_mfma_f32_16x16x32_bf16 v[78:81], v[146:149], v[200:203], v[78:81]
	v_mfma_f32_16x16x32_bf16 v[74:77], v[154:157], v[200:203], v[74:77]
	s_barrier
	s_add_i32 s46, 0, 0x14000
	v_add_u32_e32 v168, s46, v174
	s_add_i32 s44, s44, s18
	ds_read_b128 v[204:207], v168
	ds_read_b128 v[208:211], v168 offset:1024
	ds_read_b128 v[212:215], v168 offset:2048
	ds_read_b128 v[216:219], v168 offset:3072
	v_lshl_add_u64 v[168:169], s[8:9], 0, v[132:133]
	s_mov_b32 m0, s44
	v_lshl_add_u64 v[172:173], s[8:9], 0, v[136:137]
	global_load_lds_dwordx4 v[168:169], off
	s_add_i32 m0, s44, 0x2000
	s_nop 0
	global_load_lds_dwordx4 v[172:173], off
	s_barrier
	s_waitcnt lgkmcnt(0)
	v_mfma_f32_16x16x32_bf16 v[118:121], v[204:207], v[158:161], v[118:121]
	v_mfma_f32_16x16x32_bf16 v[114:117], v[212:215], v[158:161], v[114:117]
	v_mfma_f32_16x16x32_bf16 v[102:105], v[204:207], v[180:183], v[102:105]
	v_mfma_f32_16x16x32_bf16 v[98:101], v[212:215], v[180:183], v[98:101]
	v_mfma_f32_16x16x32_bf16 v[86:89], v[204:207], v[188:191], v[86:89]
	v_mfma_f32_16x16x32_bf16 v[82:85], v[212:215], v[188:191], v[82:85]
	v_mfma_f32_16x16x32_bf16 v[70:73], v[204:207], v[196:199], v[70:73]
	v_mfma_f32_16x16x32_bf16 v[66:69], v[212:215], v[196:199], v[66:69]
	v_mfma_f32_16x16x32_bf16 v[118:121], v[208:211], v[176:179], v[118:121]
	v_mfma_f32_16x16x32_bf16 v[114:117], v[216:219], v[176:179], v[114:117]
	v_mfma_f32_16x16x32_bf16 v[102:105], v[208:211], v[184:187], v[102:105]
	v_mfma_f32_16x16x32_bf16 v[98:101], v[216:219], v[184:187], v[98:101]
	v_mfma_f32_16x16x32_bf16 v[86:89], v[208:211], v[192:195], v[86:89]
	v_mfma_f32_16x16x32_bf16 v[82:85], v[216:219], v[192:195], v[82:85]
	v_mfma_f32_16x16x32_bf16 v[70:73], v[208:211], v[200:203], v[70:73]
	v_mfma_f32_16x16x32_bf16 v[66:69], v[216:219], v[200:203], v[66:69]
	s_barrier
	s_mov_b32 m0, s19
	v_lshl_add_u64 v[220:221], s[12:13], 0, v[130:131]
	ds_read_b128 v[158:161], v175 offset:16384
	ds_read_b128 v[176:179], v175 offset:17408
	ds_read_b128 v[180:183], v175 offset:18432
	ds_read_b128 v[184:187], v175 offset:19456
	ds_read_b128 v[188:191], v175 offset:20480
	ds_read_b128 v[192:195], v175 offset:21504
	ds_read_b128 v[196:199], v175 offset:22528
	ds_read_b128 v[200:203], v175 offset:23552
	global_load_lds_dwordx4 v[220:221], off
	v_lshl_add_u64 v[220:221], s[12:13], 0, v[134:135]
	s_mov_b32 m0, s20
	s_nop 0
	global_load_lds_dwordx4 v[220:221], off
	s_barrier
	s_waitcnt lgkmcnt(0)
	v_mfma_f32_16x16x32_bf16 v[62:65], v[142:145], v[158:161], v[62:65]
	v_mfma_f32_16x16x32_bf16 v[58:61], v[150:153], v[158:161], v[58:61]
	v_mfma_f32_16x16x32_bf16 v[46:49], v[142:145], v[180:183], v[46:49]
	v_mfma_f32_16x16x32_bf16 v[42:45], v[150:153], v[180:183], v[42:45]
	v_mfma_f32_16x16x32_bf16 v[30:33], v[142:145], v[188:191], v[30:33]
	v_mfma_f32_16x16x32_bf16 v[26:29], v[150:153], v[188:191], v[26:29]
	v_mfma_f32_16x16x32_bf16 v[14:17], v[142:145], v[196:199], v[14:17]
	v_mfma_f32_16x16x32_bf16 v[10:13], v[150:153], v[196:199], v[10:13]
	v_mfma_f32_16x16x32_bf16 v[62:65], v[146:149], v[176:179], v[62:65]
	v_mfma_f32_16x16x32_bf16 v[58:61], v[154:157], v[176:179], v[58:61]
	v_mfma_f32_16x16x32_bf16 v[46:49], v[146:149], v[184:187], v[46:49]
	v_mfma_f32_16x16x32_bf16 v[42:45], v[154:157], v[184:187], v[42:45]
	v_mfma_f32_16x16x32_bf16 v[30:33], v[146:149], v[192:195], v[30:33]
	v_mfma_f32_16x16x32_bf16 v[26:29], v[154:157], v[192:195], v[26:29]
	v_mfma_f32_16x16x32_bf16 v[14:17], v[146:149], v[200:203], v[14:17]
	v_mfma_f32_16x16x32_bf16 v[10:13], v[154:157], v[200:203], v[10:13]
	s_barrier
	s_add_u32 s44, s8, 0xb0000
	s_addc_u32 s45, s9, 0
	s_add_i32 s46, s46, s18
	v_lshl_add_u64 v[142:143], s[44:45], 0, v[132:133]
	s_mov_b32 m0, s46
	s_nop 0
	global_load_lds_dwordx4 v[142:143], off
	v_lshl_add_u64 v[142:143], s[44:45], 0, v[136:137]
	s_add_i32 m0, s46, 0x2000
	s_nop 0
	global_load_lds_dwordx4 v[142:143], off
	s_waitcnt vmcnt(6)
	s_barrier
	v_mfma_f32_16x16x32_bf16 v[54:57], v[204:207], v[158:161], v[54:57]
	v_mfma_f32_16x16x32_bf16 v[50:53], v[212:215], v[158:161], v[50:53]
	v_mfma_f32_16x16x32_bf16 v[38:41], v[204:207], v[180:183], v[38:41]
	v_mfma_f32_16x16x32_bf16 v[34:37], v[212:215], v[180:183], v[34:37]
	v_mfma_f32_16x16x32_bf16 v[22:25], v[204:207], v[188:191], v[22:25]
	v_mfma_f32_16x16x32_bf16 v[18:21], v[212:215], v[188:191], v[18:21]
	v_mfma_f32_16x16x32_bf16 v[6:9], v[204:207], v[196:199], v[6:9]
	v_mfma_f32_16x16x32_bf16 v[2:5], v[212:215], v[196:199], v[2:5]
	v_mfma_f32_16x16x32_bf16 v[54:57], v[208:211], v[176:179], v[54:57]
	v_mfma_f32_16x16x32_bf16 v[50:53], v[216:219], v[176:179], v[50:53]
	v_mfma_f32_16x16x32_bf16 v[38:41], v[208:211], v[184:187], v[38:41]
	v_mfma_f32_16x16x32_bf16 v[34:37], v[216:219], v[184:187], v[34:37]
	v_mfma_f32_16x16x32_bf16 v[22:25], v[208:211], v[192:195], v[22:25]
	v_mfma_f32_16x16x32_bf16 v[18:21], v[216:219], v[192:195], v[18:21]
	v_mfma_f32_16x16x32_bf16 v[6:9], v[208:211], v[200:203], v[6:9]
	v_mfma_f32_16x16x32_bf16 v[2:5], v[216:219], v[200:203], v[2:5]
	s_barrier
	s_add_i32 s44, 0, 0x18000
	v_add_u32_e32 v154, s44, v174
	ds_read_b128 v[142:145], v154
	ds_read_b128 v[146:149], v154 offset:1024
	ds_read_b128 v[150:153], v154 offset:2048
	ds_read_b128 v[154:157], v154 offset:3072
	s_add_u32 s12, s12, 0x4000
	s_addc_u32 s13, s13, 0
	s_mov_b32 m0, s21
	v_lshl_add_u64 v[204:205], s[12:13], 0, v[130:131]
	ds_read_b128 v[158:161], v175 offset:32768
	ds_read_b128 v[176:179], v175 offset:33792
	ds_read_b128 v[180:183], v175 offset:34816
	ds_read_b128 v[184:187], v175 offset:35840
	ds_read_b128 v[188:191], v175 offset:36864
	ds_read_b128 v[192:195], v175 offset:37888
	ds_read_b128 v[196:199], v175 offset:38912
	ds_read_b128 v[200:203], v175 offset:39936
	global_load_lds_dwordx4 v[204:205], off
	v_lshl_add_u64 v[204:205], s[12:13], 0, v[134:135]
	s_mov_b32 m0, s22
	s_nop 0
	global_load_lds_dwordx4 v[204:205], off
	s_waitcnt lgkmcnt(8)
	s_barrier
	s_waitcnt lgkmcnt(0)
	v_mfma_f32_16x16x32_bf16 v[126:129], v[142:145], v[158:161], v[126:129]
	v_mfma_f32_16x16x32_bf16 v[122:125], v[150:153], v[158:161], v[122:125]
	v_mfma_f32_16x16x32_bf16 v[110:113], v[142:145], v[180:183], v[110:113]
	v_mfma_f32_16x16x32_bf16 v[106:109], v[150:153], v[180:183], v[106:109]
	v_mfma_f32_16x16x32_bf16 v[94:97], v[142:145], v[188:191], v[94:97]
	v_mfma_f32_16x16x32_bf16 v[90:93], v[150:153], v[188:191], v[90:93]
	v_mfma_f32_16x16x32_bf16 v[78:81], v[142:145], v[196:199], v[78:81]
	v_mfma_f32_16x16x32_bf16 v[74:77], v[150:153], v[196:199], v[74:77]
	v_mfma_f32_16x16x32_bf16 v[126:129], v[146:149], v[176:179], v[126:129]
	v_mfma_f32_16x16x32_bf16 v[122:125], v[154:157], v[176:179], v[122:125]
	v_mfma_f32_16x16x32_bf16 v[110:113], v[146:149], v[184:187], v[110:113]
	v_mfma_f32_16x16x32_bf16 v[106:109], v[154:157], v[184:187], v[106:109]
	v_mfma_f32_16x16x32_bf16 v[94:97], v[146:149], v[192:195], v[94:97]
	v_mfma_f32_16x16x32_bf16 v[90:93], v[154:157], v[192:195], v[90:93]
	v_mfma_f32_16x16x32_bf16 v[78:81], v[146:149], v[200:203], v[78:81]
	v_mfma_f32_16x16x32_bf16 v[74:77], v[154:157], v[200:203], v[74:77]
	s_barrier
	s_add_i32 s12, 0, 0x1c000
	s_add_i32 s13, s44, s18
	v_add_u32_e32 v216, s12, v174
	v_lshl_add_u64 v[168:169], v[168:169], 0, s[84:85]
	s_mov_b32 m0, s13
	ds_read_b128 v[204:207], v216
	ds_read_b128 v[208:211], v216 offset:1024
	ds_read_b128 v[212:215], v216 offset:2048
	ds_read_b128 v[216:219], v216 offset:3072
	global_load_lds_dwordx4 v[168:169], off
	v_lshl_add_u64 v[168:169], v[172:173], 0, s[84:85]
	s_add_i32 m0, s13, 0x2000
	s_nop 0
	global_load_lds_dwordx4 v[168:169], off
	s_barrier
	s_waitcnt lgkmcnt(0)
	v_mfma_f32_16x16x32_bf16 v[118:121], v[204:207], v[158:161], v[118:121]
	v_mfma_f32_16x16x32_bf16 v[114:117], v[212:215], v[158:161], v[114:117]
	v_mfma_f32_16x16x32_bf16 v[102:105], v[204:207], v[180:183], v[102:105]
	v_mfma_f32_16x16x32_bf16 v[98:101], v[212:215], v[180:183], v[98:101]
	v_mfma_f32_16x16x32_bf16 v[86:89], v[204:207], v[188:191], v[86:89]
	v_mfma_f32_16x16x32_bf16 v[82:85], v[212:215], v[188:191], v[82:85]
	v_mfma_f32_16x16x32_bf16 v[70:73], v[204:207], v[196:199], v[70:73]
	v_mfma_f32_16x16x32_bf16 v[66:69], v[212:215], v[196:199], v[66:69]
	v_mfma_f32_16x16x32_bf16 v[118:121], v[208:211], v[176:179], v[118:121]
	v_mfma_f32_16x16x32_bf16 v[114:117], v[216:219], v[176:179], v[114:117]
	v_mfma_f32_16x16x32_bf16 v[102:105], v[208:211], v[184:187], v[102:105]
	v_mfma_f32_16x16x32_bf16 v[98:101], v[216:219], v[184:187], v[98:101]
	v_mfma_f32_16x16x32_bf16 v[86:89], v[208:211], v[192:195], v[86:89]
	v_mfma_f32_16x16x32_bf16 v[82:85], v[216:219], v[192:195], v[82:85]
	v_mfma_f32_16x16x32_bf16 v[70:73], v[208:211], v[200:203], v[70:73]
	v_mfma_f32_16x16x32_bf16 v[66:69], v[216:219], v[200:203], v[66:69]
	s_barrier
	s_mov_b32 m0, s28
	v_lshl_add_u64 v[168:169], s[10:11], 0, v[130:131]
	ds_read_b128 v[158:161], v175 offset:49152
	ds_read_b128 v[176:179], v175 offset:50176
	ds_read_b128 v[180:183], v175 offset:51200
	ds_read_b128 v[184:187], v175 offset:52224
	ds_read_b128 v[188:191], v175 offset:53248
	ds_read_b128 v[192:195], v175 offset:54272
	ds_read_b128 v[196:199], v175 offset:55296
	ds_read_b128 v[200:203], v175 offset:56320
	global_load_lds_dwordx4 v[168:169], off
	v_lshl_add_u64 v[168:169], s[10:11], 0, v[134:135]
	s_mov_b32 m0, s29
	s_nop 0
	global_load_lds_dwordx4 v[168:169], off
	s_barrier
	s_waitcnt lgkmcnt(0)
	v_mfma_f32_16x16x32_bf16 v[62:65], v[142:145], v[158:161], v[62:65]
	v_mfma_f32_16x16x32_bf16 v[58:61], v[150:153], v[158:161], v[58:61]
	v_mfma_f32_16x16x32_bf16 v[46:49], v[142:145], v[180:183], v[46:49]
	v_mfma_f32_16x16x32_bf16 v[42:45], v[150:153], v[180:183], v[42:45]
	v_mfma_f32_16x16x32_bf16 v[30:33], v[142:145], v[188:191], v[30:33]
	v_mfma_f32_16x16x32_bf16 v[26:29], v[150:153], v[188:191], v[26:29]
	v_mfma_f32_16x16x32_bf16 v[14:17], v[142:145], v[196:199], v[14:17]
	v_mfma_f32_16x16x32_bf16 v[10:13], v[150:153], v[196:199], v[10:13]
	v_mfma_f32_16x16x32_bf16 v[62:65], v[146:149], v[176:179], v[62:65]
	v_mfma_f32_16x16x32_bf16 v[58:61], v[154:157], v[176:179], v[58:61]
	v_mfma_f32_16x16x32_bf16 v[46:49], v[146:149], v[184:187], v[46:49]
	v_mfma_f32_16x16x32_bf16 v[42:45], v[154:157], v[184:187], v[42:45]
	v_mfma_f32_16x16x32_bf16 v[30:33], v[146:149], v[192:195], v[30:33]
	v_mfma_f32_16x16x32_bf16 v[26:29], v[154:157], v[192:195], v[26:29]
	v_mfma_f32_16x16x32_bf16 v[14:17], v[146:149], v[200:203], v[14:17]
	v_mfma_f32_16x16x32_bf16 v[10:13], v[154:157], v[200:203], v[10:13]
	s_barrier
	s_add_u32 s8, s8, 0xb0080
	s_addc_u32 s9, s9, 0
	s_add_i32 s10, s12, s18
	v_lshl_add_u64 v[142:143], s[8:9], 0, v[132:133]
	s_mov_b32 m0, s10
	s_nop 0
	global_load_lds_dwordx4 v[142:143], off
	v_lshl_add_u64 v[142:143], s[8:9], 0, v[136:137]
	s_add_i32 m0, s10, 0x2000
	s_nop 0
	global_load_lds_dwordx4 v[142:143], off
	s_waitcnt vmcnt(6)
	s_barrier
	v_mfma_f32_16x16x32_bf16 v[54:57], v[204:207], v[158:161], v[54:57]
	v_mfma_f32_16x16x32_bf16 v[50:53], v[212:215], v[158:161], v[50:53]
	v_mfma_f32_16x16x32_bf16 v[38:41], v[204:207], v[180:183], v[38:41]
	v_mfma_f32_16x16x32_bf16 v[34:37], v[212:215], v[180:183], v[34:37]
	v_mfma_f32_16x16x32_bf16 v[22:25], v[204:207], v[188:191], v[22:25]
	v_mfma_f32_16x16x32_bf16 v[18:21], v[212:215], v[188:191], v[18:21]
	v_mfma_f32_16x16x32_bf16 v[6:9], v[204:207], v[196:199], v[6:9]
	v_mfma_f32_16x16x32_bf16 v[2:5], v[212:215], v[196:199], v[2:5]
	v_mfma_f32_16x16x32_bf16 v[54:57], v[208:211], v[176:179], v[54:57]
	v_mfma_f32_16x16x32_bf16 v[50:53], v[216:219], v[176:179], v[50:53]
	v_mfma_f32_16x16x32_bf16 v[38:41], v[208:211], v[184:187], v[38:41]
	v_mfma_f32_16x16x32_bf16 v[34:37], v[216:219], v[184:187], v[34:37]
	v_mfma_f32_16x16x32_bf16 v[22:25], v[208:211], v[192:195], v[22:25]
	v_mfma_f32_16x16x32_bf16 v[18:21], v[216:219], v[192:195], v[18:21]
	v_mfma_f32_16x16x32_bf16 v[6:9], v[208:211], v[200:203], v[6:9]
	v_mfma_f32_16x16x32_bf16 v[2:5], v[216:219], v[200:203], v[2:5]
	s_barrier
	s_add_u32 s41, s41, 0x100
	s_addc_u32 s42, s42, 0
	s_add_u32 s6, s6, 0x10000
	s_addc_u32 s7, s7, 0
	s_cmp_ge_i32 s43, s25
	s_mov_b32 s8, s43
	s_cbranch_scc0 .LBB0_151
	s_branch .LBB0_138

.LBB0_166:
	s_add_i32 s47, s16, 2
	s_add_u32 s17, s14, 0xfffc0080
	s_addc_u32 s18, s15, -1
	s_add_i32 s48, 0, 0x10000
	v_add_u32_e32 v102, s48, v171
	ds_read_b128 v[82:85], v102
	ds_read_b128 v[86:89], v102 offset:1024
	ds_read_b128 v[98:101], v102 offset:2048
	ds_read_b128 v[102:105], v102 offset:3072
	s_cmp_eq_u32 s39, s16
	s_cselect_b32 s16, s44, s45
	s_cselect_b32 s19, s5, s18
	s_cselect_b32 s18, s7, s17
	s_cselect_b32 s17, s43, s46
	v_lshl_add_u64 v[160:161], s[14:15], 0, v[154:155]
	s_add_i32 m0, s13, 0xc000
	ds_read_b128 v[174:177], v173
	ds_read_b128 v[178:181], v173 offset:1024
	ds_read_b128 v[182:185], v173 offset:2048
	ds_read_b128 v[186:189], v173 offset:3072
	ds_read_b128 v[190:193], v173 offset:4096
	ds_read_b128 v[194:197], v173 offset:5120
	ds_read_b128 v[198:201], v173 offset:6144
	ds_read_b128 v[202:205], v173 offset:7168
	global_load_lds_dwordx4 v[160:161], off
	v_lshl_add_u64 v[160:161], s[14:15], 0, v[156:157]
	s_add_i32 m0, s13, 0xe000
	s_nop 0
	global_load_lds_dwordx4 v[160:161], off
	s_waitcnt lgkmcnt(8)
	s_barrier
	s_waitcnt lgkmcnt(0)
	v_mfma_f32_16x16x32_bf16 v[138:141], v[82:85], v[174:177], v[138:141]
	v_mfma_f32_16x16x32_bf16 v[134:137], v[98:101], v[174:177], v[134:137]
	v_mfma_f32_16x16x32_bf16 v[126:129], v[82:85], v[182:185], v[126:129]
	v_mfma_f32_16x16x32_bf16 v[118:121], v[98:101], v[182:185], v[118:121]
	v_mfma_f32_16x16x32_bf16 v[110:113], v[82:85], v[190:193], v[110:113]
	v_mfma_f32_16x16x32_bf16 v[94:97], v[98:101], v[190:193], v[94:97]
	v_mfma_f32_16x16x32_bf16 v[78:81], v[82:85], v[198:201], v[78:81]
	v_mfma_f32_16x16x32_bf16 v[70:73], v[98:101], v[198:201], v[70:73]
	v_mfma_f32_16x16x32_bf16 v[138:141], v[86:89], v[178:181], v[138:141]
	v_mfma_f32_16x16x32_bf16 v[134:137], v[102:105], v[178:181], v[134:137]
	v_mfma_f32_16x16x32_bf16 v[126:129], v[86:89], v[186:189], v[126:129]
	v_mfma_f32_16x16x32_bf16 v[118:121], v[102:105], v[186:189], v[118:121]
	v_mfma_f32_16x16x32_bf16 v[110:113], v[86:89], v[194:197], v[110:113]
	v_mfma_f32_16x16x32_bf16 v[94:97], v[102:105], v[194:197], v[94:97]
	v_mfma_f32_16x16x32_bf16 v[78:81], v[86:89], v[202:205], v[78:81]
	v_mfma_f32_16x16x32_bf16 v[70:73], v[102:105], v[202:205], v[70:73]
	s_barrier
	s_add_i32 s50, 0, 0x14000
	s_add_i32 s48, s48, s23
	v_add_u32_e32 v158, s50, v171
	v_lshl_add_u64 v[160:161], s[16:17], 0, v[150:151]
	s_mov_b32 m0, s48
	ds_read_b128 v[206:209], v158
	ds_read_b128 v[210:213], v158 offset:1024
	ds_read_b128 v[214:217], v158 offset:2048
	ds_read_b128 v[218:221], v158 offset:3072
	global_load_lds_dwordx4 v[160:161], off
	v_lshl_add_u64 v[168:169], s[16:17], 0, v[146:147]
	s_add_i32 m0, s48, 0x2000
	s_nop 0
	global_load_lds_dwordx4 v[168:169], off
	s_barrier
	s_waitcnt lgkmcnt(0)
	v_mfma_f32_16x16x32_bf16 v[142:145], v[206:209], v[174:177], v[142:145]
	v_mfma_f32_16x16x32_bf16 v[130:133], v[214:217], v[174:177], v[130:133]
	v_mfma_f32_16x16x32_bf16 v[122:125], v[206:209], v[182:185], v[122:125]
	v_mfma_f32_16x16x32_bf16 v[114:117], v[214:217], v[182:185], v[114:117]
	v_mfma_f32_16x16x32_bf16 v[106:109], v[206:209], v[190:193], v[106:109]
	v_mfma_f32_16x16x32_bf16 v[90:93], v[214:217], v[190:193], v[90:93]
	v_mfma_f32_16x16x32_bf16 v[74:77], v[206:209], v[198:201], v[74:77]
	v_mfma_f32_16x16x32_bf16 v[66:69], v[214:217], v[198:201], v[66:69]
	v_mfma_f32_16x16x32_bf16 v[142:145], v[210:213], v[178:181], v[142:145]
	v_mfma_f32_16x16x32_bf16 v[130:133], v[218:221], v[178:181], v[130:133]
	v_mfma_f32_16x16x32_bf16 v[122:125], v[210:213], v[186:189], v[122:125]
	v_mfma_f32_16x16x32_bf16 v[114:117], v[218:221], v[186:189], v[114:117]
	v_mfma_f32_16x16x32_bf16 v[106:109], v[210:213], v[194:197], v[106:109]
	v_mfma_f32_16x16x32_bf16 v[90:93], v[218:221], v[194:197], v[90:93]
	v_mfma_f32_16x16x32_bf16 v[74:77], v[210:213], v[202:205], v[74:77]
	v_mfma_f32_16x16x32_bf16 v[66:69], v[218:221], v[202:205], v[66:69]
	s_barrier
	s_mov_b32 m0, s13
	v_lshl_add_u64 v[236:237], s[18:19], 0, v[152:153]
	ds_read_b128 v[174:177], v173 offset:16384
	ds_read_b128 v[178:181], v173 offset:17408
	ds_read_b128 v[182:185], v173 offset:18432
	ds_read_b128 v[186:189], v173 offset:19456
	ds_read_b128 v[190:193], v173 offset:20480
	ds_read_b128 v[194:197], v173 offset:21504
	ds_read_b128 v[198:201], v173 offset:22528
	ds_read_b128 v[202:205], v173 offset:23552
	global_load_lds_dwordx4 v[236:237], off
	v_lshl_add_u64 v[238:239], s[18:19], 0, v[148:149]
	s_mov_b32 m0, s25
	s_nop 0
	global_load_lds_dwordx4 v[238:239], off
	s_barrier
	s_waitcnt lgkmcnt(0)
	v_mfma_f32_16x16x32_bf16 v[62:65], v[82:85], v[174:177], v[62:65]
	v_mfma_f32_16x16x32_bf16 v[54:57], v[98:101], v[174:177], v[54:57]
	v_mfma_f32_16x16x32_bf16 v[46:49], v[82:85], v[182:185], v[46:49]
	v_mfma_f32_16x16x32_bf16 v[38:41], v[98:101], v[182:185], v[38:41]
	v_mfma_f32_16x16x32_bf16 v[30:33], v[82:85], v[190:193], v[30:33]
	v_mfma_f32_16x16x32_bf16 v[22:25], v[98:101], v[190:193], v[22:25]
	v_mfma_f32_16x16x32_bf16 v[14:17], v[82:85], v[198:201], v[14:17]
	v_mfma_f32_16x16x32_bf16 v[6:9], v[98:101], v[198:201], v[6:9]
	v_mfma_f32_16x16x32_bf16 v[62:65], v[86:89], v[178:181], v[62:65]
	v_mfma_f32_16x16x32_bf16 v[54:57], v[102:105], v[178:181], v[54:57]
	v_mfma_f32_16x16x32_bf16 v[46:49], v[86:89], v[186:189], v[46:49]
	v_mfma_f32_16x16x32_bf16 v[38:41], v[102:105], v[186:189], v[38:41]
	v_mfma_f32_16x16x32_bf16 v[30:33], v[86:89], v[194:197], v[30:33]
	v_mfma_f32_16x16x32_bf16 v[22:25], v[102:105], v[194:197], v[22:25]
	v_mfma_f32_16x16x32_bf16 v[14:17], v[86:89], v[202:205], v[14:17]
	v_mfma_f32_16x16x32_bf16 v[6:9], v[102:105], v[202:205], v[6:9]
	s_barrier
	s_add_u32 s48, s16, 0x40000
	s_addc_u32 s49, s17, 0
	s_add_i32 s50, s50, s23
	v_lshl_add_u64 v[82:83], s[48:49], 0, v[150:151]
	s_mov_b32 m0, s50
	s_nop 0
	global_load_lds_dwordx4 v[82:83], off
	v_lshl_add_u64 v[82:83], s[48:49], 0, v[146:147]
	s_add_i32 m0, s50, 0x2000
	s_nop 0
	global_load_lds_dwordx4 v[82:83], off
	s_waitcnt vmcnt(6)
	s_barrier
	v_mfma_f32_16x16x32_bf16 v[58:61], v[206:209], v[174:177], v[58:61]
	v_mfma_f32_16x16x32_bf16 v[50:53], v[214:217], v[174:177], v[50:53]
	v_mfma_f32_16x16x32_bf16 v[42:45], v[206:209], v[182:185], v[42:45]
	v_mfma_f32_16x16x32_bf16 v[34:37], v[214:217], v[182:185], v[34:37]
	v_mfma_f32_16x16x32_bf16 v[26:29], v[206:209], v[190:193], v[26:29]
	v_mfma_f32_16x16x32_bf16 v[18:21], v[214:217], v[190:193], v[18:21]
	v_mfma_f32_16x16x32_bf16 v[10:13], v[206:209], v[198:201], v[10:13]
	v_mfma_f32_16x16x32_bf16 v[2:5], v[214:217], v[198:201], v[2:5]
	v_mfma_f32_16x16x32_bf16 v[58:61], v[210:213], v[178:181], v[58:61]
	v_mfma_f32_16x16x32_bf16 v[50:53], v[218:221], v[178:181], v[50:53]
	v_mfma_f32_16x16x32_bf16 v[42:45], v[210:213], v[186:189], v[42:45]
	v_mfma_f32_16x16x32_bf16 v[34:37], v[218:221], v[186:189], v[34:37]
	v_mfma_f32_16x16x32_bf16 v[26:29], v[210:213], v[194:197], v[26:29]
	v_mfma_f32_16x16x32_bf16 v[18:21], v[218:221], v[194:197], v[18:21]
	v_mfma_f32_16x16x32_bf16 v[10:13], v[210:213], v[202:205], v[10:13]
	v_mfma_f32_16x16x32_bf16 v[2:5], v[218:221], v[202:205], v[2:5]
	s_barrier
	s_add_i32 s48, 0, 0x18000
	v_add_u32_e32 v102, s48, v171
	ds_read_b128 v[82:85], v102
	ds_read_b128 v[86:89], v102 offset:1024
	ds_read_b128 v[98:101], v102 offset:2048
	ds_read_b128 v[102:105], v102 offset:3072
	s_add_u32 s18, s18, 0x40000
	s_addc_u32 s19, s19, 0
	s_mov_b32 m0, s26
	v_lshl_add_u64 v[206:207], s[18:19], 0, v[152:153]
	ds_read_b128 v[174:177], v173 offset:32768
	ds_read_b128 v[178:181], v173 offset:33792
	ds_read_b128 v[182:185], v173 offset:34816
	ds_read_b128 v[186:189], v173 offset:35840
	ds_read_b128 v[190:193], v173 offset:36864
	ds_read_b128 v[194:197], v173 offset:37888
	ds_read_b128 v[198:201], v173 offset:38912
	ds_read_b128 v[202:205], v173 offset:39936
	global_load_lds_dwordx4 v[206:207], off
	v_lshl_add_u64 v[206:207], s[18:19], 0, v[148:149]
	s_mov_b32 m0, s27
	s_nop 0
	global_load_lds_dwordx4 v[206:207], off
	s_waitcnt lgkmcnt(8)
	s_barrier
	s_waitcnt lgkmcnt(0)
	v_mfma_f32_16x16x32_bf16 v[138:141], v[82:85], v[174:177], v[138:141]
	v_mfma_f32_16x16x32_bf16 v[134:137], v[98:101], v[174:177], v[134:137]
	v_mfma_f32_16x16x32_bf16 v[126:129], v[82:85], v[182:185], v[126:129]
	v_mfma_f32_16x16x32_bf16 v[118:121], v[98:101], v[182:185], v[118:121]
	v_mfma_f32_16x16x32_bf16 v[110:113], v[82:85], v[190:193], v[110:113]
	v_mfma_f32_16x16x32_bf16 v[94:97], v[98:101], v[190:193], v[94:97]
	v_mfma_f32_16x16x32_bf16 v[78:81], v[82:85], v[198:201], v[78:81]
	v_mfma_f32_16x16x32_bf16 v[70:73], v[98:101], v[198:201], v[70:73]
	v_mfma_f32_16x16x32_bf16 v[138:141], v[86:89], v[178:181], v[138:141]
	v_mfma_f32_16x16x32_bf16 v[134:137], v[102:105], v[178:181], v[134:137]
	v_mfma_f32_16x16x32_bf16 v[126:129], v[86:89], v[186:189], v[126:129]
	v_mfma_f32_16x16x32_bf16 v[118:121], v[102:105], v[186:189], v[118:121]
	v_mfma_f32_16x16x32_bf16 v[110:113], v[86:89], v[194:197], v[110:113]
	v_mfma_f32_16x16x32_bf16 v[94:97], v[102:105], v[194:197], v[94:97]
	v_mfma_f32_16x16x32_bf16 v[78:81], v[86:89], v[202:205], v[78:81]
	v_mfma_f32_16x16x32_bf16 v[70:73], v[102:105], v[202:205], v[70:73]
	s_barrier
	s_add_i32 s18, 0, 0x1c000
	s_add_i32 s19, s48, s23
	v_add_u32_e32 v158, s18, v171
	v_lshl_add_u64 v[160:161], v[160:161], 0, s[84:85]
	s_mov_b32 m0, s19
	ds_read_b128 v[206:209], v158
	ds_read_b128 v[210:213], v158 offset:1024
	ds_read_b128 v[214:217], v158 offset:2048
	ds_read_b128 v[218:221], v158 offset:3072
	global_load_lds_dwordx4 v[160:161], off
	v_lshl_add_u64 v[160:161], v[168:169], 0, s[84:85]
	s_add_i32 m0, s19, 0x2000
	s_nop 0
	global_load_lds_dwordx4 v[160:161], off
	s_barrier
	s_waitcnt lgkmcnt(0)
	v_mfma_f32_16x16x32_bf16 v[142:145], v[206:209], v[174:177], v[142:145]
	v_mfma_f32_16x16x32_bf16 v[130:133], v[214:217], v[174:177], v[130:133]
	v_mfma_f32_16x16x32_bf16 v[122:125], v[206:209], v[182:185], v[122:125]
	v_mfma_f32_16x16x32_bf16 v[114:117], v[214:217], v[182:185], v[114:117]
	v_mfma_f32_16x16x32_bf16 v[106:109], v[206:209], v[190:193], v[106:109]
	v_mfma_f32_16x16x32_bf16 v[90:93], v[214:217], v[190:193], v[90:93]
	v_mfma_f32_16x16x32_bf16 v[74:77], v[206:209], v[198:201], v[74:77]
	v_mfma_f32_16x16x32_bf16 v[66:69], v[214:217], v[198:201], v[66:69]
	v_mfma_f32_16x16x32_bf16 v[142:145], v[210:213], v[178:181], v[142:145]
	v_mfma_f32_16x16x32_bf16 v[130:133], v[218:221], v[178:181], v[130:133]
	v_mfma_f32_16x16x32_bf16 v[122:125], v[210:213], v[186:189], v[122:125]
	v_mfma_f32_16x16x32_bf16 v[114:117], v[218:221], v[186:189], v[114:117]
	v_mfma_f32_16x16x32_bf16 v[106:109], v[210:213], v[194:197], v[106:109]
	v_mfma_f32_16x16x32_bf16 v[90:93], v[218:221], v[194:197], v[90:93]
	v_mfma_f32_16x16x32_bf16 v[74:77], v[210:213], v[202:205], v[74:77]
	v_mfma_f32_16x16x32_bf16 v[66:69], v[218:221], v[202:205], v[66:69]
	s_barrier
	s_mov_b32 m0, s35
	v_lshl_add_u64 v[160:161], v[236:237], 0, s[84:85]
	ds_read_b128 v[174:177], v173 offset:49152
	ds_read_b128 v[178:181], v173 offset:50176
	ds_read_b128 v[182:185], v173 offset:51200
	ds_read_b128 v[186:189], v173 offset:52224
	ds_read_b128 v[190:193], v173 offset:53248
	ds_read_b128 v[194:197], v173 offset:54272
	ds_read_b128 v[198:201], v173 offset:55296
	ds_read_b128 v[202:205], v173 offset:56320
	global_load_lds_dwordx4 v[160:161], off
	v_lshl_add_u64 v[160:161], v[238:239], 0, s[84:85]
	s_mov_b32 m0, s38
	s_nop 0
	global_load_lds_dwordx4 v[160:161], off
	s_barrier
	s_waitcnt lgkmcnt(0)
	v_mfma_f32_16x16x32_bf16 v[62:65], v[82:85], v[174:177], v[62:65]
	v_mfma_f32_16x16x32_bf16 v[54:57], v[98:101], v[174:177], v[54:57]
	v_mfma_f32_16x16x32_bf16 v[46:49], v[82:85], v[182:185], v[46:49]
	v_mfma_f32_16x16x32_bf16 v[38:41], v[98:101], v[182:185], v[38:41]
	v_mfma_f32_16x16x32_bf16 v[30:33], v[82:85], v[190:193], v[30:33]
	v_mfma_f32_16x16x32_bf16 v[22:25], v[98:101], v[190:193], v[22:25]
	v_mfma_f32_16x16x32_bf16 v[14:17], v[82:85], v[198:201], v[14:17]
	v_mfma_f32_16x16x32_bf16 v[6:9], v[98:101], v[198:201], v[6:9]
	v_mfma_f32_16x16x32_bf16 v[62:65], v[86:89], v[178:181], v[62:65]
	v_mfma_f32_16x16x32_bf16 v[54:57], v[102:105], v[178:181], v[54:57]
	v_mfma_f32_16x16x32_bf16 v[46:49], v[86:89], v[186:189], v[46:49]
	v_mfma_f32_16x16x32_bf16 v[38:41], v[102:105], v[186:189], v[38:41]
	v_mfma_f32_16x16x32_bf16 v[30:33], v[86:89], v[194:197], v[30:33]
	v_mfma_f32_16x16x32_bf16 v[22:25], v[102:105], v[194:197], v[22:25]
	v_mfma_f32_16x16x32_bf16 v[14:17], v[86:89], v[202:205], v[14:17]
	v_mfma_f32_16x16x32_bf16 v[6:9], v[102:105], v[202:205], v[6:9]
	s_barrier
	s_add_u32 s16, s16, 0x40080
	s_addc_u32 s17, s17, 0
	s_add_i32 s18, s18, s23
	v_lshl_add_u64 v[82:83], s[16:17], 0, v[150:151]
	s_mov_b32 m0, s18
	s_nop 0
	global_load_lds_dwordx4 v[82:83], off
	v_lshl_add_u64 v[82:83], s[16:17], 0, v[146:147]
	s_add_i32 m0, s18, 0x2000
	s_nop 0
	global_load_lds_dwordx4 v[82:83], off
	s_waitcnt vmcnt(6)
	s_barrier
	v_mfma_f32_16x16x32_bf16 v[58:61], v[206:209], v[174:177], v[58:61]
	v_mfma_f32_16x16x32_bf16 v[50:53], v[214:217], v[174:177], v[50:53]
	v_mfma_f32_16x16x32_bf16 v[42:45], v[206:209], v[182:185], v[42:45]
	v_mfma_f32_16x16x32_bf16 v[34:37], v[214:217], v[182:185], v[34:37]
	v_mfma_f32_16x16x32_bf16 v[26:29], v[206:209], v[190:193], v[26:29]
	v_mfma_f32_16x16x32_bf16 v[18:21], v[214:217], v[190:193], v[18:21]
	v_mfma_f32_16x16x32_bf16 v[10:13], v[206:209], v[198:201], v[10:13]
	v_mfma_f32_16x16x32_bf16 v[2:5], v[214:217], v[198:201], v[2:5]
	v_mfma_f32_16x16x32_bf16 v[58:61], v[210:213], v[178:181], v[58:61]
	v_mfma_f32_16x16x32_bf16 v[50:53], v[218:221], v[178:181], v[50:53]
	v_mfma_f32_16x16x32_bf16 v[42:45], v[210:213], v[186:189], v[42:45]
	v_mfma_f32_16x16x32_bf16 v[34:37], v[218:221], v[186:189], v[34:37]
	v_mfma_f32_16x16x32_bf16 v[26:29], v[210:213], v[194:197], v[26:29]
	v_mfma_f32_16x16x32_bf16 v[18:21], v[218:221], v[194:197], v[18:21]
	v_mfma_f32_16x16x32_bf16 v[10:13], v[210:213], v[202:205], v[10:13]
	v_mfma_f32_16x16x32_bf16 v[2:5], v[218:221], v[202:205], v[2:5]
	s_barrier
	s_add_u32 s14, s14, 0x100
	s_addc_u32 s15, s15, 0
	s_add_u32 s45, s45, 0x100
	s_addc_u32 s46, s46, 0
	s_cmp_ge_i32 s47, s30
	s_mov_b32 s16, s47
	s_cbranch_scc0 .LBB0_166
	s_branch .LBB0_161

.LBB0_191:
	s_add_i32 s51, s18, 2
	s_add_u32 s19, s0, 0xfffc0080
	s_addc_u32 s20, s1, -1
	s_add_i32 s52, 0, 0x10000
	v_add_u32_e32 v122, s52, v206
	ds_read_b128 v[90:93], v122
	ds_read_b128 v[102:105], v122 offset:1024
	ds_read_b128 v[110:113], v122 offset:2048
	ds_read_b128 v[122:125], v122 offset:3072
	s_cmp_eq_u32 s43, s18
	s_cselect_b32 s18, s48, s49
	s_cselect_b32 s21, s7, s20
	s_cselect_b32 s20, s9, s19
	s_cselect_b32 s19, s47, s50
	v_lshl_add_u64 v[168:169], s[0:1], 0, v[172:173]
	s_add_i32 m0, s15, 0xc000
	ds_read_b128 v[146:149], v207
	ds_read_b128 v[150:153], v207 offset:1024
	ds_read_b128 v[176:179], v207 offset:2048
	ds_read_b128 v[180:183], v207 offset:3072
	ds_read_b128 v[184:187], v207 offset:4096
	ds_read_b128 v[188:191], v207 offset:5120
	ds_read_b128 v[192:195], v207 offset:6144
	ds_read_b128 v[196:199], v207 offset:7168
	global_load_lds_dwordx4 v[168:169], off
	v_lshl_add_u64 v[168:169], s[0:1], 0, v[174:175]
	s_add_i32 m0, s15, 0xe000
	s_nop 0
	global_load_lds_dwordx4 v[168:169], off
	s_waitcnt lgkmcnt(8)
	s_barrier
	s_waitcnt lgkmcnt(0)
	v_mfma_f32_16x16x32_bf16 v[142:145], v[90:93], v[146:149], v[142:145]
	v_mfma_f32_16x16x32_bf16 v[138:141], v[110:113], v[146:149], v[138:141]
	v_mfma_f32_16x16x32_bf16 v[126:129], v[90:93], v[176:179], v[126:129]
	v_mfma_f32_16x16x32_bf16 v[118:121], v[110:113], v[176:179], v[118:121]
	v_mfma_f32_16x16x32_bf16 v[98:101], v[90:93], v[184:187], v[98:101]
	v_mfma_f32_16x16x32_bf16 v[94:97], v[110:113], v[184:187], v[94:97]
	v_mfma_f32_16x16x32_bf16 v[78:81], v[90:93], v[192:195], v[78:81]
	v_mfma_f32_16x16x32_bf16 v[74:77], v[110:113], v[192:195], v[74:77]
	v_mfma_f32_16x16x32_bf16 v[142:145], v[102:105], v[150:153], v[142:145]
	v_mfma_f32_16x16x32_bf16 v[138:141], v[122:125], v[150:153], v[138:141]
	v_mfma_f32_16x16x32_bf16 v[126:129], v[102:105], v[180:183], v[126:129]
	v_mfma_f32_16x16x32_bf16 v[118:121], v[122:125], v[180:183], v[118:121]
	v_mfma_f32_16x16x32_bf16 v[98:101], v[102:105], v[188:191], v[98:101]
	v_mfma_f32_16x16x32_bf16 v[94:97], v[122:125], v[188:191], v[94:97]
	v_mfma_f32_16x16x32_bf16 v[78:81], v[102:105], v[196:199], v[78:81]
	v_mfma_f32_16x16x32_bf16 v[74:77], v[122:125], v[196:199], v[74:77]
	s_barrier
	s_add_i32 s54, 0, 0x14000
	v_add_u32_e32 v168, s54, v206
	s_add_i32 s52, s52, s27
	ds_read_b128 v[200:203], v168
	ds_read_b128 v[208:211], v168 offset:1024
	ds_read_b128 v[212:215], v168 offset:2048
	ds_read_b128 v[216:219], v168 offset:3072
	v_lshl_add_u64 v[168:169], s[18:19], 0, v[156:157]
	s_mov_b32 m0, s52
	v_lshl_add_u64 v[204:205], s[18:19], 0, v[160:161]
	global_load_lds_dwordx4 v[168:169], off
	s_add_i32 m0, s52, 0x2000
	s_nop 0
	global_load_lds_dwordx4 v[204:205], off
	s_barrier
	s_waitcnt lgkmcnt(0)
	v_mfma_f32_16x16x32_bf16 v[134:137], v[200:203], v[146:149], v[134:137]
	v_mfma_f32_16x16x32_bf16 v[130:133], v[212:215], v[146:149], v[130:133]
	v_mfma_f32_16x16x32_bf16 v[114:117], v[200:203], v[176:179], v[114:117]
	v_mfma_f32_16x16x32_bf16 v[106:109], v[212:215], v[176:179], v[106:109]
	v_mfma_f32_16x16x32_bf16 v[86:89], v[200:203], v[184:187], v[86:89]
	v_mfma_f32_16x16x32_bf16 v[82:85], v[212:215], v[184:187], v[82:85]
	v_mfma_f32_16x16x32_bf16 v[70:73], v[200:203], v[192:195], v[70:73]
	v_mfma_f32_16x16x32_bf16 v[66:69], v[212:215], v[192:195], v[66:69]
	v_mfma_f32_16x16x32_bf16 v[134:137], v[208:211], v[150:153], v[134:137]
	v_mfma_f32_16x16x32_bf16 v[130:133], v[216:219], v[150:153], v[130:133]
	v_mfma_f32_16x16x32_bf16 v[114:117], v[208:211], v[180:183], v[114:117]
	v_mfma_f32_16x16x32_bf16 v[106:109], v[216:219], v[180:183], v[106:109]
	v_mfma_f32_16x16x32_bf16 v[86:89], v[208:211], v[188:191], v[86:89]
	v_mfma_f32_16x16x32_bf16 v[82:85], v[216:219], v[188:191], v[82:85]
	v_mfma_f32_16x16x32_bf16 v[70:73], v[208:211], v[196:199], v[70:73]
	v_mfma_f32_16x16x32_bf16 v[66:69], v[216:219], v[196:199], v[66:69]
	s_barrier
	s_mov_b32 m0, s15
	v_lshl_add_u64 v[220:221], s[20:21], 0, v[154:155]
	ds_read_b128 v[146:149], v207 offset:16384
	ds_read_b128 v[150:153], v207 offset:17408
	ds_read_b128 v[176:179], v207 offset:18432
	ds_read_b128 v[180:183], v207 offset:19456
	ds_read_b128 v[184:187], v207 offset:20480
	ds_read_b128 v[188:191], v207 offset:21504
	ds_read_b128 v[192:195], v207 offset:22528
	ds_read_b128 v[196:199], v207 offset:23552
	global_load_lds_dwordx4 v[220:221], off
	v_lshl_add_u64 v[236:237], s[20:21], 0, v[158:159]
	s_mov_b32 m0, s17
	s_nop 0
	global_load_lds_dwordx4 v[236:237], off
	s_barrier
	s_waitcnt lgkmcnt(0)
	v_mfma_f32_16x16x32_bf16 v[62:65], v[90:93], v[146:149], v[62:65]
	v_mfma_f32_16x16x32_bf16 v[58:61], v[110:113], v[146:149], v[58:61]
	v_mfma_f32_16x16x32_bf16 v[46:49], v[90:93], v[176:179], v[46:49]
	v_mfma_f32_16x16x32_bf16 v[42:45], v[110:113], v[176:179], v[42:45]
	v_mfma_f32_16x16x32_bf16 v[30:33], v[90:93], v[184:187], v[30:33]
	v_mfma_f32_16x16x32_bf16 v[26:29], v[110:113], v[184:187], v[26:29]
	v_mfma_f32_16x16x32_bf16 v[14:17], v[90:93], v[192:195], v[14:17]
	v_mfma_f32_16x16x32_bf16 v[10:13], v[110:113], v[192:195], v[10:13]
	v_mfma_f32_16x16x32_bf16 v[62:65], v[102:105], v[150:153], v[62:65]
	v_mfma_f32_16x16x32_bf16 v[58:61], v[122:125], v[150:153], v[58:61]
	v_mfma_f32_16x16x32_bf16 v[46:49], v[102:105], v[180:183], v[46:49]
	v_mfma_f32_16x16x32_bf16 v[42:45], v[122:125], v[180:183], v[42:45]
	v_mfma_f32_16x16x32_bf16 v[30:33], v[102:105], v[188:191], v[30:33]
	v_mfma_f32_16x16x32_bf16 v[26:29], v[122:125], v[188:191], v[26:29]
	v_mfma_f32_16x16x32_bf16 v[14:17], v[102:105], v[196:199], v[14:17]
	v_mfma_f32_16x16x32_bf16 v[10:13], v[122:125], v[196:199], v[10:13]
	s_barrier
	s_add_u32 s52, s18, 0x40000
	s_addc_u32 s53, s19, 0
	s_add_i32 s54, s54, s27
	v_lshl_add_u64 v[90:91], s[52:53], 0, v[156:157]
	s_mov_b32 m0, s54
	s_nop 0
	global_load_lds_dwordx4 v[90:91], off
	v_lshl_add_u64 v[90:91], s[52:53], 0, v[160:161]
	s_add_i32 m0, s54, 0x2000
	s_nop 0
	global_load_lds_dwordx4 v[90:91], off
	s_waitcnt vmcnt(6)
	s_barrier
	v_mfma_f32_16x16x32_bf16 v[54:57], v[200:203], v[146:149], v[54:57]
	v_mfma_f32_16x16x32_bf16 v[50:53], v[212:215], v[146:149], v[50:53]
	v_mfma_f32_16x16x32_bf16 v[38:41], v[200:203], v[176:179], v[38:41]
	v_mfma_f32_16x16x32_bf16 v[34:37], v[212:215], v[176:179], v[34:37]
	v_mfma_f32_16x16x32_bf16 v[22:25], v[200:203], v[184:187], v[22:25]
	v_mfma_f32_16x16x32_bf16 v[18:21], v[212:215], v[184:187], v[18:21]
	v_mfma_f32_16x16x32_bf16 v[6:9], v[200:203], v[192:195], v[6:9]
	v_mfma_f32_16x16x32_bf16 v[2:5], v[212:215], v[192:195], v[2:5]
	v_mfma_f32_16x16x32_bf16 v[54:57], v[208:211], v[150:153], v[54:57]
	v_mfma_f32_16x16x32_bf16 v[50:53], v[216:219], v[150:153], v[50:53]
	v_mfma_f32_16x16x32_bf16 v[38:41], v[208:211], v[180:183], v[38:41]
	v_mfma_f32_16x16x32_bf16 v[34:37], v[216:219], v[180:183], v[34:37]
	v_mfma_f32_16x16x32_bf16 v[22:25], v[208:211], v[188:191], v[22:25]
	v_mfma_f32_16x16x32_bf16 v[18:21], v[216:219], v[188:191], v[18:21]
	v_mfma_f32_16x16x32_bf16 v[6:9], v[208:211], v[196:199], v[6:9]
	v_mfma_f32_16x16x32_bf16 v[2:5], v[216:219], v[196:199], v[2:5]
	s_barrier
	s_add_i32 s52, 0, 0x18000
	v_add_u32_e32 v122, s52, v206
	ds_read_b128 v[90:93], v122
	ds_read_b128 v[102:105], v122 offset:1024
	ds_read_b128 v[110:113], v122 offset:2048
	ds_read_b128 v[122:125], v122 offset:3072
	s_add_u32 s20, s20, 0x40000
	s_addc_u32 s21, s21, 0
	s_mov_b32 m0, s28
	v_lshl_add_u64 v[200:201], s[20:21], 0, v[154:155]
	ds_read_b128 v[146:149], v207 offset:32768
	ds_read_b128 v[150:153], v207 offset:33792
	ds_read_b128 v[176:179], v207 offset:34816
	ds_read_b128 v[180:183], v207 offset:35840
	ds_read_b128 v[184:187], v207 offset:36864
	ds_read_b128 v[188:191], v207 offset:37888
	ds_read_b128 v[192:195], v207 offset:38912
	ds_read_b128 v[196:199], v207 offset:39936
	global_load_lds_dwordx4 v[200:201], off
	v_lshl_add_u64 v[200:201], s[20:21], 0, v[158:159]
	s_mov_b32 m0, s29
	s_nop 0
	global_load_lds_dwordx4 v[200:201], off
	s_waitcnt lgkmcnt(8)
	s_barrier
	s_waitcnt lgkmcnt(0)
	v_mfma_f32_16x16x32_bf16 v[142:145], v[90:93], v[146:149], v[142:145]
	v_mfma_f32_16x16x32_bf16 v[138:141], v[110:113], v[146:149], v[138:141]
	v_mfma_f32_16x16x32_bf16 v[126:129], v[90:93], v[176:179], v[126:129]
	v_mfma_f32_16x16x32_bf16 v[118:121], v[110:113], v[176:179], v[118:121]
	v_mfma_f32_16x16x32_bf16 v[98:101], v[90:93], v[184:187], v[98:101]
	v_mfma_f32_16x16x32_bf16 v[94:97], v[110:113], v[184:187], v[94:97]
	v_mfma_f32_16x16x32_bf16 v[78:81], v[90:93], v[192:195], v[78:81]
	v_mfma_f32_16x16x32_bf16 v[74:77], v[110:113], v[192:195], v[74:77]
	v_mfma_f32_16x16x32_bf16 v[142:145], v[102:105], v[150:153], v[142:145]
	v_mfma_f32_16x16x32_bf16 v[138:141], v[122:125], v[150:153], v[138:141]
	v_mfma_f32_16x16x32_bf16 v[126:129], v[102:105], v[180:183], v[126:129]
	v_mfma_f32_16x16x32_bf16 v[118:121], v[122:125], v[180:183], v[118:121]
	v_mfma_f32_16x16x32_bf16 v[98:101], v[102:105], v[188:191], v[98:101]
	v_mfma_f32_16x16x32_bf16 v[94:97], v[122:125], v[188:191], v[94:97]
	v_mfma_f32_16x16x32_bf16 v[78:81], v[102:105], v[196:199], v[78:81]
	v_mfma_f32_16x16x32_bf16 v[74:77], v[122:125], v[196:199], v[74:77]
	s_barrier
	s_add_i32 s20, 0, 0x1c000
	s_add_i32 s21, s52, s27
	v_add_u32_e32 v216, s20, v206
	v_lshl_add_u64 v[168:169], v[168:169], 0, s[84:85]
	s_mov_b32 m0, s21
	ds_read_b128 v[200:203], v216
	ds_read_b128 v[208:211], v216 offset:1024
	ds_read_b128 v[212:215], v216 offset:2048
	ds_read_b128 v[216:219], v216 offset:3072
	global_load_lds_dwordx4 v[168:169], off
	v_lshl_add_u64 v[168:169], v[204:205], 0, s[84:85]
	s_add_i32 m0, s21, 0x2000
	s_nop 0
	global_load_lds_dwordx4 v[168:169], off
	s_barrier
	s_waitcnt lgkmcnt(0)
	v_mfma_f32_16x16x32_bf16 v[134:137], v[200:203], v[146:149], v[134:137]
	v_mfma_f32_16x16x32_bf16 v[130:133], v[212:215], v[146:149], v[130:133]
	v_mfma_f32_16x16x32_bf16 v[114:117], v[200:203], v[176:179], v[114:117]
	v_mfma_f32_16x16x32_bf16 v[106:109], v[212:215], v[176:179], v[106:109]
	v_mfma_f32_16x16x32_bf16 v[86:89], v[200:203], v[184:187], v[86:89]
	v_mfma_f32_16x16x32_bf16 v[82:85], v[212:215], v[184:187], v[82:85]
	v_mfma_f32_16x16x32_bf16 v[70:73], v[200:203], v[192:195], v[70:73]
	v_mfma_f32_16x16x32_bf16 v[66:69], v[212:215], v[192:195], v[66:69]
	v_mfma_f32_16x16x32_bf16 v[134:137], v[208:211], v[150:153], v[134:137]
	v_mfma_f32_16x16x32_bf16 v[130:133], v[216:219], v[150:153], v[130:133]
	v_mfma_f32_16x16x32_bf16 v[114:117], v[208:211], v[180:183], v[114:117]
	v_mfma_f32_16x16x32_bf16 v[106:109], v[216:219], v[180:183], v[106:109]
	v_mfma_f32_16x16x32_bf16 v[86:89], v[208:211], v[188:191], v[86:89]
	v_mfma_f32_16x16x32_bf16 v[82:85], v[216:219], v[188:191], v[82:85]
	v_mfma_f32_16x16x32_bf16 v[70:73], v[208:211], v[196:199], v[70:73]
	v_mfma_f32_16x16x32_bf16 v[66:69], v[216:219], v[196:199], v[66:69]
	s_barrier
	s_mov_b32 m0, s41
	v_lshl_add_u64 v[168:169], v[220:221], 0, s[84:85]
	ds_read_b128 v[146:149], v207 offset:49152
	ds_read_b128 v[150:153], v207 offset:50176
	ds_read_b128 v[176:179], v207 offset:51200
	ds_read_b128 v[180:183], v207 offset:52224
	ds_read_b128 v[184:187], v207 offset:53248
	ds_read_b128 v[188:191], v207 offset:54272
	ds_read_b128 v[192:195], v207 offset:55296
	ds_read_b128 v[196:199], v207 offset:56320
	global_load_lds_dwordx4 v[168:169], off
	v_lshl_add_u64 v[168:169], v[236:237], 0, s[84:85]
	s_mov_b32 m0, s42
	s_nop 0
	global_load_lds_dwordx4 v[168:169], off
	s_barrier
	s_waitcnt lgkmcnt(0)
	v_mfma_f32_16x16x32_bf16 v[62:65], v[90:93], v[146:149], v[62:65]
	v_mfma_f32_16x16x32_bf16 v[58:61], v[110:113], v[146:149], v[58:61]
	v_mfma_f32_16x16x32_bf16 v[46:49], v[90:93], v[176:179], v[46:49]
	v_mfma_f32_16x16x32_bf16 v[42:45], v[110:113], v[176:179], v[42:45]
	v_mfma_f32_16x16x32_bf16 v[30:33], v[90:93], v[184:187], v[30:33]
	v_mfma_f32_16x16x32_bf16 v[26:29], v[110:113], v[184:187], v[26:29]
	v_mfma_f32_16x16x32_bf16 v[14:17], v[90:93], v[192:195], v[14:17]
	v_mfma_f32_16x16x32_bf16 v[10:13], v[110:113], v[192:195], v[10:13]
	v_mfma_f32_16x16x32_bf16 v[62:65], v[102:105], v[150:153], v[62:65]
	v_mfma_f32_16x16x32_bf16 v[58:61], v[122:125], v[150:153], v[58:61]
	v_mfma_f32_16x16x32_bf16 v[46:49], v[102:105], v[180:183], v[46:49]
	v_mfma_f32_16x16x32_bf16 v[42:45], v[122:125], v[180:183], v[42:45]
	v_mfma_f32_16x16x32_bf16 v[30:33], v[102:105], v[188:191], v[30:33]
	v_mfma_f32_16x16x32_bf16 v[26:29], v[122:125], v[188:191], v[26:29]
	v_mfma_f32_16x16x32_bf16 v[14:17], v[102:105], v[196:199], v[14:17]
	v_mfma_f32_16x16x32_bf16 v[10:13], v[122:125], v[196:199], v[10:13]
	s_barrier
	s_add_u32 s18, s18, 0x40080
	s_addc_u32 s19, s19, 0
	s_add_i32 s20, s20, s27
	v_lshl_add_u64 v[90:91], s[18:19], 0, v[156:157]
	s_mov_b32 m0, s20
	s_nop 0
	global_load_lds_dwordx4 v[90:91], off
	v_lshl_add_u64 v[90:91], s[18:19], 0, v[160:161]
	s_add_i32 m0, s20, 0x2000
	s_nop 0
	global_load_lds_dwordx4 v[90:91], off
	s_waitcnt vmcnt(6)
	s_barrier
	v_mfma_f32_16x16x32_bf16 v[54:57], v[200:203], v[146:149], v[54:57]
	v_mfma_f32_16x16x32_bf16 v[50:53], v[212:215], v[146:149], v[50:53]
	v_mfma_f32_16x16x32_bf16 v[38:41], v[200:203], v[176:179], v[38:41]
	v_mfma_f32_16x16x32_bf16 v[34:37], v[212:215], v[176:179], v[34:37]
	v_mfma_f32_16x16x32_bf16 v[22:25], v[200:203], v[184:187], v[22:25]
	v_mfma_f32_16x16x32_bf16 v[18:21], v[212:215], v[184:187], v[18:21]
	v_mfma_f32_16x16x32_bf16 v[6:9], v[200:203], v[192:195], v[6:9]
	v_mfma_f32_16x16x32_bf16 v[2:5], v[212:215], v[192:195], v[2:5]
	v_mfma_f32_16x16x32_bf16 v[54:57], v[208:211], v[150:153], v[54:57]
	v_mfma_f32_16x16x32_bf16 v[50:53], v[216:219], v[150:153], v[50:53]
	v_mfma_f32_16x16x32_bf16 v[38:41], v[208:211], v[180:183], v[38:41]
	v_mfma_f32_16x16x32_bf16 v[34:37], v[216:219], v[180:183], v[34:37]
	v_mfma_f32_16x16x32_bf16 v[22:25], v[208:211], v[188:191], v[22:25]
	v_mfma_f32_16x16x32_bf16 v[18:21], v[216:219], v[188:191], v[18:21]
	v_mfma_f32_16x16x32_bf16 v[6:9], v[208:211], v[196:199], v[6:9]
	v_mfma_f32_16x16x32_bf16 v[2:5], v[216:219], v[196:199], v[2:5]
	s_barrier
	s_add_u32 s49, s49, 0x100
	s_addc_u32 s50, s50, 0
	s_add_u32 s0, s0, 0x100
	s_addc_u32 s1, s1, 0
	s_cmp_ge_i32 s51, s38
	s_mov_b32 s18, s51
	s_cbranch_scc0 .LBB0_191

.LBB0_427:
	s_add_i32 s23, s6, 2
	s_add_u32 s7, s4, 0xe2bf0080
	s_addc_u32 s8, s5, -1
	s_cmp_lg_u32 s22, s6
	s_cselect_b32 s6, s7, 0
	s_cselect_b32 s24, s8, 0
	s_add_u32 s8, s2, s6
	s_addc_u32 s9, s3, s24
	s_add_i32 s25, 0, 0x10000
	v_add_u32_e32 v144, s25, v142
	ds_read_b128 v[148:151], v144
	ds_read_b128 v[152:155], v144 offset:1024
	ds_read_b128 v[172:175], v144 offset:2048
	ds_read_b128 v[176:179], v144 offset:3072
	s_add_u32 s6, s0, s6
	s_addc_u32 s7, s1, s24
	v_lshl_add_u64 v[144:145], v[138:139], 0, s[4:5]
	s_add_i32 m0, s15, 0xc000
	ds_read_b128 v[180:183], v143
	ds_read_b128 v[184:187], v143 offset:1024
	ds_read_b128 v[188:191], v143 offset:2048
	ds_read_b128 v[192:195], v143 offset:3072
	ds_read_b128 v[196:199], v143 offset:4096
	ds_read_b128 v[200:203], v143 offset:5120
	ds_read_b128 v[204:207], v143 offset:6144
	ds_read_b128 v[208:211], v143 offset:7168
	global_load_lds_dwordx4 v[144:145], off
	v_lshl_add_u64 v[144:145], v[140:141], 0, s[4:5]
	s_add_i32 m0, s15, 0xe000
	s_nop 0
	global_load_lds_dwordx4 v[144:145], off
	s_waitcnt lgkmcnt(8)
	s_barrier
	s_waitcnt lgkmcnt(0)
	v_mfma_f32_16x16x32_bf16 v[126:129], v[148:151], v[180:183], v[126:129]
	v_mfma_f32_16x16x32_bf16 v[122:125], v[172:175], v[180:183], v[122:125]
	v_mfma_f32_16x16x32_bf16 v[110:113], v[148:151], v[188:191], v[110:113]
	v_mfma_f32_16x16x32_bf16 v[106:109], v[172:175], v[188:191], v[106:109]
	v_mfma_f32_16x16x32_bf16 v[94:97], v[148:151], v[196:199], v[94:97]
	v_mfma_f32_16x16x32_bf16 v[90:93], v[172:175], v[196:199], v[90:93]
	v_mfma_f32_16x16x32_bf16 v[78:81], v[148:151], v[204:207], v[78:81]
	v_mfma_f32_16x16x32_bf16 v[74:77], v[172:175], v[204:207], v[74:77]
	v_mfma_f32_16x16x32_bf16 v[126:129], v[152:155], v[184:187], v[126:129]
	v_mfma_f32_16x16x32_bf16 v[122:125], v[176:179], v[184:187], v[122:125]
	v_mfma_f32_16x16x32_bf16 v[110:113], v[152:155], v[192:195], v[110:113]
	v_mfma_f32_16x16x32_bf16 v[106:109], v[176:179], v[192:195], v[106:109]
	v_mfma_f32_16x16x32_bf16 v[94:97], v[152:155], v[200:203], v[94:97]
	v_mfma_f32_16x16x32_bf16 v[90:93], v[176:179], v[200:203], v[90:93]
	v_mfma_f32_16x16x32_bf16 v[78:81], v[152:155], v[208:211], v[78:81]
	v_mfma_f32_16x16x32_bf16 v[74:77], v[176:179], v[208:211], v[74:77]
	s_barrier
	s_add_i32 s26, 0, 0x14000
	v_add_u32_e32 v144, s26, v142
	s_add_i32 s24, s25, s14
	ds_read_b128 v[212:215], v144
	ds_read_b128 v[216:219], v144 offset:1024
	ds_read_b128 v[236:239], v144 offset:2048
	ds_read_b128 v[240:243], v144 offset:3072
	v_lshl_add_u64 v[144:145], s[6:7], 0, v[132:133]
	s_mov_b32 m0, s24
	v_lshl_add_u64 v[156:157], s[6:7], 0, v[136:137]
	global_load_lds_dwordx4 v[144:145], off
	s_add_i32 m0, s24, 0x2000
	s_nop 0
	global_load_lds_dwordx4 v[156:157], off
	s_barrier
	s_waitcnt lgkmcnt(0)
	v_mfma_f32_16x16x32_bf16 v[118:121], v[212:215], v[180:183], v[118:121]
	v_mfma_f32_16x16x32_bf16 v[114:117], v[236:239], v[180:183], v[114:117]
	v_mfma_f32_16x16x32_bf16 v[102:105], v[212:215], v[188:191], v[102:105]
	v_mfma_f32_16x16x32_bf16 v[98:101], v[236:239], v[188:191], v[98:101]
	v_mfma_f32_16x16x32_bf16 v[86:89], v[212:215], v[196:199], v[86:89]
	v_mfma_f32_16x16x32_bf16 v[82:85], v[236:239], v[196:199], v[82:85]
	v_mfma_f32_16x16x32_bf16 v[70:73], v[212:215], v[204:207], v[70:73]
	v_mfma_f32_16x16x32_bf16 v[66:69], v[236:239], v[204:207], v[66:69]
	v_mfma_f32_16x16x32_bf16 v[118:121], v[216:219], v[184:187], v[118:121]
	v_mfma_f32_16x16x32_bf16 v[114:117], v[240:243], v[184:187], v[114:117]
	v_mfma_f32_16x16x32_bf16 v[102:105], v[216:219], v[192:195], v[102:105]
	v_mfma_f32_16x16x32_bf16 v[98:101], v[240:243], v[192:195], v[98:101]
	v_mfma_f32_16x16x32_bf16 v[86:89], v[216:219], v[200:203], v[86:89]
	v_mfma_f32_16x16x32_bf16 v[82:85], v[240:243], v[200:203], v[82:85]
	v_mfma_f32_16x16x32_bf16 v[70:73], v[216:219], v[208:211], v[70:73]
	v_mfma_f32_16x16x32_bf16 v[66:69], v[240:243], v[208:211], v[66:69]
	s_barrier
	s_mov_b32 m0, s15
	v_lshl_add_u64 v[160:161], s[8:9], 0, v[130:131]
	ds_read_b128 v[180:183], v143 offset:16384
	ds_read_b128 v[184:187], v143 offset:17408
	ds_read_b128 v[188:191], v143 offset:18432
	ds_read_b128 v[192:195], v143 offset:19456
	ds_read_b128 v[196:199], v143 offset:20480
	ds_read_b128 v[200:203], v143 offset:21504
	ds_read_b128 v[204:207], v143 offset:22528
	ds_read_b128 v[208:211], v143 offset:23552
	global_load_lds_dwordx4 v[160:161], off
	v_lshl_add_u64 v[168:169], s[8:9], 0, v[134:135]
	s_mov_b32 m0, s16
	s_nop 0
	global_load_lds_dwordx4 v[168:169], off
	s_barrier
	s_waitcnt lgkmcnt(0)
	v_mfma_f32_16x16x32_bf16 v[62:65], v[148:151], v[180:183], v[62:65]
	v_mfma_f32_16x16x32_bf16 v[58:61], v[172:175], v[180:183], v[58:61]
	v_mfma_f32_16x16x32_bf16 v[46:49], v[148:151], v[188:191], v[46:49]
	v_mfma_f32_16x16x32_bf16 v[42:45], v[172:175], v[188:191], v[42:45]
	v_mfma_f32_16x16x32_bf16 v[30:33], v[148:151], v[196:199], v[30:33]
	v_mfma_f32_16x16x32_bf16 v[26:29], v[172:175], v[196:199], v[26:29]
	v_mfma_f32_16x16x32_bf16 v[14:17], v[148:151], v[204:207], v[14:17]
	v_mfma_f32_16x16x32_bf16 v[10:13], v[172:175], v[204:207], v[10:13]
	v_mfma_f32_16x16x32_bf16 v[62:65], v[152:155], v[184:187], v[62:65]
	v_mfma_f32_16x16x32_bf16 v[58:61], v[176:179], v[184:187], v[58:61]
	v_mfma_f32_16x16x32_bf16 v[46:49], v[152:155], v[192:195], v[46:49]
	v_mfma_f32_16x16x32_bf16 v[42:45], v[176:179], v[192:195], v[42:45]
	v_mfma_f32_16x16x32_bf16 v[30:33], v[152:155], v[200:203], v[30:33]
	v_mfma_f32_16x16x32_bf16 v[26:29], v[176:179], v[200:203], v[26:29]
	v_mfma_f32_16x16x32_bf16 v[14:17], v[152:155], v[208:211], v[14:17]
	v_mfma_f32_16x16x32_bf16 v[10:13], v[176:179], v[208:211], v[10:13]
	s_barrier
	s_add_u32 s24, s6, 0x10000
	s_addc_u32 s25, s7, 0
	s_add_i32 s26, s26, s14
	v_lshl_add_u64 v[148:149], s[24:25], 0, v[132:133]
	s_mov_b32 m0, s26
	s_nop 0
	global_load_lds_dwordx4 v[148:149], off
	v_lshl_add_u64 v[148:149], s[24:25], 0, v[136:137]
	s_add_i32 m0, s26, 0x2000
	s_nop 0
	global_load_lds_dwordx4 v[148:149], off
	s_waitcnt vmcnt(6)
	s_barrier
	v_mfma_f32_16x16x32_bf16 v[54:57], v[212:215], v[180:183], v[54:57]
	v_mfma_f32_16x16x32_bf16 v[50:53], v[236:239], v[180:183], v[50:53]
	v_mfma_f32_16x16x32_bf16 v[38:41], v[212:215], v[188:191], v[38:41]
	v_mfma_f32_16x16x32_bf16 v[34:37], v[236:239], v[188:191], v[34:37]
	v_mfma_f32_16x16x32_bf16 v[22:25], v[212:215], v[196:199], v[22:25]
	v_mfma_f32_16x16x32_bf16 v[18:21], v[236:239], v[196:199], v[18:21]
	v_mfma_f32_16x16x32_bf16 v[6:9], v[212:215], v[204:207], v[6:9]
	v_mfma_f32_16x16x32_bf16 v[2:5], v[236:239], v[204:207], v[2:5]
	v_mfma_f32_16x16x32_bf16 v[54:57], v[216:219], v[184:187], v[54:57]
	v_mfma_f32_16x16x32_bf16 v[50:53], v[240:243], v[184:187], v[50:53]
	v_mfma_f32_16x16x32_bf16 v[38:41], v[216:219], v[192:195], v[38:41]
	v_mfma_f32_16x16x32_bf16 v[34:37], v[240:243], v[192:195], v[34:37]
	v_mfma_f32_16x16x32_bf16 v[22:25], v[216:219], v[200:203], v[22:25]
	v_mfma_f32_16x16x32_bf16 v[18:21], v[240:243], v[200:203], v[18:21]
	v_mfma_f32_16x16x32_bf16 v[6:9], v[216:219], v[208:211], v[6:9]
	v_mfma_f32_16x16x32_bf16 v[2:5], v[240:243], v[208:211], v[2:5]
	s_barrier
	s_add_i32 s24, 0, 0x18000
	v_add_u32_e32 v159, s24, v142
	ds_read_b128 v[148:151], v159
	ds_read_b128 v[152:155], v159 offset:1024
	ds_read_b128 v[172:175], v159 offset:2048
	ds_read_b128 v[176:179], v159 offset:3072
	s_add_u32 s8, s8, 0x10000
	s_addc_u32 s9, s9, 0
	s_mov_b32 m0, s17
	v_lshl_add_u64 v[212:213], s[8:9], 0, v[130:131]
	ds_read_b128 v[180:183], v143 offset:32768
	ds_read_b128 v[184:187], v143 offset:33792
	ds_read_b128 v[188:191], v143 offset:34816
	ds_read_b128 v[192:195], v143 offset:35840
	ds_read_b128 v[196:199], v143 offset:36864
	ds_read_b128 v[200:203], v143 offset:37888
	ds_read_b128 v[204:207], v143 offset:38912
	ds_read_b128 v[208:211], v143 offset:39936
	global_load_lds_dwordx4 v[212:213], off
	v_lshl_add_u64 v[212:213], s[8:9], 0, v[134:135]
	s_mov_b32 m0, s18
	s_nop 0
	global_load_lds_dwordx4 v[212:213], off
	s_waitcnt lgkmcnt(8)
	s_barrier
	s_waitcnt lgkmcnt(0)
	v_mfma_f32_16x16x32_bf16 v[126:129], v[148:151], v[180:183], v[126:129]
	v_mfma_f32_16x16x32_bf16 v[122:125], v[172:175], v[180:183], v[122:125]
	v_mfma_f32_16x16x32_bf16 v[110:113], v[148:151], v[188:191], v[110:113]
	v_mfma_f32_16x16x32_bf16 v[106:109], v[172:175], v[188:191], v[106:109]
	v_mfma_f32_16x16x32_bf16 v[94:97], v[148:151], v[196:199], v[94:97]
	v_mfma_f32_16x16x32_bf16 v[90:93], v[172:175], v[196:199], v[90:93]
	v_mfma_f32_16x16x32_bf16 v[78:81], v[148:151], v[204:207], v[78:81]
	v_mfma_f32_16x16x32_bf16 v[74:77], v[172:175], v[204:207], v[74:77]
	v_mfma_f32_16x16x32_bf16 v[126:129], v[152:155], v[184:187], v[126:129]
	v_mfma_f32_16x16x32_bf16 v[122:125], v[176:179], v[184:187], v[122:125]
	v_mfma_f32_16x16x32_bf16 v[110:113], v[152:155], v[192:195], v[110:113]
	v_mfma_f32_16x16x32_bf16 v[106:109], v[176:179], v[192:195], v[106:109]
	v_mfma_f32_16x16x32_bf16 v[94:97], v[152:155], v[200:203], v[94:97]
	v_mfma_f32_16x16x32_bf16 v[90:93], v[176:179], v[200:203], v[90:93]
	v_mfma_f32_16x16x32_bf16 v[78:81], v[152:155], v[208:211], v[78:81]
	v_mfma_f32_16x16x32_bf16 v[74:77], v[176:179], v[208:211], v[74:77]
	s_barrier
	s_add_i32 s8, 0, 0x1c000
	s_add_i32 s9, s24, s14
	v_add_u32_e32 v159, s8, v142
	v_lshl_add_u64 v[144:145], v[144:145], 0, s[84:85]
	s_mov_b32 m0, s9
	ds_read_b128 v[212:215], v159
	ds_read_b128 v[216:219], v159 offset:1024
	ds_read_b128 v[236:239], v159 offset:2048
	ds_read_b128 v[240:243], v159 offset:3072
	global_load_lds_dwordx4 v[144:145], off
	v_lshl_add_u64 v[144:145], v[156:157], 0, s[84:85]
	s_add_i32 m0, s9, 0x2000
	s_nop 0
	global_load_lds_dwordx4 v[144:145], off
	s_barrier
	s_waitcnt lgkmcnt(0)
	v_mfma_f32_16x16x32_bf16 v[118:121], v[212:215], v[180:183], v[118:121]
	v_mfma_f32_16x16x32_bf16 v[114:117], v[236:239], v[180:183], v[114:117]
	v_mfma_f32_16x16x32_bf16 v[102:105], v[212:215], v[188:191], v[102:105]
	v_mfma_f32_16x16x32_bf16 v[98:101], v[236:239], v[188:191], v[98:101]
	v_mfma_f32_16x16x32_bf16 v[86:89], v[212:215], v[196:199], v[86:89]
	v_mfma_f32_16x16x32_bf16 v[82:85], v[236:239], v[196:199], v[82:85]
	v_mfma_f32_16x16x32_bf16 v[70:73], v[212:215], v[204:207], v[70:73]
	v_mfma_f32_16x16x32_bf16 v[66:69], v[236:239], v[204:207], v[66:69]
	v_mfma_f32_16x16x32_bf16 v[118:121], v[216:219], v[184:187], v[118:121]
	v_mfma_f32_16x16x32_bf16 v[114:117], v[240:243], v[184:187], v[114:117]
	v_mfma_f32_16x16x32_bf16 v[102:105], v[216:219], v[192:195], v[102:105]
	v_mfma_f32_16x16x32_bf16 v[98:101], v[240:243], v[192:195], v[98:101]
	v_mfma_f32_16x16x32_bf16 v[86:89], v[216:219], v[200:203], v[86:89]
	v_mfma_f32_16x16x32_bf16 v[82:85], v[240:243], v[200:203], v[82:85]
	v_mfma_f32_16x16x32_bf16 v[70:73], v[216:219], v[208:211], v[70:73]
	v_mfma_f32_16x16x32_bf16 v[66:69], v[240:243], v[208:211], v[66:69]
	s_barrier
	s_mov_b32 m0, s19
	v_lshl_add_u64 v[144:145], v[160:161], 0, s[84:85]
	ds_read_b128 v[180:183], v143 offset:49152
	ds_read_b128 v[184:187], v143 offset:50176
	ds_read_b128 v[188:191], v143 offset:51200
	ds_read_b128 v[192:195], v143 offset:52224
	ds_read_b128 v[196:199], v143 offset:53248
	ds_read_b128 v[200:203], v143 offset:54272
	ds_read_b128 v[204:207], v143 offset:55296
	ds_read_b128 v[208:211], v143 offset:56320
	global_load_lds_dwordx4 v[144:145], off
	v_lshl_add_u64 v[144:145], v[168:169], 0, s[84:85]
	s_mov_b32 m0, s20
	s_nop 0
	global_load_lds_dwordx4 v[144:145], off
	s_barrier
	s_waitcnt lgkmcnt(0)
	v_mfma_f32_16x16x32_bf16 v[62:65], v[148:151], v[180:183], v[62:65]
	v_mfma_f32_16x16x32_bf16 v[58:61], v[172:175], v[180:183], v[58:61]
	v_mfma_f32_16x16x32_bf16 v[46:49], v[148:151], v[188:191], v[46:49]
	v_mfma_f32_16x16x32_bf16 v[42:45], v[172:175], v[188:191], v[42:45]
	v_mfma_f32_16x16x32_bf16 v[30:33], v[148:151], v[196:199], v[30:33]
	v_mfma_f32_16x16x32_bf16 v[26:29], v[172:175], v[196:199], v[26:29]
	v_mfma_f32_16x16x32_bf16 v[14:17], v[148:151], v[204:207], v[14:17]
	v_mfma_f32_16x16x32_bf16 v[10:13], v[172:175], v[204:207], v[10:13]
	v_mfma_f32_16x16x32_bf16 v[62:65], v[152:155], v[184:187], v[62:65]
	v_mfma_f32_16x16x32_bf16 v[58:61], v[176:179], v[184:187], v[58:61]
	v_mfma_f32_16x16x32_bf16 v[46:49], v[152:155], v[192:195], v[46:49]
	v_mfma_f32_16x16x32_bf16 v[42:45], v[176:179], v[192:195], v[42:45]
	v_mfma_f32_16x16x32_bf16 v[30:33], v[152:155], v[200:203], v[30:33]
	v_mfma_f32_16x16x32_bf16 v[26:29], v[176:179], v[200:203], v[26:29]
	v_mfma_f32_16x16x32_bf16 v[14:17], v[152:155], v[208:211], v[14:17]
	v_mfma_f32_16x16x32_bf16 v[10:13], v[176:179], v[208:211], v[10:13]
	s_barrier
	s_add_u32 s6, s6, 0x10080
	s_addc_u32 s7, s7, 0
	s_add_i32 s8, s8, s14
	v_lshl_add_u64 v[144:145], s[6:7], 0, v[132:133]
	s_mov_b32 m0, s8
	s_nop 0
	global_load_lds_dwordx4 v[144:145], off
	v_lshl_add_u64 v[144:145], s[6:7], 0, v[136:137]
	s_add_i32 m0, s8, 0x2000
	s_nop 0
	global_load_lds_dwordx4 v[144:145], off
	s_waitcnt vmcnt(6)
	s_barrier
	v_mfma_f32_16x16x32_bf16 v[54:57], v[212:215], v[180:183], v[54:57]
	v_mfma_f32_16x16x32_bf16 v[50:53], v[236:239], v[180:183], v[50:53]
	v_mfma_f32_16x16x32_bf16 v[38:41], v[212:215], v[188:191], v[38:41]
	v_mfma_f32_16x16x32_bf16 v[34:37], v[236:239], v[188:191], v[34:37]
	v_mfma_f32_16x16x32_bf16 v[22:25], v[212:215], v[196:199], v[22:25]
	v_mfma_f32_16x16x32_bf16 v[18:21], v[236:239], v[196:199], v[18:21]
	v_mfma_f32_16x16x32_bf16 v[6:9], v[212:215], v[204:207], v[6:9]
	v_mfma_f32_16x16x32_bf16 v[2:5], v[236:239], v[204:207], v[2:5]
	v_mfma_f32_16x16x32_bf16 v[54:57], v[216:219], v[184:187], v[54:57]
	v_mfma_f32_16x16x32_bf16 v[50:53], v[240:243], v[184:187], v[50:53]
	v_mfma_f32_16x16x32_bf16 v[38:41], v[216:219], v[192:195], v[38:41]
	v_mfma_f32_16x16x32_bf16 v[34:37], v[240:243], v[192:195], v[34:37]
	v_mfma_f32_16x16x32_bf16 v[22:25], v[216:219], v[200:203], v[22:25]
	v_mfma_f32_16x16x32_bf16 v[18:21], v[240:243], v[200:203], v[18:21]
	v_mfma_f32_16x16x32_bf16 v[6:9], v[216:219], v[208:211], v[6:9]
	v_mfma_f32_16x16x32_bf16 v[2:5], v[240:243], v[208:211], v[2:5]
	s_barrier
	s_add_u32 s4, s4, 0x100
	s_addc_u32 s5, s5, 0
	s_cmp_ge_i32 s23, s21
	s_mov_b32 s6, s23
	s_cbranch_scc0 .LBB0_427

.LBB0_439:
	s_add_i32 s23, s6, 2
	s_add_u32 s7, s4, 0xe2df0080
	s_addc_u32 s8, s5, -1
	s_cmp_lg_u32 s22, s6
	s_cselect_b32 s6, s7, 0
	s_cselect_b32 s24, s8, 0
	s_add_u32 s8, s2, s6
	s_addc_u32 s9, s3, s24
	s_add_i32 s25, 0, 0x10000
	v_add_u32_e32 v144, s25, v142
	ds_read_b128 v[148:151], v144
	ds_read_b128 v[152:155], v144 offset:1024
	ds_read_b128 v[172:175], v144 offset:2048
	ds_read_b128 v[176:179], v144 offset:3072
	s_add_u32 s6, s0, s6
	s_addc_u32 s7, s1, s24
	v_lshl_add_u64 v[144:145], v[138:139], 0, s[4:5]
	s_add_i32 m0, s15, 0xc000
	ds_read_b128 v[180:183], v143
	ds_read_b128 v[184:187], v143 offset:1024
	ds_read_b128 v[188:191], v143 offset:2048
	ds_read_b128 v[192:195], v143 offset:3072
	ds_read_b128 v[196:199], v143 offset:4096
	ds_read_b128 v[200:203], v143 offset:5120
	ds_read_b128 v[204:207], v143 offset:6144
	ds_read_b128 v[208:211], v143 offset:7168
	global_load_lds_dwordx4 v[144:145], off
	v_lshl_add_u64 v[144:145], v[140:141], 0, s[4:5]
	s_add_i32 m0, s15, 0xe000
	s_nop 0
	global_load_lds_dwordx4 v[144:145], off
	s_waitcnt lgkmcnt(8)
	s_barrier
	s_waitcnt lgkmcnt(0)
	v_mfma_f32_16x16x32_bf16 v[126:129], v[148:151], v[180:183], v[126:129]
	v_mfma_f32_16x16x32_bf16 v[122:125], v[172:175], v[180:183], v[122:125]
	v_mfma_f32_16x16x32_bf16 v[110:113], v[148:151], v[188:191], v[110:113]
	v_mfma_f32_16x16x32_bf16 v[106:109], v[172:175], v[188:191], v[106:109]
	v_mfma_f32_16x16x32_bf16 v[94:97], v[148:151], v[196:199], v[94:97]
	v_mfma_f32_16x16x32_bf16 v[90:93], v[172:175], v[196:199], v[90:93]
	v_mfma_f32_16x16x32_bf16 v[78:81], v[148:151], v[204:207], v[78:81]
	v_mfma_f32_16x16x32_bf16 v[74:77], v[172:175], v[204:207], v[74:77]
	v_mfma_f32_16x16x32_bf16 v[126:129], v[152:155], v[184:187], v[126:129]
	v_mfma_f32_16x16x32_bf16 v[122:125], v[176:179], v[184:187], v[122:125]
	v_mfma_f32_16x16x32_bf16 v[110:113], v[152:155], v[192:195], v[110:113]
	v_mfma_f32_16x16x32_bf16 v[106:109], v[176:179], v[192:195], v[106:109]
	v_mfma_f32_16x16x32_bf16 v[94:97], v[152:155], v[200:203], v[94:97]
	v_mfma_f32_16x16x32_bf16 v[90:93], v[176:179], v[200:203], v[90:93]
	v_mfma_f32_16x16x32_bf16 v[78:81], v[152:155], v[208:211], v[78:81]
	v_mfma_f32_16x16x32_bf16 v[74:77], v[176:179], v[208:211], v[74:77]
	s_barrier
	s_add_i32 s26, 0, 0x14000
	v_add_u32_e32 v144, s26, v142
	s_add_i32 s24, s25, s14
	ds_read_b128 v[212:215], v144
	ds_read_b128 v[216:219], v144 offset:1024
	ds_read_b128 v[236:239], v144 offset:2048
	ds_read_b128 v[240:243], v144 offset:3072
	v_lshl_add_u64 v[144:145], s[6:7], 0, v[132:133]
	s_mov_b32 m0, s24
	v_lshl_add_u64 v[156:157], s[6:7], 0, v[136:137]
	global_load_lds_dwordx4 v[144:145], off
	s_add_i32 m0, s24, 0x2000
	s_nop 0
	global_load_lds_dwordx4 v[156:157], off
	s_barrier
	s_waitcnt lgkmcnt(0)
	v_mfma_f32_16x16x32_bf16 v[118:121], v[212:215], v[180:183], v[118:121]
	v_mfma_f32_16x16x32_bf16 v[114:117], v[236:239], v[180:183], v[114:117]
	v_mfma_f32_16x16x32_bf16 v[102:105], v[212:215], v[188:191], v[102:105]
	v_mfma_f32_16x16x32_bf16 v[98:101], v[236:239], v[188:191], v[98:101]
	v_mfma_f32_16x16x32_bf16 v[86:89], v[212:215], v[196:199], v[86:89]
	v_mfma_f32_16x16x32_bf16 v[82:85], v[236:239], v[196:199], v[82:85]
	v_mfma_f32_16x16x32_bf16 v[70:73], v[212:215], v[204:207], v[70:73]
	v_mfma_f32_16x16x32_bf16 v[66:69], v[236:239], v[204:207], v[66:69]
	v_mfma_f32_16x16x32_bf16 v[118:121], v[216:219], v[184:187], v[118:121]
	v_mfma_f32_16x16x32_bf16 v[114:117], v[240:243], v[184:187], v[114:117]
	v_mfma_f32_16x16x32_bf16 v[102:105], v[216:219], v[192:195], v[102:105]
	v_mfma_f32_16x16x32_bf16 v[98:101], v[240:243], v[192:195], v[98:101]
	v_mfma_f32_16x16x32_bf16 v[86:89], v[216:219], v[200:203], v[86:89]
	v_mfma_f32_16x16x32_bf16 v[82:85], v[240:243], v[200:203], v[82:85]
	v_mfma_f32_16x16x32_bf16 v[70:73], v[216:219], v[208:211], v[70:73]
	v_mfma_f32_16x16x32_bf16 v[66:69], v[240:243], v[208:211], v[66:69]
	s_barrier
	s_mov_b32 m0, s15
	v_lshl_add_u64 v[160:161], s[8:9], 0, v[130:131]
	ds_read_b128 v[180:183], v143 offset:16384
	ds_read_b128 v[184:187], v143 offset:17408
	ds_read_b128 v[188:191], v143 offset:18432
	ds_read_b128 v[192:195], v143 offset:19456
	ds_read_b128 v[196:199], v143 offset:20480
	ds_read_b128 v[200:203], v143 offset:21504
	ds_read_b128 v[204:207], v143 offset:22528
	ds_read_b128 v[208:211], v143 offset:23552
	global_load_lds_dwordx4 v[160:161], off
	v_lshl_add_u64 v[168:169], s[8:9], 0, v[134:135]
	s_mov_b32 m0, s16
	s_nop 0
	global_load_lds_dwordx4 v[168:169], off
	s_barrier
	s_waitcnt lgkmcnt(0)
	v_mfma_f32_16x16x32_bf16 v[62:65], v[148:151], v[180:183], v[62:65]
	v_mfma_f32_16x16x32_bf16 v[58:61], v[172:175], v[180:183], v[58:61]
	v_mfma_f32_16x16x32_bf16 v[46:49], v[148:151], v[188:191], v[46:49]
	v_mfma_f32_16x16x32_bf16 v[42:45], v[172:175], v[188:191], v[42:45]
	v_mfma_f32_16x16x32_bf16 v[30:33], v[148:151], v[196:199], v[30:33]
	v_mfma_f32_16x16x32_bf16 v[26:29], v[172:175], v[196:199], v[26:29]
	v_mfma_f32_16x16x32_bf16 v[14:17], v[148:151], v[204:207], v[14:17]
	v_mfma_f32_16x16x32_bf16 v[10:13], v[172:175], v[204:207], v[10:13]
	v_mfma_f32_16x16x32_bf16 v[62:65], v[152:155], v[184:187], v[62:65]
	v_mfma_f32_16x16x32_bf16 v[58:61], v[176:179], v[184:187], v[58:61]
	v_mfma_f32_16x16x32_bf16 v[46:49], v[152:155], v[192:195], v[46:49]
	v_mfma_f32_16x16x32_bf16 v[42:45], v[176:179], v[192:195], v[42:45]
	v_mfma_f32_16x16x32_bf16 v[30:33], v[152:155], v[200:203], v[30:33]
	v_mfma_f32_16x16x32_bf16 v[26:29], v[176:179], v[200:203], v[26:29]
	v_mfma_f32_16x16x32_bf16 v[14:17], v[152:155], v[208:211], v[14:17]
	v_mfma_f32_16x16x32_bf16 v[10:13], v[176:179], v[208:211], v[10:13]
	s_barrier
	s_add_u32 s24, s6, 0x10000
	s_addc_u32 s25, s7, 0
	s_add_i32 s26, s26, s14
	v_lshl_add_u64 v[148:149], s[24:25], 0, v[132:133]
	s_mov_b32 m0, s26
	s_nop 0
	global_load_lds_dwordx4 v[148:149], off
	v_lshl_add_u64 v[148:149], s[24:25], 0, v[136:137]
	s_add_i32 m0, s26, 0x2000
	s_nop 0
	global_load_lds_dwordx4 v[148:149], off
	s_waitcnt vmcnt(6)
	s_barrier
	v_mfma_f32_16x16x32_bf16 v[54:57], v[212:215], v[180:183], v[54:57]
	v_mfma_f32_16x16x32_bf16 v[50:53], v[236:239], v[180:183], v[50:53]
	v_mfma_f32_16x16x32_bf16 v[38:41], v[212:215], v[188:191], v[38:41]
	v_mfma_f32_16x16x32_bf16 v[34:37], v[236:239], v[188:191], v[34:37]
	v_mfma_f32_16x16x32_bf16 v[22:25], v[212:215], v[196:199], v[22:25]
	v_mfma_f32_16x16x32_bf16 v[18:21], v[236:239], v[196:199], v[18:21]
	v_mfma_f32_16x16x32_bf16 v[6:9], v[212:215], v[204:207], v[6:9]
	v_mfma_f32_16x16x32_bf16 v[2:5], v[236:239], v[204:207], v[2:5]
	v_mfma_f32_16x16x32_bf16 v[54:57], v[216:219], v[184:187], v[54:57]
	v_mfma_f32_16x16x32_bf16 v[50:53], v[240:243], v[184:187], v[50:53]
	v_mfma_f32_16x16x32_bf16 v[38:41], v[216:219], v[192:195], v[38:41]
	v_mfma_f32_16x16x32_bf16 v[34:37], v[240:243], v[192:195], v[34:37]
	v_mfma_f32_16x16x32_bf16 v[22:25], v[216:219], v[200:203], v[22:25]
	v_mfma_f32_16x16x32_bf16 v[18:21], v[240:243], v[200:203], v[18:21]
	v_mfma_f32_16x16x32_bf16 v[6:9], v[216:219], v[208:211], v[6:9]
	v_mfma_f32_16x16x32_bf16 v[2:5], v[240:243], v[208:211], v[2:5]
	s_barrier
	s_add_i32 s24, 0, 0x18000
	v_add_u32_e32 v159, s24, v142
	ds_read_b128 v[148:151], v159
	ds_read_b128 v[152:155], v159 offset:1024
	ds_read_b128 v[172:175], v159 offset:2048
	ds_read_b128 v[176:179], v159 offset:3072
	s_add_u32 s8, s8, 0x10000
	s_addc_u32 s9, s9, 0
	s_mov_b32 m0, s17
	v_lshl_add_u64 v[212:213], s[8:9], 0, v[130:131]
	ds_read_b128 v[180:183], v143 offset:32768
	ds_read_b128 v[184:187], v143 offset:33792
	ds_read_b128 v[188:191], v143 offset:34816
	ds_read_b128 v[192:195], v143 offset:35840
	ds_read_b128 v[196:199], v143 offset:36864
	ds_read_b128 v[200:203], v143 offset:37888
	ds_read_b128 v[204:207], v143 offset:38912
	ds_read_b128 v[208:211], v143 offset:39936
	global_load_lds_dwordx4 v[212:213], off
	v_lshl_add_u64 v[212:213], s[8:9], 0, v[134:135]
	s_mov_b32 m0, s18
	s_nop 0
	global_load_lds_dwordx4 v[212:213], off
	s_waitcnt lgkmcnt(8)
	s_barrier
	s_waitcnt lgkmcnt(0)
	v_mfma_f32_16x16x32_bf16 v[126:129], v[148:151], v[180:183], v[126:129]
	v_mfma_f32_16x16x32_bf16 v[122:125], v[172:175], v[180:183], v[122:125]
	v_mfma_f32_16x16x32_bf16 v[110:113], v[148:151], v[188:191], v[110:113]
	v_mfma_f32_16x16x32_bf16 v[106:109], v[172:175], v[188:191], v[106:109]
	v_mfma_f32_16x16x32_bf16 v[94:97], v[148:151], v[196:199], v[94:97]
	v_mfma_f32_16x16x32_bf16 v[90:93], v[172:175], v[196:199], v[90:93]
	v_mfma_f32_16x16x32_bf16 v[78:81], v[148:151], v[204:207], v[78:81]
	v_mfma_f32_16x16x32_bf16 v[74:77], v[172:175], v[204:207], v[74:77]
	v_mfma_f32_16x16x32_bf16 v[126:129], v[152:155], v[184:187], v[126:129]
	v_mfma_f32_16x16x32_bf16 v[122:125], v[176:179], v[184:187], v[122:125]
	v_mfma_f32_16x16x32_bf16 v[110:113], v[152:155], v[192:195], v[110:113]
	v_mfma_f32_16x16x32_bf16 v[106:109], v[176:179], v[192:195], v[106:109]
	v_mfma_f32_16x16x32_bf16 v[94:97], v[152:155], v[200:203], v[94:97]
	v_mfma_f32_16x16x32_bf16 v[90:93], v[176:179], v[200:203], v[90:93]
	v_mfma_f32_16x16x32_bf16 v[78:81], v[152:155], v[208:211], v[78:81]
	v_mfma_f32_16x16x32_bf16 v[74:77], v[176:179], v[208:211], v[74:77]
	s_barrier
	s_add_i32 s8, 0, 0x1c000
	s_add_i32 s9, s24, s14
	v_add_u32_e32 v159, s8, v142
	v_lshl_add_u64 v[144:145], v[144:145], 0, s[84:85]
	s_mov_b32 m0, s9
	ds_read_b128 v[212:215], v159
	ds_read_b128 v[216:219], v159 offset:1024
	ds_read_b128 v[236:239], v159 offset:2048
	ds_read_b128 v[240:243], v159 offset:3072
	global_load_lds_dwordx4 v[144:145], off
	v_lshl_add_u64 v[144:145], v[156:157], 0, s[84:85]
	s_add_i32 m0, s9, 0x2000
	s_nop 0
	global_load_lds_dwordx4 v[144:145], off
	s_barrier
	s_waitcnt lgkmcnt(0)
	v_mfma_f32_16x16x32_bf16 v[118:121], v[212:215], v[180:183], v[118:121]
	v_mfma_f32_16x16x32_bf16 v[114:117], v[236:239], v[180:183], v[114:117]
	v_mfma_f32_16x16x32_bf16 v[102:105], v[212:215], v[188:191], v[102:105]
	v_mfma_f32_16x16x32_bf16 v[98:101], v[236:239], v[188:191], v[98:101]
	v_mfma_f32_16x16x32_bf16 v[86:89], v[212:215], v[196:199], v[86:89]
	v_mfma_f32_16x16x32_bf16 v[82:85], v[236:239], v[196:199], v[82:85]
	v_mfma_f32_16x16x32_bf16 v[70:73], v[212:215], v[204:207], v[70:73]
	v_mfma_f32_16x16x32_bf16 v[66:69], v[236:239], v[204:207], v[66:69]
	v_mfma_f32_16x16x32_bf16 v[118:121], v[216:219], v[184:187], v[118:121]
	v_mfma_f32_16x16x32_bf16 v[114:117], v[240:243], v[184:187], v[114:117]
	v_mfma_f32_16x16x32_bf16 v[102:105], v[216:219], v[192:195], v[102:105]
	v_mfma_f32_16x16x32_bf16 v[98:101], v[240:243], v[192:195], v[98:101]
	v_mfma_f32_16x16x32_bf16 v[86:89], v[216:219], v[200:203], v[86:89]
	v_mfma_f32_16x16x32_bf16 v[82:85], v[240:243], v[200:203], v[82:85]
	v_mfma_f32_16x16x32_bf16 v[70:73], v[216:219], v[208:211], v[70:73]
	v_mfma_f32_16x16x32_bf16 v[66:69], v[240:243], v[208:211], v[66:69]
	s_barrier
	s_mov_b32 m0, s19
	v_lshl_add_u64 v[144:145], v[160:161], 0, s[84:85]
	ds_read_b128 v[180:183], v143 offset:49152
	ds_read_b128 v[184:187], v143 offset:50176
	ds_read_b128 v[188:191], v143 offset:51200
	ds_read_b128 v[192:195], v143 offset:52224
	ds_read_b128 v[196:199], v143 offset:53248
	ds_read_b128 v[200:203], v143 offset:54272
	ds_read_b128 v[204:207], v143 offset:55296
	ds_read_b128 v[208:211], v143 offset:56320
	global_load_lds_dwordx4 v[144:145], off
	v_lshl_add_u64 v[144:145], v[168:169], 0, s[84:85]
	s_mov_b32 m0, s20
	s_nop 0
	global_load_lds_dwordx4 v[144:145], off
	s_barrier
	s_waitcnt lgkmcnt(0)
	v_mfma_f32_16x16x32_bf16 v[62:65], v[148:151], v[180:183], v[62:65]
	v_mfma_f32_16x16x32_bf16 v[58:61], v[172:175], v[180:183], v[58:61]
	v_mfma_f32_16x16x32_bf16 v[46:49], v[148:151], v[188:191], v[46:49]
	v_mfma_f32_16x16x32_bf16 v[42:45], v[172:175], v[188:191], v[42:45]
	v_mfma_f32_16x16x32_bf16 v[30:33], v[148:151], v[196:199], v[30:33]
	v_mfma_f32_16x16x32_bf16 v[26:29], v[172:175], v[196:199], v[26:29]
	v_mfma_f32_16x16x32_bf16 v[14:17], v[148:151], v[204:207], v[14:17]
	v_mfma_f32_16x16x32_bf16 v[10:13], v[172:175], v[204:207], v[10:13]
	v_mfma_f32_16x16x32_bf16 v[62:65], v[152:155], v[184:187], v[62:65]
	v_mfma_f32_16x16x32_bf16 v[58:61], v[176:179], v[184:187], v[58:61]
	v_mfma_f32_16x16x32_bf16 v[46:49], v[152:155], v[192:195], v[46:49]
	v_mfma_f32_16x16x32_bf16 v[42:45], v[176:179], v[192:195], v[42:45]
	v_mfma_f32_16x16x32_bf16 v[30:33], v[152:155], v[200:203], v[30:33]
	v_mfma_f32_16x16x32_bf16 v[26:29], v[176:179], v[200:203], v[26:29]
	v_mfma_f32_16x16x32_bf16 v[14:17], v[152:155], v[208:211], v[14:17]
	v_mfma_f32_16x16x32_bf16 v[10:13], v[176:179], v[208:211], v[10:13]
	s_barrier
	s_add_u32 s6, s6, 0x10080
	s_addc_u32 s7, s7, 0
	s_add_i32 s8, s8, s14
	v_lshl_add_u64 v[144:145], s[6:7], 0, v[132:133]
	s_mov_b32 m0, s8
	s_nop 0
	global_load_lds_dwordx4 v[144:145], off
	v_lshl_add_u64 v[144:145], s[6:7], 0, v[136:137]
	s_add_i32 m0, s8, 0x2000
	s_nop 0
	global_load_lds_dwordx4 v[144:145], off
	s_waitcnt vmcnt(6)
	s_barrier
	v_mfma_f32_16x16x32_bf16 v[54:57], v[212:215], v[180:183], v[54:57]
	v_mfma_f32_16x16x32_bf16 v[50:53], v[236:239], v[180:183], v[50:53]
	v_mfma_f32_16x16x32_bf16 v[38:41], v[212:215], v[188:191], v[38:41]
	v_mfma_f32_16x16x32_bf16 v[34:37], v[236:239], v[188:191], v[34:37]
	v_mfma_f32_16x16x32_bf16 v[22:25], v[212:215], v[196:199], v[22:25]
	v_mfma_f32_16x16x32_bf16 v[18:21], v[236:239], v[196:199], v[18:21]
	v_mfma_f32_16x16x32_bf16 v[6:9], v[212:215], v[204:207], v[6:9]
	v_mfma_f32_16x16x32_bf16 v[2:5], v[236:239], v[204:207], v[2:5]
	v_mfma_f32_16x16x32_bf16 v[54:57], v[216:219], v[184:187], v[54:57]
	v_mfma_f32_16x16x32_bf16 v[50:53], v[240:243], v[184:187], v[50:53]
	v_mfma_f32_16x16x32_bf16 v[38:41], v[216:219], v[192:195], v[38:41]
	v_mfma_f32_16x16x32_bf16 v[34:37], v[240:243], v[192:195], v[34:37]
	v_mfma_f32_16x16x32_bf16 v[22:25], v[216:219], v[200:203], v[22:25]
	v_mfma_f32_16x16x32_bf16 v[18:21], v[240:243], v[200:203], v[18:21]
	v_mfma_f32_16x16x32_bf16 v[6:9], v[216:219], v[208:211], v[6:9]
	v_mfma_f32_16x16x32_bf16 v[2:5], v[240:243], v[208:211], v[2:5]
	s_barrier
	s_add_u32 s4, s4, 0x100
	s_addc_u32 s5, s5, 0
	s_cmp_ge_i32 s23, s21
	s_mov_b32 s6, s23
	s_cbranch_scc0 .LBB0_439

.LBB0_454:
	s_add_i32 s52, s20, 2
	s_add_u32 s21, s18, 0xfffc0080
	s_addc_u32 s22, s19, -1
	s_add_i32 s53, 0, 0x10000
	v_add_u32_e32 v154, s53, v159
	ds_read_b128 v[130:133], v154
	ds_read_b128 v[134:137], v154 offset:1024
	ds_read_b128 v[150:153], v154 offset:2048
	ds_read_b128 v[154:157], v154 offset:3072
	s_cmp_eq_u32 s44, s20
	s_cselect_b32 s20, s49, s50
	s_cselect_b32 s23, s9, s22
	s_cselect_b32 s22, s11, s21
	s_cselect_b32 s21, s48, s51
	v_lshl_add_u64 v[168:169], s[18:19], 0, v[146:147]
	s_add_i32 m0, s29, 0xc000
	ds_read_b128 v[172:175], v160
	ds_read_b128 v[176:179], v160 offset:1024
	ds_read_b128 v[180:183], v160 offset:2048
	ds_read_b128 v[184:187], v160 offset:3072
	ds_read_b128 v[188:191], v160 offset:4096
	ds_read_b128 v[192:195], v160 offset:5120
	ds_read_b128 v[196:199], v160 offset:6144
	ds_read_b128 v[200:203], v160 offset:7168
	global_load_lds_dwordx4 v[168:169], off
	v_lshl_add_u64 v[168:169], s[18:19], 0, v[148:149]
	s_add_i32 m0, s29, 0xe000
	s_nop 0
	global_load_lds_dwordx4 v[168:169], off
	s_waitcnt lgkmcnt(8)
	s_barrier
	s_waitcnt lgkmcnt(0)
	v_mfma_f32_16x16x32_bf16 v[118:121], v[130:133], v[172:175], v[118:121]
	v_mfma_f32_16x16x32_bf16 v[122:125], v[150:153], v[172:175], v[122:125]
	v_mfma_f32_16x16x32_bf16 v[102:105], v[130:133], v[180:183], v[102:105]
	v_mfma_f32_16x16x32_bf16 v[106:109], v[150:153], v[180:183], v[106:109]
	v_mfma_f32_16x16x32_bf16 v[86:89], v[130:133], v[188:191], v[86:89]
	v_mfma_f32_16x16x32_bf16 v[90:93], v[150:153], v[188:191], v[90:93]
	v_mfma_f32_16x16x32_bf16 v[70:73], v[130:133], v[196:199], v[70:73]
	v_mfma_f32_16x16x32_bf16 v[74:77], v[150:153], v[196:199], v[74:77]
	v_mfma_f32_16x16x32_bf16 v[118:121], v[134:137], v[176:179], v[118:121]
	v_mfma_f32_16x16x32_bf16 v[122:125], v[154:157], v[176:179], v[122:125]
	v_mfma_f32_16x16x32_bf16 v[102:105], v[134:137], v[184:187], v[102:105]
	v_mfma_f32_16x16x32_bf16 v[106:109], v[154:157], v[184:187], v[106:109]
	v_mfma_f32_16x16x32_bf16 v[86:89], v[134:137], v[192:195], v[86:89]
	v_mfma_f32_16x16x32_bf16 v[90:93], v[154:157], v[192:195], v[90:93]
	v_mfma_f32_16x16x32_bf16 v[70:73], v[134:137], v[200:203], v[70:73]
	v_mfma_f32_16x16x32_bf16 v[74:77], v[154:157], v[200:203], v[74:77]
	s_barrier
	s_add_i32 s56, 0, 0x14000
	s_add_i32 s53, s53, s27
	v_add_u32_e32 v161, s56, v159
	v_lshl_add_u64 v[168:169], s[20:21], 0, v[142:143]
	s_mov_b32 m0, s53
	ds_read_b128 v[204:207], v161
	ds_read_b128 v[208:211], v161 offset:1024
	ds_read_b128 v[212:215], v161 offset:2048
	ds_read_b128 v[216:219], v161 offset:3072
	global_load_lds_dwordx4 v[168:169], off
	v_lshl_add_u64 v[220:221], s[20:21], 0, v[138:139]
	s_add_i32 m0, s53, 0x2000
	s_nop 0
	global_load_lds_dwordx4 v[220:221], off
	s_barrier
	s_waitcnt lgkmcnt(0)
	v_mfma_f32_16x16x32_bf16 v[114:117], v[204:207], v[172:175], v[114:117]
	v_mfma_f32_16x16x32_bf16 v[126:129], v[212:215], v[172:175], v[126:129]
	v_mfma_f32_16x16x32_bf16 v[98:101], v[204:207], v[180:183], v[98:101]
	v_mfma_f32_16x16x32_bf16 v[110:113], v[212:215], v[180:183], v[110:113]
	v_mfma_f32_16x16x32_bf16 v[82:85], v[204:207], v[188:191], v[82:85]
	v_mfma_f32_16x16x32_bf16 v[94:97], v[212:215], v[188:191], v[94:97]
	v_mfma_f32_16x16x32_bf16 v[66:69], v[204:207], v[196:199], v[66:69]
	v_mfma_f32_16x16x32_bf16 v[78:81], v[212:215], v[196:199], v[78:81]
	v_mfma_f32_16x16x32_bf16 v[114:117], v[208:211], v[176:179], v[114:117]
	v_mfma_f32_16x16x32_bf16 v[126:129], v[216:219], v[176:179], v[126:129]
	v_mfma_f32_16x16x32_bf16 v[98:101], v[208:211], v[184:187], v[98:101]
	v_mfma_f32_16x16x32_bf16 v[110:113], v[216:219], v[184:187], v[110:113]
	v_mfma_f32_16x16x32_bf16 v[82:85], v[208:211], v[192:195], v[82:85]
	v_mfma_f32_16x16x32_bf16 v[94:97], v[216:219], v[192:195], v[94:97]
	v_mfma_f32_16x16x32_bf16 v[66:69], v[208:211], v[200:203], v[66:69]
	v_mfma_f32_16x16x32_bf16 v[78:81], v[216:219], v[200:203], v[78:81]
	s_barrier
	s_mov_b32 m0, s29
	v_lshl_add_u64 v[236:237], s[22:23], 0, v[144:145]
	ds_read_b128 v[172:175], v160 offset:16384
	ds_read_b128 v[176:179], v160 offset:17408
	ds_read_b128 v[180:183], v160 offset:18432
	ds_read_b128 v[184:187], v160 offset:19456
	ds_read_b128 v[188:191], v160 offset:20480
	ds_read_b128 v[192:195], v160 offset:21504
	ds_read_b128 v[196:199], v160 offset:22528
	ds_read_b128 v[200:203], v160 offset:23552
	global_load_lds_dwordx4 v[236:237], off
	v_lshl_add_u64 v[238:239], s[22:23], 0, v[140:141]
	s_mov_b32 m0, s30
	s_nop 0
	global_load_lds_dwordx4 v[238:239], off
	s_barrier
	s_waitcnt lgkmcnt(0)
	v_mfma_f32_16x16x32_bf16 v[54:57], v[130:133], v[172:175], v[54:57]
	v_mfma_f32_16x16x32_bf16 v[58:61], v[150:153], v[172:175], v[58:61]
	v_mfma_f32_16x16x32_bf16 v[38:41], v[130:133], v[180:183], v[38:41]
	v_mfma_f32_16x16x32_bf16 v[42:45], v[150:153], v[180:183], v[42:45]
	v_mfma_f32_16x16x32_bf16 v[22:25], v[130:133], v[188:191], v[22:25]
	v_mfma_f32_16x16x32_bf16 v[26:29], v[150:153], v[188:191], v[26:29]
	v_mfma_f32_16x16x32_bf16 v[10:13], v[130:133], v[196:199], v[10:13]
	v_mfma_f32_16x16x32_bf16 v[14:17], v[150:153], v[196:199], v[14:17]
	v_mfma_f32_16x16x32_bf16 v[54:57], v[134:137], v[176:179], v[54:57]
	v_mfma_f32_16x16x32_bf16 v[58:61], v[154:157], v[176:179], v[58:61]
	v_mfma_f32_16x16x32_bf16 v[38:41], v[134:137], v[184:187], v[38:41]
	v_mfma_f32_16x16x32_bf16 v[42:45], v[154:157], v[184:187], v[42:45]
	v_mfma_f32_16x16x32_bf16 v[22:25], v[134:137], v[192:195], v[22:25]
	v_mfma_f32_16x16x32_bf16 v[26:29], v[154:157], v[192:195], v[26:29]
	v_mfma_f32_16x16x32_bf16 v[10:13], v[134:137], v[200:203], v[10:13]
	v_mfma_f32_16x16x32_bf16 v[14:17], v[154:157], v[200:203], v[14:17]
	s_barrier
	s_add_u32 s54, s20, 0x40000
	s_addc_u32 s55, s21, 0
	s_add_i32 s53, s56, s27
	v_lshl_add_u64 v[130:131], s[54:55], 0, v[142:143]
	s_mov_b32 m0, s53
	s_nop 0
	global_load_lds_dwordx4 v[130:131], off
	v_lshl_add_u64 v[130:131], s[54:55], 0, v[138:139]
	s_add_i32 m0, s53, 0x2000
	s_nop 0
	global_load_lds_dwordx4 v[130:131], off
	s_waitcnt vmcnt(6)
	s_barrier
	v_mfma_f32_16x16x32_bf16 v[50:53], v[204:207], v[172:175], v[50:53]
	v_mfma_f32_16x16x32_bf16 v[62:65], v[212:215], v[172:175], v[62:65]
	v_mfma_f32_16x16x32_bf16 v[34:37], v[204:207], v[180:183], v[34:37]
	v_mfma_f32_16x16x32_bf16 v[46:49], v[212:215], v[180:183], v[46:49]
	v_mfma_f32_16x16x32_bf16 v[18:21], v[204:207], v[188:191], v[18:21]
	v_mfma_f32_16x16x32_bf16 v[30:33], v[212:215], v[188:191], v[30:33]
	v_mfma_f32_16x16x32_bf16 v[2:5], v[204:207], v[196:199], v[2:5]
	v_mfma_f32_16x16x32_bf16 v[6:9], v[212:215], v[196:199], v[6:9]
	v_mfma_f32_16x16x32_bf16 v[50:53], v[208:211], v[176:179], v[50:53]
	v_mfma_f32_16x16x32_bf16 v[62:65], v[216:219], v[176:179], v[62:65]
	v_mfma_f32_16x16x32_bf16 v[34:37], v[208:211], v[184:187], v[34:37]
	v_mfma_f32_16x16x32_bf16 v[46:49], v[216:219], v[184:187], v[46:49]
	v_mfma_f32_16x16x32_bf16 v[18:21], v[208:211], v[192:195], v[18:21]
	v_mfma_f32_16x16x32_bf16 v[30:33], v[216:219], v[192:195], v[30:33]
	v_mfma_f32_16x16x32_bf16 v[2:5], v[208:211], v[200:203], v[2:5]
	v_mfma_f32_16x16x32_bf16 v[6:9], v[216:219], v[200:203], v[6:9]
	s_barrier
	s_add_i32 s53, 0, 0x18000
	v_add_u32_e32 v154, s53, v159
	ds_read_b128 v[130:133], v154
	ds_read_b128 v[134:137], v154 offset:1024
	ds_read_b128 v[150:153], v154 offset:2048
	ds_read_b128 v[154:157], v154 offset:3072
	s_add_u32 s22, s22, 0x40000
	s_addc_u32 s23, s23, 0
	s_mov_b32 m0, s31
	v_lshl_add_u64 v[204:205], s[22:23], 0, v[144:145]
	ds_read_b128 v[172:175], v160 offset:32768
	ds_read_b128 v[176:179], v160 offset:33792
	ds_read_b128 v[180:183], v160 offset:34816
	ds_read_b128 v[184:187], v160 offset:35840
	ds_read_b128 v[188:191], v160 offset:36864
	ds_read_b128 v[192:195], v160 offset:37888
	ds_read_b128 v[196:199], v160 offset:38912
	ds_read_b128 v[200:203], v160 offset:39936
	global_load_lds_dwordx4 v[204:205], off
	v_lshl_add_u64 v[204:205], s[22:23], 0, v[140:141]
	s_mov_b32 m0, s34
	s_nop 0
	global_load_lds_dwordx4 v[204:205], off
	s_waitcnt lgkmcnt(8)
	s_barrier
	s_waitcnt lgkmcnt(0)
	v_mfma_f32_16x16x32_bf16 v[118:121], v[130:133], v[172:175], v[118:121]
	v_mfma_f32_16x16x32_bf16 v[122:125], v[150:153], v[172:175], v[122:125]
	v_mfma_f32_16x16x32_bf16 v[102:105], v[130:133], v[180:183], v[102:105]
	v_mfma_f32_16x16x32_bf16 v[106:109], v[150:153], v[180:183], v[106:109]
	v_mfma_f32_16x16x32_bf16 v[86:89], v[130:133], v[188:191], v[86:89]
	v_mfma_f32_16x16x32_bf16 v[90:93], v[150:153], v[188:191], v[90:93]
	v_mfma_f32_16x16x32_bf16 v[70:73], v[130:133], v[196:199], v[70:73]
	v_mfma_f32_16x16x32_bf16 v[74:77], v[150:153], v[196:199], v[74:77]
	v_mfma_f32_16x16x32_bf16 v[118:121], v[134:137], v[176:179], v[118:121]
	v_mfma_f32_16x16x32_bf16 v[122:125], v[154:157], v[176:179], v[122:125]
	v_mfma_f32_16x16x32_bf16 v[102:105], v[134:137], v[184:187], v[102:105]
	v_mfma_f32_16x16x32_bf16 v[106:109], v[154:157], v[184:187], v[106:109]
	v_mfma_f32_16x16x32_bf16 v[86:89], v[134:137], v[192:195], v[86:89]
	v_mfma_f32_16x16x32_bf16 v[90:93], v[154:157], v[192:195], v[90:93]
	v_mfma_f32_16x16x32_bf16 v[70:73], v[134:137], v[200:203], v[70:73]
	v_mfma_f32_16x16x32_bf16 v[74:77], v[154:157], v[200:203], v[74:77]
	s_barrier
	s_add_i32 s22, 0, 0x1c000
	s_add_i32 s23, s53, s27
	v_add_u32_e32 v161, s22, v159
	v_lshl_add_u64 v[168:169], v[168:169], 0, s[84:85]
	s_mov_b32 m0, s23
	ds_read_b128 v[204:207], v161
	ds_read_b128 v[208:211], v161 offset:1024
	ds_read_b128 v[212:215], v161 offset:2048
	ds_read_b128 v[216:219], v161 offset:3072
	global_load_lds_dwordx4 v[168:169], off
	v_lshl_add_u64 v[168:169], v[220:221], 0, s[84:85]
	s_add_i32 m0, s23, 0x2000
	s_nop 0
	global_load_lds_dwordx4 v[168:169], off
	s_barrier
	s_waitcnt lgkmcnt(0)
	v_mfma_f32_16x16x32_bf16 v[114:117], v[204:207], v[172:175], v[114:117]
	v_mfma_f32_16x16x32_bf16 v[126:129], v[212:215], v[172:175], v[126:129]
	v_mfma_f32_16x16x32_bf16 v[98:101], v[204:207], v[180:183], v[98:101]
	v_mfma_f32_16x16x32_bf16 v[110:113], v[212:215], v[180:183], v[110:113]
	v_mfma_f32_16x16x32_bf16 v[82:85], v[204:207], v[188:191], v[82:85]
	v_mfma_f32_16x16x32_bf16 v[94:97], v[212:215], v[188:191], v[94:97]
	v_mfma_f32_16x16x32_bf16 v[66:69], v[204:207], v[196:199], v[66:69]
	v_mfma_f32_16x16x32_bf16 v[78:81], v[212:215], v[196:199], v[78:81]
	v_mfma_f32_16x16x32_bf16 v[114:117], v[208:211], v[176:179], v[114:117]
	v_mfma_f32_16x16x32_bf16 v[126:129], v[216:219], v[176:179], v[126:129]
	v_mfma_f32_16x16x32_bf16 v[98:101], v[208:211], v[184:187], v[98:101]
	v_mfma_f32_16x16x32_bf16 v[110:113], v[216:219], v[184:187], v[110:113]
	v_mfma_f32_16x16x32_bf16 v[82:85], v[208:211], v[192:195], v[82:85]
	v_mfma_f32_16x16x32_bf16 v[94:97], v[216:219], v[192:195], v[94:97]
	v_mfma_f32_16x16x32_bf16 v[66:69], v[208:211], v[200:203], v[66:69]
	v_mfma_f32_16x16x32_bf16 v[78:81], v[216:219], v[200:203], v[78:81]
	s_barrier
	s_mov_b32 m0, s42
	v_lshl_add_u64 v[168:169], v[236:237], 0, s[84:85]
	ds_read_b128 v[172:175], v160 offset:49152
	ds_read_b128 v[176:179], v160 offset:50176
	ds_read_b128 v[180:183], v160 offset:51200
	ds_read_b128 v[184:187], v160 offset:52224
	ds_read_b128 v[188:191], v160 offset:53248
	ds_read_b128 v[192:195], v160 offset:54272
	ds_read_b128 v[196:199], v160 offset:55296
	ds_read_b128 v[200:203], v160 offset:56320
	global_load_lds_dwordx4 v[168:169], off
	v_lshl_add_u64 v[168:169], v[238:239], 0, s[84:85]
	s_mov_b32 m0, s43
	s_nop 0
	global_load_lds_dwordx4 v[168:169], off
	s_barrier
	s_waitcnt lgkmcnt(0)
	v_mfma_f32_16x16x32_bf16 v[54:57], v[130:133], v[172:175], v[54:57]
	v_mfma_f32_16x16x32_bf16 v[58:61], v[150:153], v[172:175], v[58:61]
	v_mfma_f32_16x16x32_bf16 v[38:41], v[130:133], v[180:183], v[38:41]
	v_mfma_f32_16x16x32_bf16 v[42:45], v[150:153], v[180:183], v[42:45]
	v_mfma_f32_16x16x32_bf16 v[22:25], v[130:133], v[188:191], v[22:25]
	v_mfma_f32_16x16x32_bf16 v[26:29], v[150:153], v[188:191], v[26:29]
	v_mfma_f32_16x16x32_bf16 v[10:13], v[130:133], v[196:199], v[10:13]
	v_mfma_f32_16x16x32_bf16 v[14:17], v[150:153], v[196:199], v[14:17]
	v_mfma_f32_16x16x32_bf16 v[54:57], v[134:137], v[176:179], v[54:57]
	v_mfma_f32_16x16x32_bf16 v[58:61], v[154:157], v[176:179], v[58:61]
	v_mfma_f32_16x16x32_bf16 v[38:41], v[134:137], v[184:187], v[38:41]
	v_mfma_f32_16x16x32_bf16 v[42:45], v[154:157], v[184:187], v[42:45]
	v_mfma_f32_16x16x32_bf16 v[22:25], v[134:137], v[192:195], v[22:25]
	v_mfma_f32_16x16x32_bf16 v[26:29], v[154:157], v[192:195], v[26:29]
	v_mfma_f32_16x16x32_bf16 v[10:13], v[134:137], v[200:203], v[10:13]
	v_mfma_f32_16x16x32_bf16 v[14:17], v[154:157], v[200:203], v[14:17]
	s_barrier
	s_add_u32 s20, s20, 0x40080
	s_addc_u32 s21, s21, 0
	s_add_i32 s22, s22, s27
	v_lshl_add_u64 v[130:131], s[20:21], 0, v[142:143]
	s_mov_b32 m0, s22
	s_nop 0
	global_load_lds_dwordx4 v[130:131], off
	v_lshl_add_u64 v[130:131], s[20:21], 0, v[138:139]
	s_add_i32 m0, s22, 0x2000
	s_nop 0
	global_load_lds_dwordx4 v[130:131], off
	s_waitcnt vmcnt(6)
	s_barrier
	v_mfma_f32_16x16x32_bf16 v[50:53], v[204:207], v[172:175], v[50:53]
	v_mfma_f32_16x16x32_bf16 v[62:65], v[212:215], v[172:175], v[62:65]
	v_mfma_f32_16x16x32_bf16 v[34:37], v[204:207], v[180:183], v[34:37]
	v_mfma_f32_16x16x32_bf16 v[46:49], v[212:215], v[180:183], v[46:49]
	v_mfma_f32_16x16x32_bf16 v[18:21], v[204:207], v[188:191], v[18:21]
	v_mfma_f32_16x16x32_bf16 v[30:33], v[212:215], v[188:191], v[30:33]
	v_mfma_f32_16x16x32_bf16 v[2:5], v[204:207], v[196:199], v[2:5]
	v_mfma_f32_16x16x32_bf16 v[6:9], v[212:215], v[196:199], v[6:9]
	v_mfma_f32_16x16x32_bf16 v[50:53], v[208:211], v[176:179], v[50:53]
	v_mfma_f32_16x16x32_bf16 v[62:65], v[216:219], v[176:179], v[62:65]
	v_mfma_f32_16x16x32_bf16 v[34:37], v[208:211], v[184:187], v[34:37]
	v_mfma_f32_16x16x32_bf16 v[46:49], v[216:219], v[184:187], v[46:49]
	v_mfma_f32_16x16x32_bf16 v[18:21], v[208:211], v[192:195], v[18:21]
	v_mfma_f32_16x16x32_bf16 v[30:33], v[216:219], v[192:195], v[30:33]
	v_mfma_f32_16x16x32_bf16 v[2:5], v[208:211], v[200:203], v[2:5]
	v_mfma_f32_16x16x32_bf16 v[6:9], v[216:219], v[200:203], v[6:9]
	s_barrier
	s_add_u32 s18, s18, 0x100
	s_addc_u32 s19, s19, 0
	s_add_u32 s50, s50, 0x100
	s_addc_u32 s51, s51, 0
	s_cmp_ge_i32 s52, s39
	s_mov_b32 s20, s52
	s_cbranch_scc0 .LBB0_454

.LBB0_473:
	s_add_i32 s31, s10, 2
	s_add_u32 s6, s8, 0x100
	s_addc_u32 s7, s9, 0
	s_cmp_lg_u32 s30, s10
	s_cselect_b32 s10, s6, 0
	s_cselect_b32 s11, s7, 0
	s_add_u32 s12, s4, s10
	s_addc_u32 s13, s5, s11
	s_add_i32 s34, 0, 0x10000
	v_add_u32_e32 v106, s34, v92
	ds_read_b128 v[94:97], v106
	ds_read_b128 v[98:101], v106 offset:1024
	ds_read_b128 v[102:105], v106 offset:2048
	ds_read_b128 v[106:109], v106 offset:3072
	s_add_u32 s10, s2, s10
	s_addc_u32 s11, s3, s11
	v_lshl_add_u64 v[142:143], v[74:75], 0, s[8:9]
	s_add_i32 m0, s19, 0xc000
	ds_read_b128 v[110:113], v93
	ds_read_b128 v[114:117], v93 offset:1024
	ds_read_b128 v[118:121], v93 offset:2048
	ds_read_b128 v[122:125], v93 offset:3072
	ds_read_b128 v[126:129], v93 offset:4096
	ds_read_b128 v[130:133], v93 offset:5120
	ds_read_b128 v[134:137], v93 offset:6144
	ds_read_b128 v[138:141], v93 offset:7168
	global_load_lds_dwordx4 v[142:143], off
	v_lshl_add_u64 v[142:143], v[76:77], 0, s[8:9]
	s_add_i32 m0, s19, 0xe000
	s_nop 0
	global_load_lds_dwordx4 v[142:143], off
	s_waitcnt lgkmcnt(8)
	s_barrier
	s_waitcnt lgkmcnt(0)
	v_mfma_f32_16x16x32_bf16 v[70:73], v[94:97], v[110:113], v[70:73]
	v_mfma_f32_16x16x32_bf16 v[66:69], v[102:105], v[110:113], v[66:69]
	v_mfma_f32_16x16x32_bf16 v[62:65], v[94:97], v[118:121], v[62:65]
	v_mfma_f32_16x16x32_bf16 v[58:61], v[102:105], v[118:121], v[58:61]
	v_mfma_f32_16x16x32_bf16 v[54:57], v[94:97], v[126:129], v[54:57]
	v_mfma_f32_16x16x32_bf16 v[50:53], v[102:105], v[126:129], v[50:53]
	v_mfma_f32_16x16x32_bf16 v[46:49], v[94:97], v[134:137], v[46:49]
	v_mfma_f32_16x16x32_bf16 v[42:45], v[102:105], v[134:137], v[42:45]
	v_mfma_f32_16x16x32_bf16 v[70:73], v[98:101], v[114:117], v[70:73]
	v_mfma_f32_16x16x32_bf16 v[66:69], v[106:109], v[114:117], v[66:69]
	v_mfma_f32_16x16x32_bf16 v[62:65], v[98:101], v[122:125], v[62:65]
	v_mfma_f32_16x16x32_bf16 v[58:61], v[106:109], v[122:125], v[58:61]
	v_mfma_f32_16x16x32_bf16 v[54:57], v[98:101], v[130:133], v[54:57]
	v_mfma_f32_16x16x32_bf16 v[50:53], v[106:109], v[130:133], v[50:53]
	v_mfma_f32_16x16x32_bf16 v[46:49], v[98:101], v[138:141], v[46:49]
	v_mfma_f32_16x16x32_bf16 v[42:45], v[106:109], v[138:141], v[42:45]
	s_barrier
	s_add_i32 s8, s34, s18
	v_lshl_add_u64 v[142:143], s[10:11], 0, v[16:17]
	s_mov_b32 m0, s8
	v_lshl_add_u64 v[144:145], s[10:11], 0, v[24:25]
	global_load_lds_dwordx4 v[142:143], off
	s_add_i32 m0, s8, 0x2000
	s_nop 0
	global_load_lds_dwordx4 v[144:145], off
	s_barrier
	s_waitcnt lgkmcnt(0)
	s_mov_b32 m0, s19
	v_lshl_add_u64 v[146:147], s[12:13], 0, v[14:15]
	s_barrier
	ds_read_b128 v[110:113], v93 offset:16384
	ds_read_b128 v[114:117], v93 offset:17408
	ds_read_b128 v[118:121], v93 offset:18432
	ds_read_b128 v[122:125], v93 offset:19456
	ds_read_b128 v[126:129], v93 offset:20480
	ds_read_b128 v[130:133], v93 offset:21504
	ds_read_b128 v[134:137], v93 offset:22528
	ds_read_b128 v[138:141], v93 offset:23552
	global_load_lds_dwordx4 v[146:147], off
	v_lshl_add_u64 v[148:149], s[12:13], 0, v[22:23]
	s_mov_b32 m0, s20
	s_nop 0
	global_load_lds_dwordx4 v[148:149], off
	s_barrier
	s_waitcnt lgkmcnt(0)
	v_mfma_f32_16x16x32_bf16 v[38:41], v[94:97], v[110:113], v[38:41]
	v_mfma_f32_16x16x32_bf16 v[34:37], v[102:105], v[110:113], v[34:37]
	v_mfma_f32_16x16x32_bf16 v[30:33], v[94:97], v[118:121], v[30:33]
	v_mfma_f32_16x16x32_bf16 v[26:29], v[102:105], v[118:121], v[26:29]
	v_mfma_f32_16x16x32_bf16 v[18:21], v[94:97], v[126:129], v[18:21]
	v_mfma_f32_16x16x32_bf16 v[10:13], v[102:105], v[126:129], v[10:13]
	v_mfma_f32_16x16x32_bf16 v[6:9], v[94:97], v[134:137], v[6:9]
	v_mfma_f32_16x16x32_bf16 v[2:5], v[102:105], v[134:137], v[2:5]
	v_mfma_f32_16x16x32_bf16 v[38:41], v[98:101], v[114:117], v[38:41]
	v_mfma_f32_16x16x32_bf16 v[34:37], v[106:109], v[114:117], v[34:37]
	v_mfma_f32_16x16x32_bf16 v[30:33], v[98:101], v[122:125], v[30:33]
	v_mfma_f32_16x16x32_bf16 v[26:29], v[106:109], v[122:125], v[26:29]
	v_mfma_f32_16x16x32_bf16 v[18:21], v[98:101], v[130:133], v[18:21]
	v_mfma_f32_16x16x32_bf16 v[10:13], v[106:109], v[130:133], v[10:13]
	v_mfma_f32_16x16x32_bf16 v[6:9], v[98:101], v[138:141], v[6:9]
	v_mfma_f32_16x16x32_bf16 v[2:5], v[106:109], v[138:141], v[2:5]
	s_barrier
	s_add_u32 s8, s10, 0x80000
	s_addc_u32 s9, s11, 0
	s_mov_b32 m0, s21
	v_lshl_add_u64 v[94:95], s[8:9], 0, v[16:17]
	global_load_lds_dwordx4 v[94:95], off
	v_lshl_add_u64 v[94:95], s[8:9], 0, v[24:25]
	s_mov_b32 m0, s22
	s_nop 0
	global_load_lds_dwordx4 v[94:95], off
	s_waitcnt vmcnt(6)
	s_barrier
	s_add_i32 s34, 0, 0x18000
	v_add_u32_e32 v106, s34, v92
	s_barrier
	ds_read_b128 v[94:97], v106
	ds_read_b128 v[98:101], v106 offset:1024
	ds_read_b128 v[102:105], v106 offset:2048
	ds_read_b128 v[106:109], v106 offset:3072
	s_add_u32 s8, s12, 0x40000
	s_addc_u32 s9, s13, 0
	s_mov_b32 m0, s23
	v_lshl_add_u64 v[150:151], s[8:9], 0, v[14:15]
	ds_read_b128 v[110:113], v93 offset:32768
	ds_read_b128 v[114:117], v93 offset:33792
	ds_read_b128 v[118:121], v93 offset:34816
	ds_read_b128 v[122:125], v93 offset:35840
	ds_read_b128 v[126:129], v93 offset:36864
	ds_read_b128 v[130:133], v93 offset:37888
	ds_read_b128 v[134:137], v93 offset:38912
	ds_read_b128 v[138:141], v93 offset:39936
	global_load_lds_dwordx4 v[150:151], off
	v_lshl_add_u64 v[150:151], s[8:9], 0, v[22:23]
	s_mov_b32 m0, s24
	s_nop 0
	global_load_lds_dwordx4 v[150:151], off
	s_waitcnt lgkmcnt(8)
	s_barrier
	s_waitcnt lgkmcnt(0)
	v_mfma_f32_16x16x32_bf16 v[70:73], v[94:97], v[110:113], v[70:73]
	v_mfma_f32_16x16x32_bf16 v[66:69], v[102:105], v[110:113], v[66:69]
	v_mfma_f32_16x16x32_bf16 v[62:65], v[94:97], v[118:121], v[62:65]
	v_mfma_f32_16x16x32_bf16 v[58:61], v[102:105], v[118:121], v[58:61]
	v_mfma_f32_16x16x32_bf16 v[54:57], v[94:97], v[126:129], v[54:57]
	v_mfma_f32_16x16x32_bf16 v[50:53], v[102:105], v[126:129], v[50:53]
	v_mfma_f32_16x16x32_bf16 v[46:49], v[94:97], v[134:137], v[46:49]
	v_mfma_f32_16x16x32_bf16 v[42:45], v[102:105], v[134:137], v[42:45]
	v_mfma_f32_16x16x32_bf16 v[70:73], v[98:101], v[114:117], v[70:73]
	v_mfma_f32_16x16x32_bf16 v[66:69], v[106:109], v[114:117], v[66:69]
	v_mfma_f32_16x16x32_bf16 v[62:65], v[98:101], v[122:125], v[62:65]
	v_mfma_f32_16x16x32_bf16 v[58:61], v[106:109], v[122:125], v[58:61]
	v_mfma_f32_16x16x32_bf16 v[54:57], v[98:101], v[130:133], v[54:57]
	v_mfma_f32_16x16x32_bf16 v[50:53], v[106:109], v[130:133], v[50:53]
	v_mfma_f32_16x16x32_bf16 v[46:49], v[98:101], v[138:141], v[46:49]
	v_mfma_f32_16x16x32_bf16 v[42:45], v[106:109], v[138:141], v[42:45]
	s_barrier
	s_add_i32 s8, s34, s18
	v_lshl_add_u64 v[110:111], v[142:143], 0, s[84:85]
	s_mov_b32 m0, s8
	s_nop 0
	global_load_lds_dwordx4 v[110:111], off
	v_lshl_add_u64 v[110:111], v[144:145], 0, s[84:85]
	s_add_i32 m0, s8, 0x2000
	s_nop 0
	global_load_lds_dwordx4 v[110:111], off
	s_barrier
	s_waitcnt lgkmcnt(0)
	s_mov_b32 m0, s25
	v_lshl_add_u64 v[142:143], v[146:147], 0, s[84:85]
	s_barrier
	ds_read_b128 v[110:113], v93 offset:49152
	ds_read_b128 v[114:117], v93 offset:50176
	ds_read_b128 v[118:121], v93 offset:51200
	ds_read_b128 v[122:125], v93 offset:52224
	ds_read_b128 v[126:129], v93 offset:53248
	ds_read_b128 v[130:133], v93 offset:54272
	ds_read_b128 v[134:137], v93 offset:55296
	ds_read_b128 v[138:141], v93 offset:56320
	global_load_lds_dwordx4 v[142:143], off
	v_lshl_add_u64 v[142:143], v[148:149], 0, s[84:85]
	s_mov_b32 m0, s26
	s_nop 0
	global_load_lds_dwordx4 v[142:143], off
	s_barrier
	s_waitcnt lgkmcnt(0)
	v_mfma_f32_16x16x32_bf16 v[38:41], v[94:97], v[110:113], v[38:41]
	v_mfma_f32_16x16x32_bf16 v[34:37], v[102:105], v[110:113], v[34:37]
	v_mfma_f32_16x16x32_bf16 v[30:33], v[94:97], v[118:121], v[30:33]
	v_mfma_f32_16x16x32_bf16 v[26:29], v[102:105], v[118:121], v[26:29]
	v_mfma_f32_16x16x32_bf16 v[18:21], v[94:97], v[126:129], v[18:21]
	v_mfma_f32_16x16x32_bf16 v[10:13], v[102:105], v[126:129], v[10:13]
	v_mfma_f32_16x16x32_bf16 v[6:9], v[94:97], v[134:137], v[6:9]
	v_mfma_f32_16x16x32_bf16 v[2:5], v[102:105], v[134:137], v[2:5]
	v_mfma_f32_16x16x32_bf16 v[38:41], v[98:101], v[114:117], v[38:41]
	v_mfma_f32_16x16x32_bf16 v[34:37], v[106:109], v[114:117], v[34:37]
	v_mfma_f32_16x16x32_bf16 v[30:33], v[98:101], v[122:125], v[30:33]
	v_mfma_f32_16x16x32_bf16 v[26:29], v[106:109], v[122:125], v[26:29]
	v_mfma_f32_16x16x32_bf16 v[18:21], v[98:101], v[130:133], v[18:21]
	v_mfma_f32_16x16x32_bf16 v[10:13], v[106:109], v[130:133], v[10:13]
	v_mfma_f32_16x16x32_bf16 v[6:9], v[98:101], v[138:141], v[6:9]
	v_mfma_f32_16x16x32_bf16 v[2:5], v[106:109], v[138:141], v[2:5]
	s_barrier
	s_add_u32 s8, s10, 0x80080
	s_addc_u32 s9, s11, 0
	s_mov_b32 m0, s27
	v_lshl_add_u64 v[94:95], s[8:9], 0, v[16:17]
	global_load_lds_dwordx4 v[94:95], off
	v_lshl_add_u64 v[94:95], s[8:9], 0, v[24:25]
	s_mov_b32 m0, s28
	s_nop 0
	global_load_lds_dwordx4 v[94:95], off
	s_waitcnt vmcnt(6)
	s_barrier
	s_cmp_ge_i32 s31, s29
	s_mov_b64 s[8:9], s[6:7]
	s_mov_b32 s10, s31
	s_barrier
	s_cbranch_scc0 .LBB0_473

.LBB0_500:
	s_add_i32 s47, s10, 2
	s_add_u32 s11, s8, 0x4000
	s_addc_u32 s12, s9, 0
	s_cmp_eq_u32 s35, s10
	s_cselect_b32 s14, s0, s11
	s_cselect_b32 s15, s1, s12
	s_cselect_b32 s10, s2, s45
	s_cselect_b32 s11, s3, s46
	s_add_u32 s12, s14, 0x8000
	s_addc_u32 s13, s15, 0
	s_add_i32 s48, 0, 0x10000
	v_add_u32_e32 v122, s48, v206
	ds_read_b128 v[98:101], v122
	ds_read_b128 v[106:109], v122 offset:1024
	ds_read_b128 v[114:117], v122 offset:2048
	ds_read_b128 v[122:125], v122 offset:3072
	v_lshl_add_u64 v[168:169], s[8:9], 0, v[158:159]
	s_add_i32 m0, s20, 0xc000
	ds_read_b128 v[146:149], v207
	ds_read_b128 v[150:153], v207 offset:1024
	ds_read_b128 v[154:157], v207 offset:2048
	ds_read_b128 v[176:179], v207 offset:3072
	ds_read_b128 v[180:183], v207 offset:4096
	ds_read_b128 v[184:187], v207 offset:5120
	ds_read_b128 v[188:191], v207 offset:6144
	ds_read_b128 v[192:195], v207 offset:7168
	global_load_lds_dwordx4 v[168:169], off
	v_lshl_add_u64 v[168:169], s[8:9], 0, v[172:173]
	s_add_i32 m0, s20, 0xe000
	s_nop 0
	global_load_lds_dwordx4 v[168:169], off
	s_waitcnt lgkmcnt(8)
	s_barrier
	s_waitcnt lgkmcnt(0)
	v_mfma_f32_16x16x32_bf16 v[142:145], v[98:101], v[146:149], v[142:145]
	v_mfma_f32_16x16x32_bf16 v[138:141], v[114:117], v[146:149], v[138:141]
	v_mfma_f32_16x16x32_bf16 v[126:129], v[98:101], v[154:157], v[126:129]
	v_mfma_f32_16x16x32_bf16 v[118:121], v[114:117], v[154:157], v[118:121]
	v_mfma_f32_16x16x32_bf16 v[94:97], v[98:101], v[180:183], v[94:97]
	v_mfma_f32_16x16x32_bf16 v[90:93], v[114:117], v[180:183], v[90:93]
	v_mfma_f32_16x16x32_bf16 v[78:81], v[98:101], v[188:191], v[78:81]
	v_mfma_f32_16x16x32_bf16 v[74:77], v[114:117], v[188:191], v[74:77]
	v_mfma_f32_16x16x32_bf16 v[142:145], v[106:109], v[150:153], v[142:145]
	v_mfma_f32_16x16x32_bf16 v[138:141], v[122:125], v[150:153], v[138:141]
	v_mfma_f32_16x16x32_bf16 v[126:129], v[106:109], v[176:179], v[126:129]
	v_mfma_f32_16x16x32_bf16 v[118:121], v[122:125], v[176:179], v[118:121]
	v_mfma_f32_16x16x32_bf16 v[94:97], v[106:109], v[184:187], v[94:97]
	v_mfma_f32_16x16x32_bf16 v[90:93], v[122:125], v[184:187], v[90:93]
	v_mfma_f32_16x16x32_bf16 v[78:81], v[106:109], v[192:195], v[78:81]
	v_mfma_f32_16x16x32_bf16 v[74:77], v[122:125], v[192:195], v[74:77]
	s_barrier
	s_add_i32 s50, 0, 0x14000
	v_add_u32_e32 v168, s50, v206
	s_add_i32 s48, s48, s19
	ds_read_b128 v[196:199], v168
	ds_read_b128 v[200:203], v168 offset:1024
	ds_read_b128 v[208:211], v168 offset:2048
	ds_read_b128 v[212:215], v168 offset:3072
	v_lshl_add_u64 v[168:169], s[10:11], 0, v[160:161]
	s_mov_b32 m0, s48
	v_lshl_add_u64 v[204:205], s[10:11], 0, v[174:175]
	global_load_lds_dwordx4 v[168:169], off
	s_add_i32 m0, s48, 0x2000
	s_nop 0
	global_load_lds_dwordx4 v[204:205], off
	s_barrier
	s_waitcnt lgkmcnt(0)
	v_mfma_f32_16x16x32_bf16 v[134:137], v[196:199], v[146:149], v[134:137]
	v_mfma_f32_16x16x32_bf16 v[130:133], v[208:211], v[146:149], v[130:133]
	v_mfma_f32_16x16x32_bf16 v[110:113], v[196:199], v[154:157], v[110:113]
	v_mfma_f32_16x16x32_bf16 v[102:105], v[208:211], v[154:157], v[102:105]
	v_mfma_f32_16x16x32_bf16 v[86:89], v[196:199], v[180:183], v[86:89]
	v_mfma_f32_16x16x32_bf16 v[82:85], v[208:211], v[180:183], v[82:85]
	v_mfma_f32_16x16x32_bf16 v[70:73], v[196:199], v[188:191], v[70:73]
	v_mfma_f32_16x16x32_bf16 v[66:69], v[208:211], v[188:191], v[66:69]
	v_mfma_f32_16x16x32_bf16 v[134:137], v[200:203], v[150:153], v[134:137]
	v_mfma_f32_16x16x32_bf16 v[130:133], v[212:215], v[150:153], v[130:133]
	v_mfma_f32_16x16x32_bf16 v[110:113], v[200:203], v[176:179], v[110:113]
	v_mfma_f32_16x16x32_bf16 v[102:105], v[212:215], v[176:179], v[102:105]
	v_mfma_f32_16x16x32_bf16 v[86:89], v[200:203], v[184:187], v[86:89]
	v_mfma_f32_16x16x32_bf16 v[82:85], v[212:215], v[184:187], v[82:85]
	v_mfma_f32_16x16x32_bf16 v[70:73], v[200:203], v[192:195], v[70:73]
	v_mfma_f32_16x16x32_bf16 v[66:69], v[212:215], v[192:195], v[66:69]
	s_barrier
	s_mov_b32 m0, s20
	v_lshl_add_u64 v[216:217], s[14:15], 0, v[158:159]
	ds_read_b128 v[146:149], v207 offset:16384
	ds_read_b128 v[150:153], v207 offset:17408
	ds_read_b128 v[154:157], v207 offset:18432
	ds_read_b128 v[176:179], v207 offset:19456
	ds_read_b128 v[180:183], v207 offset:20480
	ds_read_b128 v[184:187], v207 offset:21504
	ds_read_b128 v[188:191], v207 offset:22528
	ds_read_b128 v[192:195], v207 offset:23552
	global_load_lds_dwordx4 v[216:217], off
	v_lshl_add_u64 v[216:217], s[14:15], 0, v[172:173]
	s_mov_b32 m0, s21
	s_nop 0
	global_load_lds_dwordx4 v[216:217], off
	s_barrier
	s_waitcnt lgkmcnt(0)
	v_mfma_f32_16x16x32_bf16 v[62:65], v[98:101], v[146:149], v[62:65]
	v_mfma_f32_16x16x32_bf16 v[58:61], v[114:117], v[146:149], v[58:61]
	v_mfma_f32_16x16x32_bf16 v[46:49], v[98:101], v[154:157], v[46:49]
	v_mfma_f32_16x16x32_bf16 v[42:45], v[114:117], v[154:157], v[42:45]
	v_mfma_f32_16x16x32_bf16 v[30:33], v[98:101], v[180:183], v[30:33]
	v_mfma_f32_16x16x32_bf16 v[26:29], v[114:117], v[180:183], v[26:29]
	v_mfma_f32_16x16x32_bf16 v[14:17], v[98:101], v[188:191], v[14:17]
	v_mfma_f32_16x16x32_bf16 v[10:13], v[114:117], v[188:191], v[10:13]
	v_mfma_f32_16x16x32_bf16 v[62:65], v[106:109], v[150:153], v[62:65]
	v_mfma_f32_16x16x32_bf16 v[58:61], v[122:125], v[150:153], v[58:61]
	v_mfma_f32_16x16x32_bf16 v[46:49], v[106:109], v[176:179], v[46:49]
	v_mfma_f32_16x16x32_bf16 v[42:45], v[122:125], v[176:179], v[42:45]
	v_mfma_f32_16x16x32_bf16 v[30:33], v[106:109], v[184:187], v[30:33]
	v_mfma_f32_16x16x32_bf16 v[26:29], v[122:125], v[184:187], v[26:29]
	v_mfma_f32_16x16x32_bf16 v[14:17], v[106:109], v[192:195], v[14:17]
	v_mfma_f32_16x16x32_bf16 v[10:13], v[122:125], v[192:195], v[10:13]
	s_barrier
	s_add_u32 s48, s10, 0xb0000
	s_addc_u32 s49, s11, 0
	s_add_i32 s50, s50, s19
	v_lshl_add_u64 v[98:99], s[48:49], 0, v[160:161]
	s_mov_b32 m0, s50
	s_nop 0
	global_load_lds_dwordx4 v[98:99], off
	v_lshl_add_u64 v[98:99], s[48:49], 0, v[174:175]
	s_add_i32 m0, s50, 0x2000
	s_nop 0
	global_load_lds_dwordx4 v[98:99], off
	s_waitcnt vmcnt(6)
	s_barrier
	v_mfma_f32_16x16x32_bf16 v[54:57], v[196:199], v[146:149], v[54:57]
	v_mfma_f32_16x16x32_bf16 v[50:53], v[208:211], v[146:149], v[50:53]
	v_mfma_f32_16x16x32_bf16 v[38:41], v[196:199], v[154:157], v[38:41]
	v_mfma_f32_16x16x32_bf16 v[34:37], v[208:211], v[154:157], v[34:37]
	v_mfma_f32_16x16x32_bf16 v[22:25], v[196:199], v[180:183], v[22:25]
	v_mfma_f32_16x16x32_bf16 v[18:21], v[208:211], v[180:183], v[18:21]
	v_mfma_f32_16x16x32_bf16 v[6:9], v[196:199], v[188:191], v[6:9]
	v_mfma_f32_16x16x32_bf16 v[2:5], v[208:211], v[188:191], v[2:5]
	v_mfma_f32_16x16x32_bf16 v[54:57], v[200:203], v[150:153], v[54:57]
	v_mfma_f32_16x16x32_bf16 v[50:53], v[212:215], v[150:153], v[50:53]
	v_mfma_f32_16x16x32_bf16 v[38:41], v[200:203], v[176:179], v[38:41]
	v_mfma_f32_16x16x32_bf16 v[34:37], v[212:215], v[176:179], v[34:37]
	v_mfma_f32_16x16x32_bf16 v[22:25], v[200:203], v[184:187], v[22:25]
	v_mfma_f32_16x16x32_bf16 v[18:21], v[212:215], v[184:187], v[18:21]
	v_mfma_f32_16x16x32_bf16 v[6:9], v[200:203], v[192:195], v[6:9]
	v_mfma_f32_16x16x32_bf16 v[2:5], v[212:215], v[192:195], v[2:5]
	s_barrier
	s_add_i32 s48, 0, 0x18000
	v_add_u32_e32 v122, s48, v206
	ds_read_b128 v[98:101], v122
	ds_read_b128 v[106:109], v122 offset:1024
	ds_read_b128 v[114:117], v122 offset:2048
	ds_read_b128 v[122:125], v122 offset:3072
	s_add_u32 s14, s14, 0x4000
	s_addc_u32 s15, s15, 0
	s_mov_b32 m0, s22
	v_lshl_add_u64 v[196:197], s[14:15], 0, v[158:159]
	ds_read_b128 v[146:149], v207 offset:32768
	ds_read_b128 v[150:153], v207 offset:33792
	ds_read_b128 v[154:157], v207 offset:34816
	ds_read_b128 v[176:179], v207 offset:35840
	ds_read_b128 v[180:183], v207 offset:36864
	ds_read_b128 v[184:187], v207 offset:37888
	ds_read_b128 v[188:191], v207 offset:38912
	ds_read_b128 v[192:195], v207 offset:39936
	global_load_lds_dwordx4 v[196:197], off
	v_lshl_add_u64 v[196:197], s[14:15], 0, v[172:173]
	s_mov_b32 m0, s23
	s_nop 0
	global_load_lds_dwordx4 v[196:197], off
	s_waitcnt lgkmcnt(8)
	s_barrier
	s_waitcnt lgkmcnt(0)
	v_mfma_f32_16x16x32_bf16 v[142:145], v[98:101], v[146:149], v[142:145]
	v_mfma_f32_16x16x32_bf16 v[138:141], v[114:117], v[146:149], v[138:141]
	v_mfma_f32_16x16x32_bf16 v[126:129], v[98:101], v[154:157], v[126:129]
	v_mfma_f32_16x16x32_bf16 v[118:121], v[114:117], v[154:157], v[118:121]
	v_mfma_f32_16x16x32_bf16 v[94:97], v[98:101], v[180:183], v[94:97]
	v_mfma_f32_16x16x32_bf16 v[90:93], v[114:117], v[180:183], v[90:93]
	v_mfma_f32_16x16x32_bf16 v[78:81], v[98:101], v[188:191], v[78:81]
	v_mfma_f32_16x16x32_bf16 v[74:77], v[114:117], v[188:191], v[74:77]
	v_mfma_f32_16x16x32_bf16 v[142:145], v[106:109], v[150:153], v[142:145]
	v_mfma_f32_16x16x32_bf16 v[138:141], v[122:125], v[150:153], v[138:141]
	v_mfma_f32_16x16x32_bf16 v[126:129], v[106:109], v[176:179], v[126:129]
	v_mfma_f32_16x16x32_bf16 v[118:121], v[122:125], v[176:179], v[118:121]
	v_mfma_f32_16x16x32_bf16 v[94:97], v[106:109], v[184:187], v[94:97]
	v_mfma_f32_16x16x32_bf16 v[90:93], v[122:125], v[184:187], v[90:93]
	v_mfma_f32_16x16x32_bf16 v[78:81], v[106:109], v[192:195], v[78:81]
	v_mfma_f32_16x16x32_bf16 v[74:77], v[122:125], v[192:195], v[74:77]
	s_barrier
	s_add_i32 s14, 0, 0x1c000
	s_add_i32 s15, s48, s19
	v_add_u32_e32 v212, s14, v206
	v_lshl_add_u64 v[168:169], v[168:169], 0, s[84:85]
	s_mov_b32 m0, s15
	ds_read_b128 v[196:199], v212
	ds_read_b128 v[200:203], v212 offset:1024
	ds_read_b128 v[208:211], v212 offset:2048
	ds_read_b128 v[212:215], v212 offset:3072
	global_load_lds_dwordx4 v[168:169], off
	v_lshl_add_u64 v[168:169], v[204:205], 0, s[84:85]
	s_add_i32 m0, s15, 0x2000
	s_nop 0
	global_load_lds_dwordx4 v[168:169], off
	s_barrier
	s_waitcnt lgkmcnt(0)
	v_mfma_f32_16x16x32_bf16 v[134:137], v[196:199], v[146:149], v[134:137]
	v_mfma_f32_16x16x32_bf16 v[130:133], v[208:211], v[146:149], v[130:133]
	v_mfma_f32_16x16x32_bf16 v[110:113], v[196:199], v[154:157], v[110:113]
	v_mfma_f32_16x16x32_bf16 v[102:105], v[208:211], v[154:157], v[102:105]
	v_mfma_f32_16x16x32_bf16 v[86:89], v[196:199], v[180:183], v[86:89]
	v_mfma_f32_16x16x32_bf16 v[82:85], v[208:211], v[180:183], v[82:85]
	v_mfma_f32_16x16x32_bf16 v[70:73], v[196:199], v[188:191], v[70:73]
	v_mfma_f32_16x16x32_bf16 v[66:69], v[208:211], v[188:191], v[66:69]
	v_mfma_f32_16x16x32_bf16 v[134:137], v[200:203], v[150:153], v[134:137]
	v_mfma_f32_16x16x32_bf16 v[130:133], v[212:215], v[150:153], v[130:133]
	v_mfma_f32_16x16x32_bf16 v[110:113], v[200:203], v[176:179], v[110:113]
	v_mfma_f32_16x16x32_bf16 v[102:105], v[212:215], v[176:179], v[102:105]
	v_mfma_f32_16x16x32_bf16 v[86:89], v[200:203], v[184:187], v[86:89]
	v_mfma_f32_16x16x32_bf16 v[82:85], v[212:215], v[184:187], v[82:85]
	v_mfma_f32_16x16x32_bf16 v[70:73], v[200:203], v[192:195], v[70:73]
	v_mfma_f32_16x16x32_bf16 v[66:69], v[212:215], v[192:195], v[66:69]
	s_barrier
	s_mov_b32 m0, s31
	v_lshl_add_u64 v[168:169], s[12:13], 0, v[158:159]
	ds_read_b128 v[146:149], v207 offset:49152
	ds_read_b128 v[150:153], v207 offset:50176
	ds_read_b128 v[154:157], v207 offset:51200
	ds_read_b128 v[176:179], v207 offset:52224
	ds_read_b128 v[180:183], v207 offset:53248
	ds_read_b128 v[184:187], v207 offset:54272
	ds_read_b128 v[188:191], v207 offset:55296
	ds_read_b128 v[192:195], v207 offset:56320
	global_load_lds_dwordx4 v[168:169], off
	v_lshl_add_u64 v[168:169], s[12:13], 0, v[172:173]
	s_mov_b32 m0, s34
	s_nop 0
	global_load_lds_dwordx4 v[168:169], off
	s_barrier
	s_waitcnt lgkmcnt(0)
	v_mfma_f32_16x16x32_bf16 v[62:65], v[98:101], v[146:149], v[62:65]
	v_mfma_f32_16x16x32_bf16 v[58:61], v[114:117], v[146:149], v[58:61]
	v_mfma_f32_16x16x32_bf16 v[46:49], v[98:101], v[154:157], v[46:49]
	v_mfma_f32_16x16x32_bf16 v[42:45], v[114:117], v[154:157], v[42:45]
	v_mfma_f32_16x16x32_bf16 v[30:33], v[98:101], v[180:183], v[30:33]
	v_mfma_f32_16x16x32_bf16 v[26:29], v[114:117], v[180:183], v[26:29]
	v_mfma_f32_16x16x32_bf16 v[14:17], v[98:101], v[188:191], v[14:17]
	v_mfma_f32_16x16x32_bf16 v[10:13], v[114:117], v[188:191], v[10:13]
	v_mfma_f32_16x16x32_bf16 v[62:65], v[106:109], v[150:153], v[62:65]
	v_mfma_f32_16x16x32_bf16 v[58:61], v[122:125], v[150:153], v[58:61]
	v_mfma_f32_16x16x32_bf16 v[46:49], v[106:109], v[176:179], v[46:49]
	v_mfma_f32_16x16x32_bf16 v[42:45], v[122:125], v[176:179], v[42:45]
	v_mfma_f32_16x16x32_bf16 v[30:33], v[106:109], v[184:187], v[30:33]
	v_mfma_f32_16x16x32_bf16 v[26:29], v[122:125], v[184:187], v[26:29]
	v_mfma_f32_16x16x32_bf16 v[14:17], v[106:109], v[192:195], v[14:17]
	v_mfma_f32_16x16x32_bf16 v[10:13], v[122:125], v[192:195], v[10:13]
	s_barrier
	s_add_u32 s10, s10, 0xb0080
	s_addc_u32 s11, s11, 0
	s_add_i32 s12, s14, s19
	v_lshl_add_u64 v[98:99], s[10:11], 0, v[160:161]
	s_mov_b32 m0, s12
	s_nop 0
	global_load_lds_dwordx4 v[98:99], off
	v_lshl_add_u64 v[98:99], s[10:11], 0, v[174:175]
	s_add_i32 m0, s12, 0x2000
	s_nop 0
	global_load_lds_dwordx4 v[98:99], off
	s_waitcnt vmcnt(6)
	s_barrier
	v_mfma_f32_16x16x32_bf16 v[54:57], v[196:199], v[146:149], v[54:57]
	v_mfma_f32_16x16x32_bf16 v[50:53], v[208:211], v[146:149], v[50:53]
	v_mfma_f32_16x16x32_bf16 v[38:41], v[196:199], v[154:157], v[38:41]
	v_mfma_f32_16x16x32_bf16 v[34:37], v[208:211], v[154:157], v[34:37]
	v_mfma_f32_16x16x32_bf16 v[22:25], v[196:199], v[180:183], v[22:25]
	v_mfma_f32_16x16x32_bf16 v[18:21], v[208:211], v[180:183], v[18:21]
	v_mfma_f32_16x16x32_bf16 v[6:9], v[196:199], v[188:191], v[6:9]
	v_mfma_f32_16x16x32_bf16 v[2:5], v[208:211], v[188:191], v[2:5]
	v_mfma_f32_16x16x32_bf16 v[54:57], v[200:203], v[150:153], v[54:57]
	v_mfma_f32_16x16x32_bf16 v[50:53], v[212:215], v[150:153], v[50:53]
	v_mfma_f32_16x16x32_bf16 v[38:41], v[200:203], v[176:179], v[38:41]
	v_mfma_f32_16x16x32_bf16 v[34:37], v[212:215], v[176:179], v[34:37]
	v_mfma_f32_16x16x32_bf16 v[22:25], v[200:203], v[184:187], v[22:25]
	v_mfma_f32_16x16x32_bf16 v[18:21], v[212:215], v[184:187], v[18:21]
	v_mfma_f32_16x16x32_bf16 v[6:9], v[200:203], v[192:195], v[6:9]
	v_mfma_f32_16x16x32_bf16 v[2:5], v[212:215], v[192:195], v[2:5]
	s_barrier
	s_add_u32 s45, s45, 0x100
	s_addc_u32 s46, s46, 0
	s_add_u32 s8, s8, 0x10000
	s_addc_u32 s9, s9, 0
	s_cmp_ge_i32 s47, s28
	s_mov_b32 s10, s47
	s_cbranch_scc0 .LBB0_500

.LBB0_534:
	s_add_i32 s57, s22, 2
	s_add_u32 s23, s20, 0xfffc0080
	s_addc_u32 s24, s21, -1
	s_add_i32 s58, 0, 0x10000
	v_add_u32_e32 v62, s58, v214
	ds_read_b128 v[34:37], v62
	ds_read_b128 v[38:41], v62 offset:1024
	ds_read_b128 v[58:61], v62 offset:2048
	ds_read_b128 v[62:65], v62 offset:3072
	s_cmp_eq_u32 s49, s22
	s_cselect_b32 s22, s38, s39
	s_cselect_b32 s25, s11, s24
	s_cselect_b32 s24, s13, s23
	s_cselect_b32 s23, s19, s56
	v_lshl_add_u64 v[168:169], s[20:21], 0, v[180:181]
	s_add_i32 m0, s35, 0xc000
	ds_read_b128 v[146:149], v215
	ds_read_b128 v[150:153], v215 offset:1024
	ds_read_b128 v[154:157], v215 offset:2048
	ds_read_b128 v[158:161], v215 offset:3072
	ds_read_b128 v[184:187], v215 offset:4096
	ds_read_b128 v[188:191], v215 offset:5120
	ds_read_b128 v[192:195], v215 offset:6144
	ds_read_b128 v[196:199], v215 offset:7168
	global_load_lds_dwordx4 v[168:169], off
	v_lshl_add_u64 v[168:169], s[20:21], 0, v[182:183]
	s_add_i32 m0, s35, 0xe000
	s_nop 0
	global_load_lds_dwordx4 v[168:169], off
	s_waitcnt lgkmcnt(8)
	s_barrier
	s_waitcnt lgkmcnt(0)
	v_mfma_f32_16x16x32_bf16 v[142:145], v[34:37], v[146:149], v[142:145]
	v_mfma_f32_16x16x32_bf16 v[134:137], v[58:61], v[146:149], v[134:137]
	v_mfma_f32_16x16x32_bf16 v[126:129], v[34:37], v[154:157], v[126:129]
	v_mfma_f32_16x16x32_bf16 v[118:121], v[58:61], v[154:157], v[118:121]
	v_mfma_f32_16x16x32_bf16 v[110:113], v[34:37], v[184:187], v[110:113]
	v_mfma_f32_16x16x32_bf16 v[102:105], v[58:61], v[184:187], v[102:105]
	v_mfma_f32_16x16x32_bf16 v[94:97], v[34:37], v[192:195], v[94:97]
	v_mfma_f32_16x16x32_bf16 v[86:89], v[58:61], v[192:195], v[86:89]
	v_mfma_f32_16x16x32_bf16 v[142:145], v[38:41], v[150:153], v[142:145]
	v_mfma_f32_16x16x32_bf16 v[134:137], v[62:65], v[150:153], v[134:137]
	v_mfma_f32_16x16x32_bf16 v[126:129], v[38:41], v[158:161], v[126:129]
	v_mfma_f32_16x16x32_bf16 v[118:121], v[62:65], v[158:161], v[118:121]
	v_mfma_f32_16x16x32_bf16 v[110:113], v[38:41], v[188:191], v[110:113]
	v_mfma_f32_16x16x32_bf16 v[102:105], v[62:65], v[188:191], v[102:105]
	v_mfma_f32_16x16x32_bf16 v[94:97], v[38:41], v[196:199], v[94:97]
	v_mfma_f32_16x16x32_bf16 v[86:89], v[62:65], v[196:199], v[86:89]
	s_barrier
	s_add_i32 s60, 0, 0x14000
	v_add_u32_e32 v168, s60, v214
	s_add_i32 s58, s58, s31
	ds_read_b128 v[200:203], v168
	ds_read_b128 v[204:207], v168 offset:1024
	ds_read_b128 v[208:211], v168 offset:2048
	ds_read_b128 v[216:219], v168 offset:3072
	v_lshl_add_u64 v[168:169], s[22:23], 0, v[176:177]
	s_mov_b32 m0, s58
	v_lshl_add_u64 v[220:221], s[22:23], 0, v[172:173]
	global_load_lds_dwordx4 v[168:169], off
	s_add_i32 m0, s58, 0x2000
	s_nop 0
	global_load_lds_dwordx4 v[220:221], off
	s_barrier
	s_waitcnt lgkmcnt(0)
	v_mfma_f32_16x16x32_bf16 v[138:141], v[200:203], v[146:149], v[138:141]
	v_mfma_f32_16x16x32_bf16 v[130:133], v[208:211], v[146:149], v[130:133]
	v_mfma_f32_16x16x32_bf16 v[122:125], v[200:203], v[154:157], v[122:125]
	v_mfma_f32_16x16x32_bf16 v[114:117], v[208:211], v[154:157], v[114:117]
	v_mfma_f32_16x16x32_bf16 v[106:109], v[200:203], v[184:187], v[106:109]
	v_mfma_f32_16x16x32_bf16 v[98:101], v[208:211], v[184:187], v[98:101]
	v_mfma_f32_16x16x32_bf16 v[90:93], v[200:203], v[192:195], v[90:93]
	v_mfma_f32_16x16x32_bf16 v[82:85], v[208:211], v[192:195], v[82:85]
	v_mfma_f32_16x16x32_bf16 v[138:141], v[204:207], v[150:153], v[138:141]
	v_mfma_f32_16x16x32_bf16 v[130:133], v[216:219], v[150:153], v[130:133]
	v_mfma_f32_16x16x32_bf16 v[122:125], v[204:207], v[158:161], v[122:125]
	v_mfma_f32_16x16x32_bf16 v[114:117], v[216:219], v[158:161], v[114:117]
	v_mfma_f32_16x16x32_bf16 v[106:109], v[204:207], v[188:191], v[106:109]
	v_mfma_f32_16x16x32_bf16 v[98:101], v[216:219], v[188:191], v[98:101]
	v_mfma_f32_16x16x32_bf16 v[90:93], v[204:207], v[196:199], v[90:93]
	v_mfma_f32_16x16x32_bf16 v[82:85], v[216:219], v[196:199], v[82:85]
	s_barrier
	s_mov_b32 m0, s35
	v_lshl_add_u64 v[236:237], s[24:25], 0, v[178:179]
	ds_read_b128 v[146:149], v215 offset:16384
	ds_read_b128 v[150:153], v215 offset:17408
	ds_read_b128 v[154:157], v215 offset:18432
	ds_read_b128 v[158:161], v215 offset:19456
	ds_read_b128 v[184:187], v215 offset:20480
	ds_read_b128 v[188:191], v215 offset:21504
	ds_read_b128 v[192:195], v215 offset:22528
	ds_read_b128 v[196:199], v215 offset:23552
	global_load_lds_dwordx4 v[236:237], off
	v_lshl_add_u64 v[238:239], s[24:25], 0, v[174:175]
	s_mov_b32 m0, s40
	s_nop 0
	global_load_lds_dwordx4 v[238:239], off
	s_barrier
	s_waitcnt lgkmcnt(0)
	v_mfma_f32_16x16x32_bf16 v[78:81], v[34:37], v[146:149], v[78:81]
	v_mfma_f32_16x16x32_bf16 v[70:73], v[58:61], v[146:149], v[70:73]
	v_mfma_f32_16x16x32_bf16 v[54:57], v[34:37], v[154:157], v[54:57]
	v_mfma_f32_16x16x32_bf16 v[46:49], v[58:61], v[154:157], v[46:49]
	v_mfma_f32_16x16x32_bf16 v[30:33], v[34:37], v[184:187], v[30:33]
	v_mfma_f32_16x16x32_bf16 v[22:25], v[58:61], v[184:187], v[22:25]
	v_mfma_f32_16x16x32_bf16 v[14:17], v[34:37], v[192:195], v[14:17]
	v_mfma_f32_16x16x32_bf16 v[6:9], v[58:61], v[192:195], v[6:9]
	v_mfma_f32_16x16x32_bf16 v[78:81], v[38:41], v[150:153], v[78:81]
	v_mfma_f32_16x16x32_bf16 v[70:73], v[62:65], v[150:153], v[70:73]
	v_mfma_f32_16x16x32_bf16 v[54:57], v[38:41], v[158:161], v[54:57]
	v_mfma_f32_16x16x32_bf16 v[46:49], v[62:65], v[158:161], v[46:49]
	v_mfma_f32_16x16x32_bf16 v[30:33], v[38:41], v[188:191], v[30:33]
	v_mfma_f32_16x16x32_bf16 v[22:25], v[62:65], v[188:191], v[22:25]
	v_mfma_f32_16x16x32_bf16 v[14:17], v[38:41], v[196:199], v[14:17]
	v_mfma_f32_16x16x32_bf16 v[6:9], v[62:65], v[196:199], v[6:9]
	s_barrier
	s_add_u32 s58, s22, 0x40000
	s_addc_u32 s59, s23, 0
	s_add_i32 s60, s60, s31
	v_lshl_add_u64 v[34:35], s[58:59], 0, v[176:177]
	s_mov_b32 m0, s60
	s_nop 0
	global_load_lds_dwordx4 v[34:35], off
	v_lshl_add_u64 v[34:35], s[58:59], 0, v[172:173]
	s_add_i32 m0, s60, 0x2000
	s_nop 0
	global_load_lds_dwordx4 v[34:35], off
	s_waitcnt vmcnt(6)
	s_barrier
	v_mfma_f32_16x16x32_bf16 v[50:53], v[200:203], v[154:157], v[50:53]
	v_mfma_f32_16x16x32_bf16 v[42:45], v[208:211], v[154:157], v[42:45]
	v_mfma_f32_16x16x32_bf16 v[26:29], v[200:203], v[184:187], v[26:29]
	v_mfma_f32_16x16x32_bf16 v[18:21], v[208:211], v[184:187], v[18:21]
	v_mfma_f32_16x16x32_bf16 v[10:13], v[200:203], v[192:195], v[10:13]
	v_mfma_f32_16x16x32_bf16 v[2:5], v[208:211], v[192:195], v[2:5]
	v_mfma_f32_16x16x32_bf16 v[34:37], v[200:203], v[146:149], v[74:77]
	v_mfma_f32_16x16x32_bf16 v[38:41], v[208:211], v[146:149], v[66:69]
	v_mfma_f32_16x16x32_bf16 v[50:53], v[204:207], v[158:161], v[50:53]
	v_mfma_f32_16x16x32_bf16 v[42:45], v[216:219], v[158:161], v[42:45]
	v_mfma_f32_16x16x32_bf16 v[26:29], v[204:207], v[188:191], v[26:29]
	v_mfma_f32_16x16x32_bf16 v[18:21], v[216:219], v[188:191], v[18:21]
	v_mfma_f32_16x16x32_bf16 v[10:13], v[204:207], v[196:199], v[10:13]
	v_mfma_f32_16x16x32_bf16 v[2:5], v[216:219], v[196:199], v[2:5]
	v_mfma_f32_16x16x32_bf16 v[34:37], v[204:207], v[150:153], v[34:37]
	v_mfma_f32_16x16x32_bf16 v[38:41], v[216:219], v[150:153], v[38:41]
	s_barrier
	s_add_i32 s58, 0, 0x18000
	v_add_u32_e32 v74, s58, v214
	ds_read_b128 v[58:61], v74
	ds_read_b128 v[62:65], v74 offset:1024
	ds_read_b128 v[66:69], v74 offset:2048
	ds_read_b128 v[74:77], v74 offset:3072
	s_add_u32 s24, s24, 0x40000
	s_addc_u32 s25, s25, 0
	s_mov_b32 m0, s41
	v_lshl_add_u64 v[200:201], s[24:25], 0, v[178:179]
	ds_read_b128 v[146:149], v215 offset:32768
	ds_read_b128 v[150:153], v215 offset:33792
	ds_read_b128 v[154:157], v215 offset:34816
	ds_read_b128 v[158:161], v215 offset:35840
	ds_read_b128 v[184:187], v215 offset:36864
	ds_read_b128 v[188:191], v215 offset:37888
	ds_read_b128 v[192:195], v215 offset:38912
	ds_read_b128 v[196:199], v215 offset:39936
	global_load_lds_dwordx4 v[200:201], off
	v_lshl_add_u64 v[200:201], s[24:25], 0, v[174:175]
	s_mov_b32 m0, s42
	s_nop 0
	global_load_lds_dwordx4 v[200:201], off
	s_waitcnt lgkmcnt(8)
	s_barrier
	s_waitcnt lgkmcnt(0)
	v_mfma_f32_16x16x32_bf16 v[142:145], v[58:61], v[146:149], v[142:145]
	v_mfma_f32_16x16x32_bf16 v[134:137], v[66:69], v[146:149], v[134:137]
	v_mfma_f32_16x16x32_bf16 v[126:129], v[58:61], v[154:157], v[126:129]
	v_mfma_f32_16x16x32_bf16 v[118:121], v[66:69], v[154:157], v[118:121]
	v_mfma_f32_16x16x32_bf16 v[110:113], v[58:61], v[184:187], v[110:113]
	v_mfma_f32_16x16x32_bf16 v[102:105], v[66:69], v[184:187], v[102:105]
	v_mfma_f32_16x16x32_bf16 v[94:97], v[58:61], v[192:195], v[94:97]
	v_mfma_f32_16x16x32_bf16 v[86:89], v[66:69], v[192:195], v[86:89]
	v_mfma_f32_16x16x32_bf16 v[142:145], v[62:65], v[150:153], v[142:145]
	v_mfma_f32_16x16x32_bf16 v[134:137], v[74:77], v[150:153], v[134:137]
	v_mfma_f32_16x16x32_bf16 v[126:129], v[62:65], v[158:161], v[126:129]
	v_mfma_f32_16x16x32_bf16 v[118:121], v[74:77], v[158:161], v[118:121]
	v_mfma_f32_16x16x32_bf16 v[110:113], v[62:65], v[188:191], v[110:113]
	v_mfma_f32_16x16x32_bf16 v[102:105], v[74:77], v[188:191], v[102:105]
	v_mfma_f32_16x16x32_bf16 v[94:97], v[62:65], v[196:199], v[94:97]
	v_mfma_f32_16x16x32_bf16 v[86:89], v[74:77], v[196:199], v[86:89]
	s_barrier
	s_add_i32 s24, 0, 0x1c000
	s_add_i32 s25, s58, s31
	v_add_u32_e32 v216, s24, v214
	v_lshl_add_u64 v[168:169], v[168:169], 0, s[84:85]
	s_mov_b32 m0, s25
	ds_read_b128 v[200:203], v216
	ds_read_b128 v[204:207], v216 offset:1024
	ds_read_b128 v[208:211], v216 offset:2048
	ds_read_b128 v[216:219], v216 offset:3072
	global_load_lds_dwordx4 v[168:169], off
	v_lshl_add_u64 v[168:169], v[220:221], 0, s[84:85]
	s_add_i32 m0, s25, 0x2000
	s_nop 0
	global_load_lds_dwordx4 v[168:169], off
	s_barrier
	s_waitcnt lgkmcnt(0)
	v_mfma_f32_16x16x32_bf16 v[138:141], v[200:203], v[146:149], v[138:141]
	v_mfma_f32_16x16x32_bf16 v[130:133], v[208:211], v[146:149], v[130:133]
	v_mfma_f32_16x16x32_bf16 v[122:125], v[200:203], v[154:157], v[122:125]
	v_mfma_f32_16x16x32_bf16 v[114:117], v[208:211], v[154:157], v[114:117]
	v_mfma_f32_16x16x32_bf16 v[106:109], v[200:203], v[184:187], v[106:109]
	v_mfma_f32_16x16x32_bf16 v[98:101], v[208:211], v[184:187], v[98:101]
	v_mfma_f32_16x16x32_bf16 v[90:93], v[200:203], v[192:195], v[90:93]
	v_mfma_f32_16x16x32_bf16 v[82:85], v[208:211], v[192:195], v[82:85]
	v_mfma_f32_16x16x32_bf16 v[138:141], v[204:207], v[150:153], v[138:141]
	v_mfma_f32_16x16x32_bf16 v[130:133], v[216:219], v[150:153], v[130:133]
	v_mfma_f32_16x16x32_bf16 v[122:125], v[204:207], v[158:161], v[122:125]
	v_mfma_f32_16x16x32_bf16 v[114:117], v[216:219], v[158:161], v[114:117]
	v_mfma_f32_16x16x32_bf16 v[106:109], v[204:207], v[188:191], v[106:109]
	v_mfma_f32_16x16x32_bf16 v[98:101], v[216:219], v[188:191], v[98:101]
	v_mfma_f32_16x16x32_bf16 v[90:93], v[204:207], v[196:199], v[90:93]
	v_mfma_f32_16x16x32_bf16 v[82:85], v[216:219], v[196:199], v[82:85]
	s_barrier
	s_mov_b32 m0, s47
	v_lshl_add_u64 v[168:169], v[236:237], 0, s[84:85]
	ds_read_b128 v[146:149], v215 offset:49152
	ds_read_b128 v[150:153], v215 offset:50176
	ds_read_b128 v[154:157], v215 offset:51200
	ds_read_b128 v[158:161], v215 offset:52224
	ds_read_b128 v[184:187], v215 offset:53248
	ds_read_b128 v[188:191], v215 offset:54272
	ds_read_b128 v[192:195], v215 offset:55296
	ds_read_b128 v[196:199], v215 offset:56320
	global_load_lds_dwordx4 v[168:169], off
	v_lshl_add_u64 v[168:169], v[238:239], 0, s[84:85]
	s_mov_b32 m0, s48
	s_nop 0
	global_load_lds_dwordx4 v[168:169], off
	s_barrier
	s_waitcnt lgkmcnt(0)
	v_mfma_f32_16x16x32_bf16 v[78:81], v[58:61], v[146:149], v[78:81]
	v_mfma_f32_16x16x32_bf16 v[70:73], v[66:69], v[146:149], v[70:73]
	v_mfma_f32_16x16x32_bf16 v[54:57], v[58:61], v[154:157], v[54:57]
	v_mfma_f32_16x16x32_bf16 v[46:49], v[66:69], v[154:157], v[46:49]
	v_mfma_f32_16x16x32_bf16 v[30:33], v[58:61], v[184:187], v[30:33]
	v_mfma_f32_16x16x32_bf16 v[22:25], v[66:69], v[184:187], v[22:25]
	v_mfma_f32_16x16x32_bf16 v[14:17], v[58:61], v[192:195], v[14:17]
	v_mfma_f32_16x16x32_bf16 v[6:9], v[66:69], v[192:195], v[6:9]
	v_mfma_f32_16x16x32_bf16 v[78:81], v[62:65], v[150:153], v[78:81]
	v_mfma_f32_16x16x32_bf16 v[70:73], v[74:77], v[150:153], v[70:73]
	v_mfma_f32_16x16x32_bf16 v[54:57], v[62:65], v[158:161], v[54:57]
	v_mfma_f32_16x16x32_bf16 v[46:49], v[74:77], v[158:161], v[46:49]
	v_mfma_f32_16x16x32_bf16 v[30:33], v[62:65], v[188:191], v[30:33]
	v_mfma_f32_16x16x32_bf16 v[22:25], v[74:77], v[188:191], v[22:25]
	v_mfma_f32_16x16x32_bf16 v[14:17], v[62:65], v[196:199], v[14:17]
	v_mfma_f32_16x16x32_bf16 v[6:9], v[74:77], v[196:199], v[6:9]
	s_barrier
	s_add_u32 s22, s22, 0x40080
	s_addc_u32 s23, s23, 0
	s_add_i32 s24, s24, s31
	v_lshl_add_u64 v[58:59], s[22:23], 0, v[176:177]
	s_mov_b32 m0, s24
	s_nop 0
	global_load_lds_dwordx4 v[58:59], off
	v_lshl_add_u64 v[58:59], s[22:23], 0, v[172:173]
	s_add_i32 m0, s24, 0x2000
	s_nop 0
	global_load_lds_dwordx4 v[58:59], off
	s_waitcnt vmcnt(6)
	s_barrier
	v_mfma_f32_16x16x32_bf16 v[34:37], v[200:203], v[146:149], v[34:37]
	v_mfma_f32_16x16x32_bf16 v[74:77], v[204:207], v[150:153], v[34:37]
	v_mfma_f32_16x16x32_bf16 v[34:37], v[208:211], v[146:149], v[38:41]
	v_mfma_f32_16x16x32_bf16 v[66:69], v[216:219], v[150:153], v[34:37]
	v_mfma_f32_16x16x32_bf16 v[34:37], v[200:203], v[154:157], v[50:53]
	v_mfma_f32_16x16x32_bf16 v[50:53], v[204:207], v[158:161], v[34:37]
	v_mfma_f32_16x16x32_bf16 v[34:37], v[208:211], v[154:157], v[42:45]
	v_mfma_f32_16x16x32_bf16 v[26:29], v[200:203], v[184:187], v[26:29]
	v_mfma_f32_16x16x32_bf16 v[18:21], v[208:211], v[184:187], v[18:21]
	v_mfma_f32_16x16x32_bf16 v[10:13], v[200:203], v[192:195], v[10:13]
	v_mfma_f32_16x16x32_bf16 v[2:5], v[208:211], v[192:195], v[2:5]
	v_mfma_f32_16x16x32_bf16 v[42:45], v[216:219], v[158:161], v[34:37]
	v_mfma_f32_16x16x32_bf16 v[26:29], v[204:207], v[188:191], v[26:29]
	v_mfma_f32_16x16x32_bf16 v[18:21], v[216:219], v[188:191], v[18:21]
	v_mfma_f32_16x16x32_bf16 v[10:13], v[204:207], v[196:199], v[10:13]
	v_mfma_f32_16x16x32_bf16 v[2:5], v[216:219], v[196:199], v[2:5]
	s_barrier
	s_add_u32 s20, s20, 0x100
	s_addc_u32 s21, s21, 0
	s_add_u32 s39, s39, 0x100
	s_addc_u32 s56, s56, 0
	s_cmp_ge_i32 s57, s45
	s_mov_b32 s22, s57
	s_cbranch_scc0 .LBB0_534

.LBB0_563:
	s_add_i32 s47, s16, 2
	s_add_u32 s17, s14, 0xfffc0080
	s_addc_u32 s18, s15, -1
	s_add_i32 s48, 0, 0x10000
	v_add_u32_e32 v102, s48, v159
	ds_read_b128 v[82:85], v102
	ds_read_b128 v[86:89], v102 offset:1024
	ds_read_b128 v[98:101], v102 offset:2048
	ds_read_b128 v[102:105], v102 offset:3072
	s_cmp_eq_u32 s39, s16
	s_cselect_b32 s16, s44, s45
	s_cselect_b32 s19, s5, s18
	s_cselect_b32 s18, s7, s17
	s_cselect_b32 s17, s43, s46
	v_lshl_add_u64 v[160:161], s[14:15], 0, v[154:155]
	s_add_i32 m0, s13, 0xc000
	ds_read_b128 v[174:177], v173
	ds_read_b128 v[178:181], v173 offset:1024
	ds_read_b128 v[182:185], v173 offset:2048
	ds_read_b128 v[186:189], v173 offset:3072
	ds_read_b128 v[190:193], v173 offset:4096
	ds_read_b128 v[194:197], v173 offset:5120
	ds_read_b128 v[198:201], v173 offset:6144
	ds_read_b128 v[202:205], v173 offset:7168
	global_load_lds_dwordx4 v[160:161], off
	v_lshl_add_u64 v[160:161], s[14:15], 0, v[156:157]
	s_add_i32 m0, s13, 0xe000
	s_nop 0
	global_load_lds_dwordx4 v[160:161], off
	s_waitcnt lgkmcnt(8)
	s_barrier
	s_waitcnt lgkmcnt(0)
	v_mfma_f32_16x16x32_bf16 v[138:141], v[82:85], v[174:177], v[138:141]
	v_mfma_f32_16x16x32_bf16 v[134:137], v[98:101], v[174:177], v[134:137]
	v_mfma_f32_16x16x32_bf16 v[126:129], v[82:85], v[182:185], v[126:129]
	v_mfma_f32_16x16x32_bf16 v[118:121], v[98:101], v[182:185], v[118:121]
	v_mfma_f32_16x16x32_bf16 v[110:113], v[82:85], v[190:193], v[110:113]
	v_mfma_f32_16x16x32_bf16 v[94:97], v[98:101], v[190:193], v[94:97]
	v_mfma_f32_16x16x32_bf16 v[78:81], v[82:85], v[198:201], v[78:81]
	v_mfma_f32_16x16x32_bf16 v[70:73], v[98:101], v[198:201], v[70:73]
	v_mfma_f32_16x16x32_bf16 v[138:141], v[86:89], v[178:181], v[138:141]
	v_mfma_f32_16x16x32_bf16 v[134:137], v[102:105], v[178:181], v[134:137]
	v_mfma_f32_16x16x32_bf16 v[126:129], v[86:89], v[186:189], v[126:129]
	v_mfma_f32_16x16x32_bf16 v[118:121], v[102:105], v[186:189], v[118:121]
	v_mfma_f32_16x16x32_bf16 v[110:113], v[86:89], v[194:197], v[110:113]
	v_mfma_f32_16x16x32_bf16 v[94:97], v[102:105], v[194:197], v[94:97]
	v_mfma_f32_16x16x32_bf16 v[78:81], v[86:89], v[202:205], v[78:81]
	v_mfma_f32_16x16x32_bf16 v[70:73], v[102:105], v[202:205], v[70:73]
	s_barrier
	s_add_i32 s50, 0, 0x14000
	s_add_i32 s48, s48, s23
	v_add_u32_e32 v158, s50, v159
	v_lshl_add_u64 v[160:161], s[16:17], 0, v[150:151]
	s_mov_b32 m0, s48
	ds_read_b128 v[206:209], v158
	ds_read_b128 v[210:213], v158 offset:1024
	ds_read_b128 v[214:217], v158 offset:2048
	ds_read_b128 v[218:221], v158 offset:3072
	global_load_lds_dwordx4 v[160:161], off
	v_lshl_add_u64 v[168:169], s[16:17], 0, v[146:147]
	s_add_i32 m0, s48, 0x2000
	s_nop 0
	global_load_lds_dwordx4 v[168:169], off
	s_barrier
	s_waitcnt lgkmcnt(0)
	v_mfma_f32_16x16x32_bf16 v[142:145], v[206:209], v[174:177], v[142:145]
	v_mfma_f32_16x16x32_bf16 v[130:133], v[214:217], v[174:177], v[130:133]
	v_mfma_f32_16x16x32_bf16 v[122:125], v[206:209], v[182:185], v[122:125]
	v_mfma_f32_16x16x32_bf16 v[114:117], v[214:217], v[182:185], v[114:117]
	v_mfma_f32_16x16x32_bf16 v[106:109], v[206:209], v[190:193], v[106:109]
	v_mfma_f32_16x16x32_bf16 v[90:93], v[214:217], v[190:193], v[90:93]
	v_mfma_f32_16x16x32_bf16 v[74:77], v[206:209], v[198:201], v[74:77]
	v_mfma_f32_16x16x32_bf16 v[66:69], v[214:217], v[198:201], v[66:69]
	v_mfma_f32_16x16x32_bf16 v[142:145], v[210:213], v[178:181], v[142:145]
	v_mfma_f32_16x16x32_bf16 v[130:133], v[218:221], v[178:181], v[130:133]
	v_mfma_f32_16x16x32_bf16 v[122:125], v[210:213], v[186:189], v[122:125]
	v_mfma_f32_16x16x32_bf16 v[114:117], v[218:221], v[186:189], v[114:117]
	v_mfma_f32_16x16x32_bf16 v[106:109], v[210:213], v[194:197], v[106:109]
	v_mfma_f32_16x16x32_bf16 v[90:93], v[218:221], v[194:197], v[90:93]
	v_mfma_f32_16x16x32_bf16 v[74:77], v[210:213], v[202:205], v[74:77]
	v_mfma_f32_16x16x32_bf16 v[66:69], v[218:221], v[202:205], v[66:69]
	s_barrier
	s_mov_b32 m0, s13
	v_lshl_add_u64 v[236:237], s[18:19], 0, v[152:153]
	ds_read_b128 v[174:177], v173 offset:16384
	ds_read_b128 v[178:181], v173 offset:17408
	ds_read_b128 v[182:185], v173 offset:18432
	ds_read_b128 v[186:189], v173 offset:19456
	ds_read_b128 v[190:193], v173 offset:20480
	ds_read_b128 v[194:197], v173 offset:21504
	ds_read_b128 v[198:201], v173 offset:22528
	ds_read_b128 v[202:205], v173 offset:23552
	global_load_lds_dwordx4 v[236:237], off
	v_lshl_add_u64 v[238:239], s[18:19], 0, v[148:149]
	s_mov_b32 m0, s25
	s_nop 0
	global_load_lds_dwordx4 v[238:239], off
	s_barrier
	s_waitcnt lgkmcnt(0)
	v_mfma_f32_16x16x32_bf16 v[62:65], v[82:85], v[174:177], v[62:65]
	v_mfma_f32_16x16x32_bf16 v[54:57], v[98:101], v[174:177], v[54:57]
	v_mfma_f32_16x16x32_bf16 v[46:49], v[82:85], v[182:185], v[46:49]
	v_mfma_f32_16x16x32_bf16 v[38:41], v[98:101], v[182:185], v[38:41]
	v_mfma_f32_16x16x32_bf16 v[30:33], v[82:85], v[190:193], v[30:33]
	v_mfma_f32_16x16x32_bf16 v[22:25], v[98:101], v[190:193], v[22:25]
	v_mfma_f32_16x16x32_bf16 v[14:17], v[82:85], v[198:201], v[14:17]
	v_mfma_f32_16x16x32_bf16 v[6:9], v[98:101], v[198:201], v[6:9]
	v_mfma_f32_16x16x32_bf16 v[62:65], v[86:89], v[178:181], v[62:65]
	v_mfma_f32_16x16x32_bf16 v[54:57], v[102:105], v[178:181], v[54:57]
	v_mfma_f32_16x16x32_bf16 v[46:49], v[86:89], v[186:189], v[46:49]
	v_mfma_f32_16x16x32_bf16 v[38:41], v[102:105], v[186:189], v[38:41]
	v_mfma_f32_16x16x32_bf16 v[30:33], v[86:89], v[194:197], v[30:33]
	v_mfma_f32_16x16x32_bf16 v[22:25], v[102:105], v[194:197], v[22:25]
	v_mfma_f32_16x16x32_bf16 v[14:17], v[86:89], v[202:205], v[14:17]
	v_mfma_f32_16x16x32_bf16 v[6:9], v[102:105], v[202:205], v[6:9]
	s_barrier
	s_add_u32 s48, s16, 0x40000
	s_addc_u32 s49, s17, 0
	s_add_i32 s50, s50, s23
	v_lshl_add_u64 v[82:83], s[48:49], 0, v[150:151]
	s_mov_b32 m0, s50
	s_nop 0
	global_load_lds_dwordx4 v[82:83], off
	v_lshl_add_u64 v[82:83], s[48:49], 0, v[146:147]
	s_add_i32 m0, s50, 0x2000
	s_nop 0
	global_load_lds_dwordx4 v[82:83], off
	s_waitcnt vmcnt(6)
	s_barrier
	v_mfma_f32_16x16x32_bf16 v[58:61], v[206:209], v[174:177], v[58:61]
	v_mfma_f32_16x16x32_bf16 v[50:53], v[214:217], v[174:177], v[50:53]
	v_mfma_f32_16x16x32_bf16 v[42:45], v[206:209], v[182:185], v[42:45]
	v_mfma_f32_16x16x32_bf16 v[34:37], v[214:217], v[182:185], v[34:37]
	v_mfma_f32_16x16x32_bf16 v[26:29], v[206:209], v[190:193], v[26:29]
	v_mfma_f32_16x16x32_bf16 v[18:21], v[214:217], v[190:193], v[18:21]
	v_mfma_f32_16x16x32_bf16 v[10:13], v[206:209], v[198:201], v[10:13]
	v_mfma_f32_16x16x32_bf16 v[2:5], v[214:217], v[198:201], v[2:5]
	v_mfma_f32_16x16x32_bf16 v[58:61], v[210:213], v[178:181], v[58:61]
	v_mfma_f32_16x16x32_bf16 v[50:53], v[218:221], v[178:181], v[50:53]
	v_mfma_f32_16x16x32_bf16 v[42:45], v[210:213], v[186:189], v[42:45]
	v_mfma_f32_16x16x32_bf16 v[34:37], v[218:221], v[186:189], v[34:37]
	v_mfma_f32_16x16x32_bf16 v[26:29], v[210:213], v[194:197], v[26:29]
	v_mfma_f32_16x16x32_bf16 v[18:21], v[218:221], v[194:197], v[18:21]
	v_mfma_f32_16x16x32_bf16 v[10:13], v[210:213], v[202:205], v[10:13]
	v_mfma_f32_16x16x32_bf16 v[2:5], v[218:221], v[202:205], v[2:5]
	s_barrier
	s_add_i32 s48, 0, 0x18000
	v_add_u32_e32 v102, s48, v159
	ds_read_b128 v[82:85], v102
	ds_read_b128 v[86:89], v102 offset:1024
	ds_read_b128 v[98:101], v102 offset:2048
	ds_read_b128 v[102:105], v102 offset:3072
	s_add_u32 s18, s18, 0x40000
	s_addc_u32 s19, s19, 0
	s_mov_b32 m0, s26
	v_lshl_add_u64 v[206:207], s[18:19], 0, v[152:153]
	ds_read_b128 v[174:177], v173 offset:32768
	ds_read_b128 v[178:181], v173 offset:33792
	ds_read_b128 v[182:185], v173 offset:34816
	ds_read_b128 v[186:189], v173 offset:35840
	ds_read_b128 v[190:193], v173 offset:36864
	ds_read_b128 v[194:197], v173 offset:37888
	ds_read_b128 v[198:201], v173 offset:38912
	ds_read_b128 v[202:205], v173 offset:39936
	global_load_lds_dwordx4 v[206:207], off
	v_lshl_add_u64 v[206:207], s[18:19], 0, v[148:149]
	s_mov_b32 m0, s27
	s_nop 0
	global_load_lds_dwordx4 v[206:207], off
	s_waitcnt lgkmcnt(8)
	s_barrier
	s_waitcnt lgkmcnt(0)
	v_mfma_f32_16x16x32_bf16 v[138:141], v[82:85], v[174:177], v[138:141]
	v_mfma_f32_16x16x32_bf16 v[134:137], v[98:101], v[174:177], v[134:137]
	v_mfma_f32_16x16x32_bf16 v[126:129], v[82:85], v[182:185], v[126:129]
	v_mfma_f32_16x16x32_bf16 v[118:121], v[98:101], v[182:185], v[118:121]
	v_mfma_f32_16x16x32_bf16 v[110:113], v[82:85], v[190:193], v[110:113]
	v_mfma_f32_16x16x32_bf16 v[94:97], v[98:101], v[190:193], v[94:97]
	v_mfma_f32_16x16x32_bf16 v[78:81], v[82:85], v[198:201], v[78:81]
	v_mfma_f32_16x16x32_bf16 v[70:73], v[98:101], v[198:201], v[70:73]
	v_mfma_f32_16x16x32_bf16 v[138:141], v[86:89], v[178:181], v[138:141]
	v_mfma_f32_16x16x32_bf16 v[134:137], v[102:105], v[178:181], v[134:137]
	v_mfma_f32_16x16x32_bf16 v[126:129], v[86:89], v[186:189], v[126:129]
	v_mfma_f32_16x16x32_bf16 v[118:121], v[102:105], v[186:189], v[118:121]
	v_mfma_f32_16x16x32_bf16 v[110:113], v[86:89], v[194:197], v[110:113]
	v_mfma_f32_16x16x32_bf16 v[94:97], v[102:105], v[194:197], v[94:97]
	v_mfma_f32_16x16x32_bf16 v[78:81], v[86:89], v[202:205], v[78:81]
	v_mfma_f32_16x16x32_bf16 v[70:73], v[102:105], v[202:205], v[70:73]
	s_barrier
	s_add_i32 s18, 0, 0x1c000
	s_add_i32 s19, s48, s23
	v_add_u32_e32 v158, s18, v159
	v_lshl_add_u64 v[160:161], v[160:161], 0, s[84:85]
	s_mov_b32 m0, s19
	ds_read_b128 v[206:209], v158
	ds_read_b128 v[210:213], v158 offset:1024
	ds_read_b128 v[214:217], v158 offset:2048
	ds_read_b128 v[218:221], v158 offset:3072
	global_load_lds_dwordx4 v[160:161], off
	v_lshl_add_u64 v[160:161], v[168:169], 0, s[84:85]
	s_add_i32 m0, s19, 0x2000
	s_nop 0
	global_load_lds_dwordx4 v[160:161], off
	s_barrier
	s_waitcnt lgkmcnt(0)
	v_mfma_f32_16x16x32_bf16 v[142:145], v[206:209], v[174:177], v[142:145]
	v_mfma_f32_16x16x32_bf16 v[130:133], v[214:217], v[174:177], v[130:133]
	v_mfma_f32_16x16x32_bf16 v[122:125], v[206:209], v[182:185], v[122:125]
	v_mfma_f32_16x16x32_bf16 v[114:117], v[214:217], v[182:185], v[114:117]
	v_mfma_f32_16x16x32_bf16 v[106:109], v[206:209], v[190:193], v[106:109]
	v_mfma_f32_16x16x32_bf16 v[90:93], v[214:217], v[190:193], v[90:93]
	v_mfma_f32_16x16x32_bf16 v[74:77], v[206:209], v[198:201], v[74:77]
	v_mfma_f32_16x16x32_bf16 v[66:69], v[214:217], v[198:201], v[66:69]
	v_mfma_f32_16x16x32_bf16 v[142:145], v[210:213], v[178:181], v[142:145]
	v_mfma_f32_16x16x32_bf16 v[130:133], v[218:221], v[178:181], v[130:133]
	v_mfma_f32_16x16x32_bf16 v[122:125], v[210:213], v[186:189], v[122:125]
	v_mfma_f32_16x16x32_bf16 v[114:117], v[218:221], v[186:189], v[114:117]
	v_mfma_f32_16x16x32_bf16 v[106:109], v[210:213], v[194:197], v[106:109]
	v_mfma_f32_16x16x32_bf16 v[90:93], v[218:221], v[194:197], v[90:93]
	v_mfma_f32_16x16x32_bf16 v[74:77], v[210:213], v[202:205], v[74:77]
	v_mfma_f32_16x16x32_bf16 v[66:69], v[218:221], v[202:205], v[66:69]
	s_barrier
	s_mov_b32 m0, s35
	v_lshl_add_u64 v[160:161], v[236:237], 0, s[84:85]
	ds_read_b128 v[174:177], v173 offset:49152
	ds_read_b128 v[178:181], v173 offset:50176
	ds_read_b128 v[182:185], v173 offset:51200
	ds_read_b128 v[186:189], v173 offset:52224
	ds_read_b128 v[190:193], v173 offset:53248
	ds_read_b128 v[194:197], v173 offset:54272
	ds_read_b128 v[198:201], v173 offset:55296
	ds_read_b128 v[202:205], v173 offset:56320
	global_load_lds_dwordx4 v[160:161], off
	v_lshl_add_u64 v[160:161], v[238:239], 0, s[84:85]
	s_mov_b32 m0, s38
	s_nop 0
	global_load_lds_dwordx4 v[160:161], off
	s_barrier
	s_waitcnt lgkmcnt(0)
	v_mfma_f32_16x16x32_bf16 v[62:65], v[82:85], v[174:177], v[62:65]
	v_mfma_f32_16x16x32_bf16 v[54:57], v[98:101], v[174:177], v[54:57]
	v_mfma_f32_16x16x32_bf16 v[46:49], v[82:85], v[182:185], v[46:49]
	v_mfma_f32_16x16x32_bf16 v[38:41], v[98:101], v[182:185], v[38:41]
	v_mfma_f32_16x16x32_bf16 v[30:33], v[82:85], v[190:193], v[30:33]
	v_mfma_f32_16x16x32_bf16 v[22:25], v[98:101], v[190:193], v[22:25]
	v_mfma_f32_16x16x32_bf16 v[14:17], v[82:85], v[198:201], v[14:17]
	v_mfma_f32_16x16x32_bf16 v[6:9], v[98:101], v[198:201], v[6:9]
	v_mfma_f32_16x16x32_bf16 v[62:65], v[86:89], v[178:181], v[62:65]
	v_mfma_f32_16x16x32_bf16 v[54:57], v[102:105], v[178:181], v[54:57]
	v_mfma_f32_16x16x32_bf16 v[46:49], v[86:89], v[186:189], v[46:49]
	v_mfma_f32_16x16x32_bf16 v[38:41], v[102:105], v[186:189], v[38:41]
	v_mfma_f32_16x16x32_bf16 v[30:33], v[86:89], v[194:197], v[30:33]
	v_mfma_f32_16x16x32_bf16 v[22:25], v[102:105], v[194:197], v[22:25]
	v_mfma_f32_16x16x32_bf16 v[14:17], v[86:89], v[202:205], v[14:17]
	v_mfma_f32_16x16x32_bf16 v[6:9], v[102:105], v[202:205], v[6:9]
	s_barrier
	s_add_u32 s16, s16, 0x40080
	s_addc_u32 s17, s17, 0
	s_add_i32 s18, s18, s23
	v_lshl_add_u64 v[82:83], s[16:17], 0, v[150:151]
	s_mov_b32 m0, s18
	s_nop 0
	global_load_lds_dwordx4 v[82:83], off
	v_lshl_add_u64 v[82:83], s[16:17], 0, v[146:147]
	s_add_i32 m0, s18, 0x2000
	s_nop 0
	global_load_lds_dwordx4 v[82:83], off
	s_waitcnt vmcnt(6)
	s_barrier
	v_mfma_f32_16x16x32_bf16 v[58:61], v[206:209], v[174:177], v[58:61]
	v_mfma_f32_16x16x32_bf16 v[50:53], v[214:217], v[174:177], v[50:53]
	v_mfma_f32_16x16x32_bf16 v[42:45], v[206:209], v[182:185], v[42:45]
	v_mfma_f32_16x16x32_bf16 v[34:37], v[214:217], v[182:185], v[34:37]
	v_mfma_f32_16x16x32_bf16 v[26:29], v[206:209], v[190:193], v[26:29]
	v_mfma_f32_16x16x32_bf16 v[18:21], v[214:217], v[190:193], v[18:21]
	v_mfma_f32_16x16x32_bf16 v[10:13], v[206:209], v[198:201], v[10:13]
	v_mfma_f32_16x16x32_bf16 v[2:5], v[214:217], v[198:201], v[2:5]
	v_mfma_f32_16x16x32_bf16 v[58:61], v[210:213], v[178:181], v[58:61]
	v_mfma_f32_16x16x32_bf16 v[50:53], v[218:221], v[178:181], v[50:53]
	v_mfma_f32_16x16x32_bf16 v[42:45], v[210:213], v[186:189], v[42:45]
	v_mfma_f32_16x16x32_bf16 v[34:37], v[218:221], v[186:189], v[34:37]
	v_mfma_f32_16x16x32_bf16 v[26:29], v[210:213], v[194:197], v[26:29]
	v_mfma_f32_16x16x32_bf16 v[18:21], v[218:221], v[194:197], v[18:21]
	v_mfma_f32_16x16x32_bf16 v[10:13], v[210:213], v[202:205], v[10:13]
	v_mfma_f32_16x16x32_bf16 v[2:5], v[218:221], v[202:205], v[2:5]
	s_barrier
	s_add_u32 s14, s14, 0x100
	s_addc_u32 s15, s15, 0
	s_add_u32 s45, s45, 0x100
	s_addc_u32 s46, s46, 0
	s_cmp_ge_i32 s47, s30
	s_mov_b32 s16, s47
	s_cbranch_scc0 .LBB0_563
	s_branch .LBB0_558

.LBB0_592:
	s_add_i32 s51, s12, 2
	s_add_u32 s13, s10, 0x4000
	s_addc_u32 s14, s11, 0
	s_cmp_eq_u32 s41, s12
	s_cselect_b32 s16, s0, s13
	s_cselect_b32 s17, s1, s14
	s_cselect_b32 s12, s2, s49
	s_cselect_b32 s13, s3, s50
	s_add_u32 s14, s16, 0x8000
	s_addc_u32 s15, s17, 0
	s_add_i32 s52, 0, 0x10000
	v_add_u32_e32 v94, s52, v237
	ds_read_b128 v[66:69], v94
	ds_read_b128 v[70:73], v94 offset:1024
	ds_read_b128 v[90:93], v94 offset:2048
	ds_read_b128 v[94:97], v94 offset:3072
	v_lshl_add_u64 v[168:169], s[10:11], 0, v[176:177]
	s_add_i32 m0, s22, 0xc000
	ds_read_b128 v[146:149], v238
	ds_read_b128 v[150:153], v238 offset:1024
	ds_read_b128 v[154:157], v238 offset:2048
	ds_read_b128 v[180:183], v238 offset:3072
	ds_read_b128 v[184:187], v238 offset:4096
	ds_read_b128 v[188:191], v238 offset:5120
	ds_read_b128 v[192:195], v238 offset:6144
	ds_read_b128 v[196:199], v238 offset:7168
	global_load_lds_dwordx4 v[168:169], off
	v_lshl_add_u64 v[168:169], s[10:11], 0, v[178:179]
	s_add_i32 m0, s22, 0xe000
	s_nop 0
	global_load_lds_dwordx4 v[168:169], off
	s_waitcnt lgkmcnt(8)
	s_barrier
	s_waitcnt lgkmcnt(0)
	v_mfma_f32_16x16x32_bf16 v[138:141], v[66:69], v[146:149], v[138:141]
	v_mfma_f32_16x16x32_bf16 v[142:145], v[90:93], v[146:149], v[142:145]
	v_mfma_f32_16x16x32_bf16 v[126:129], v[66:69], v[154:157], v[126:129]
	v_mfma_f32_16x16x32_bf16 v[122:125], v[90:93], v[154:157], v[122:125]
	v_mfma_f32_16x16x32_bf16 v[110:113], v[66:69], v[184:187], v[110:113]
	v_mfma_f32_16x16x32_bf16 v[106:109], v[90:93], v[184:187], v[106:109]
	v_mfma_f32_16x16x32_bf16 v[86:89], v[66:69], v[192:195], v[86:89]
	v_mfma_f32_16x16x32_bf16 v[82:85], v[90:93], v[192:195], v[82:85]
	v_mfma_f32_16x16x32_bf16 v[138:141], v[70:73], v[150:153], v[138:141]
	v_mfma_f32_16x16x32_bf16 v[142:145], v[94:97], v[150:153], v[142:145]
	v_mfma_f32_16x16x32_bf16 v[126:129], v[70:73], v[180:183], v[126:129]
	v_mfma_f32_16x16x32_bf16 v[122:125], v[94:97], v[180:183], v[122:125]
	v_mfma_f32_16x16x32_bf16 v[110:113], v[70:73], v[188:191], v[110:113]
	v_mfma_f32_16x16x32_bf16 v[106:109], v[94:97], v[188:191], v[106:109]
	v_mfma_f32_16x16x32_bf16 v[86:89], v[70:73], v[196:199], v[86:89]
	v_mfma_f32_16x16x32_bf16 v[82:85], v[94:97], v[196:199], v[82:85]
	s_barrier
	s_add_i32 s54, 0, 0x14000
	v_add_u32_e32 v168, s54, v237
	s_add_i32 s52, s52, s21
	ds_read_b128 v[200:203], v168
	ds_read_b128 v[204:207], v168 offset:1024
	ds_read_b128 v[208:211], v168 offset:2048
	ds_read_b128 v[212:215], v168 offset:3072
	v_lshl_add_u64 v[168:169], s[12:13], 0, v[160:161]
	s_mov_b32 m0, s52
	v_lshl_add_u64 v[216:217], s[12:13], 0, v[174:175]
	global_load_lds_dwordx4 v[168:169], off
	s_add_i32 m0, s52, 0x2000
	s_nop 0
	global_load_lds_dwordx4 v[216:217], off
	s_barrier
	s_waitcnt lgkmcnt(0)
	v_mfma_f32_16x16x32_bf16 v[134:137], v[200:203], v[146:149], v[134:137]
	v_mfma_f32_16x16x32_bf16 v[130:133], v[208:211], v[146:149], v[130:133]
	v_mfma_f32_16x16x32_bf16 v[118:121], v[200:203], v[154:157], v[118:121]
	v_mfma_f32_16x16x32_bf16 v[114:117], v[208:211], v[154:157], v[114:117]
	v_mfma_f32_16x16x32_bf16 v[102:105], v[200:203], v[184:187], v[102:105]
	v_mfma_f32_16x16x32_bf16 v[98:101], v[208:211], v[184:187], v[98:101]
	v_mfma_f32_16x16x32_bf16 v[78:81], v[200:203], v[192:195], v[78:81]
	v_mfma_f32_16x16x32_bf16 v[74:77], v[208:211], v[192:195], v[74:77]
	v_mfma_f32_16x16x32_bf16 v[134:137], v[204:207], v[150:153], v[134:137]
	v_mfma_f32_16x16x32_bf16 v[130:133], v[212:215], v[150:153], v[130:133]
	v_mfma_f32_16x16x32_bf16 v[118:121], v[204:207], v[180:183], v[118:121]
	v_mfma_f32_16x16x32_bf16 v[114:117], v[212:215], v[180:183], v[114:117]
	v_mfma_f32_16x16x32_bf16 v[102:105], v[204:207], v[188:191], v[102:105]
	v_mfma_f32_16x16x32_bf16 v[98:101], v[212:215], v[188:191], v[98:101]
	v_mfma_f32_16x16x32_bf16 v[78:81], v[204:207], v[196:199], v[78:81]
	v_mfma_f32_16x16x32_bf16 v[74:77], v[212:215], v[196:199], v[74:77]
	s_barrier
	s_mov_b32 m0, s22
	v_lshl_add_u64 v[218:219], s[16:17], 0, v[158:159]
	ds_read_b128 v[146:149], v238 offset:16384
	ds_read_b128 v[150:153], v238 offset:17408
	ds_read_b128 v[154:157], v238 offset:18432
	ds_read_b128 v[180:183], v238 offset:19456
	ds_read_b128 v[184:187], v238 offset:20480
	ds_read_b128 v[188:191], v238 offset:21504
	ds_read_b128 v[192:195], v238 offset:22528
	ds_read_b128 v[196:199], v238 offset:23552
	global_load_lds_dwordx4 v[218:219], off
	v_lshl_add_u64 v[218:219], s[16:17], 0, v[172:173]
	s_mov_b32 m0, s23
	s_nop 0
	global_load_lds_dwordx4 v[218:219], off
	s_barrier
	s_waitcnt lgkmcnt(0)
	v_mfma_f32_16x16x32_bf16 v[62:65], v[66:69], v[146:149], v[62:65]
	v_mfma_f32_16x16x32_bf16 v[58:61], v[90:93], v[146:149], v[58:61]
	v_mfma_f32_16x16x32_bf16 v[46:49], v[66:69], v[154:157], v[46:49]
	v_mfma_f32_16x16x32_bf16 v[42:45], v[90:93], v[154:157], v[42:45]
	v_mfma_f32_16x16x32_bf16 v[30:33], v[66:69], v[184:187], v[30:33]
	v_mfma_f32_16x16x32_bf16 v[26:29], v[90:93], v[184:187], v[26:29]
	v_mfma_f32_16x16x32_bf16 v[14:17], v[66:69], v[192:195], v[14:17]
	v_mfma_f32_16x16x32_bf16 v[10:13], v[90:93], v[192:195], v[10:13]
	v_mfma_f32_16x16x32_bf16 v[62:65], v[70:73], v[150:153], v[62:65]
	v_mfma_f32_16x16x32_bf16 v[58:61], v[94:97], v[150:153], v[58:61]
	v_mfma_f32_16x16x32_bf16 v[46:49], v[70:73], v[180:183], v[46:49]
	v_mfma_f32_16x16x32_bf16 v[42:45], v[94:97], v[180:183], v[42:45]
	v_mfma_f32_16x16x32_bf16 v[30:33], v[70:73], v[188:191], v[30:33]
	v_mfma_f32_16x16x32_bf16 v[26:29], v[94:97], v[188:191], v[26:29]
	v_mfma_f32_16x16x32_bf16 v[14:17], v[70:73], v[196:199], v[14:17]
	v_mfma_f32_16x16x32_bf16 v[10:13], v[94:97], v[196:199], v[10:13]
	s_barrier
	s_add_u32 s52, s12, 0xb0000
	s_addc_u32 s53, s13, 0
	s_add_i32 s54, s54, s21
	v_lshl_add_u64 v[66:67], s[52:53], 0, v[160:161]
	s_mov_b32 m0, s54
	s_nop 0
	global_load_lds_dwordx4 v[66:67], off
	v_lshl_add_u64 v[66:67], s[52:53], 0, v[174:175]
	s_add_i32 m0, s54, 0x2000
	s_nop 0
	global_load_lds_dwordx4 v[66:67], off
	s_waitcnt vmcnt(6)
	s_barrier
	v_mfma_f32_16x16x32_bf16 v[54:57], v[200:203], v[146:149], v[54:57]
	v_mfma_f32_16x16x32_bf16 v[50:53], v[208:211], v[146:149], v[50:53]
	v_mfma_f32_16x16x32_bf16 v[38:41], v[200:203], v[154:157], v[38:41]
	v_mfma_f32_16x16x32_bf16 v[34:37], v[208:211], v[154:157], v[34:37]
	v_mfma_f32_16x16x32_bf16 v[22:25], v[200:203], v[184:187], v[22:25]
	v_mfma_f32_16x16x32_bf16 v[18:21], v[208:211], v[184:187], v[18:21]
	v_mfma_f32_16x16x32_bf16 v[6:9], v[200:203], v[192:195], v[6:9]
	v_mfma_f32_16x16x32_bf16 v[2:5], v[208:211], v[192:195], v[2:5]
	v_mfma_f32_16x16x32_bf16 v[54:57], v[204:207], v[150:153], v[54:57]
	v_mfma_f32_16x16x32_bf16 v[50:53], v[212:215], v[150:153], v[50:53]
	v_mfma_f32_16x16x32_bf16 v[38:41], v[204:207], v[180:183], v[38:41]
	v_mfma_f32_16x16x32_bf16 v[34:37], v[212:215], v[180:183], v[34:37]
	v_mfma_f32_16x16x32_bf16 v[22:25], v[204:207], v[188:191], v[22:25]
	v_mfma_f32_16x16x32_bf16 v[18:21], v[212:215], v[188:191], v[18:21]
	v_mfma_f32_16x16x32_bf16 v[6:9], v[204:207], v[196:199], v[6:9]
	v_mfma_f32_16x16x32_bf16 v[2:5], v[212:215], v[196:199], v[2:5]
	s_barrier
	s_add_i32 s52, 0, 0x18000
	v_add_u32_e32 v94, s52, v237
	ds_read_b128 v[66:69], v94
	ds_read_b128 v[70:73], v94 offset:1024
	ds_read_b128 v[90:93], v94 offset:2048
	ds_read_b128 v[94:97], v94 offset:3072
	s_add_u32 s16, s16, 0x4000
	s_addc_u32 s17, s17, 0
	s_mov_b32 m0, s24
	v_lshl_add_u64 v[200:201], s[16:17], 0, v[158:159]
	ds_read_b128 v[146:149], v238 offset:32768
	ds_read_b128 v[150:153], v238 offset:33792
	ds_read_b128 v[154:157], v238 offset:34816
	ds_read_b128 v[180:183], v238 offset:35840
	ds_read_b128 v[184:187], v238 offset:36864
	ds_read_b128 v[188:191], v238 offset:37888
	ds_read_b128 v[192:195], v238 offset:38912
	ds_read_b128 v[196:199], v238 offset:39936
	global_load_lds_dwordx4 v[200:201], off
	v_lshl_add_u64 v[200:201], s[16:17], 0, v[172:173]
	s_mov_b32 m0, s25
	s_nop 0
	global_load_lds_dwordx4 v[200:201], off
	s_waitcnt lgkmcnt(8)
	s_barrier
	s_waitcnt lgkmcnt(0)
	v_mfma_f32_16x16x32_bf16 v[138:141], v[66:69], v[146:149], v[138:141]
	v_mfma_f32_16x16x32_bf16 v[142:145], v[90:93], v[146:149], v[142:145]
	v_mfma_f32_16x16x32_bf16 v[126:129], v[66:69], v[154:157], v[126:129]
	v_mfma_f32_16x16x32_bf16 v[122:125], v[90:93], v[154:157], v[122:125]
	v_mfma_f32_16x16x32_bf16 v[110:113], v[66:69], v[184:187], v[110:113]
	v_mfma_f32_16x16x32_bf16 v[106:109], v[90:93], v[184:187], v[106:109]
	v_mfma_f32_16x16x32_bf16 v[86:89], v[66:69], v[192:195], v[86:89]
	v_mfma_f32_16x16x32_bf16 v[82:85], v[90:93], v[192:195], v[82:85]
	v_mfma_f32_16x16x32_bf16 v[138:141], v[70:73], v[150:153], v[138:141]
	v_mfma_f32_16x16x32_bf16 v[142:145], v[94:97], v[150:153], v[142:145]
	v_mfma_f32_16x16x32_bf16 v[126:129], v[70:73], v[180:183], v[126:129]
	v_mfma_f32_16x16x32_bf16 v[122:125], v[94:97], v[180:183], v[122:125]
	v_mfma_f32_16x16x32_bf16 v[110:113], v[70:73], v[188:191], v[110:113]
	v_mfma_f32_16x16x32_bf16 v[106:109], v[94:97], v[188:191], v[106:109]
	v_mfma_f32_16x16x32_bf16 v[86:89], v[70:73], v[196:199], v[86:89]
	v_mfma_f32_16x16x32_bf16 v[82:85], v[94:97], v[196:199], v[82:85]
	s_barrier
	s_add_i32 s16, 0, 0x1c000
	s_add_i32 s17, s52, s21
	v_add_u32_e32 v212, s16, v237
	v_lshl_add_u64 v[168:169], v[168:169], 0, s[84:85]
	s_mov_b32 m0, s17
	ds_read_b128 v[200:203], v212
	ds_read_b128 v[204:207], v212 offset:1024
	ds_read_b128 v[208:211], v212 offset:2048
	ds_read_b128 v[212:215], v212 offset:3072
	global_load_lds_dwordx4 v[168:169], off
	v_lshl_add_u64 v[168:169], v[216:217], 0, s[84:85]
	s_add_i32 m0, s17, 0x2000
	s_nop 0
	global_load_lds_dwordx4 v[168:169], off
	s_barrier
	s_waitcnt lgkmcnt(0)
	v_mfma_f32_16x16x32_bf16 v[134:137], v[200:203], v[146:149], v[134:137]
	v_mfma_f32_16x16x32_bf16 v[130:133], v[208:211], v[146:149], v[130:133]
	v_mfma_f32_16x16x32_bf16 v[118:121], v[200:203], v[154:157], v[118:121]
	v_mfma_f32_16x16x32_bf16 v[114:117], v[208:211], v[154:157], v[114:117]
	v_mfma_f32_16x16x32_bf16 v[102:105], v[200:203], v[184:187], v[102:105]
	v_mfma_f32_16x16x32_bf16 v[98:101], v[208:211], v[184:187], v[98:101]
	v_mfma_f32_16x16x32_bf16 v[78:81], v[200:203], v[192:195], v[78:81]
	v_mfma_f32_16x16x32_bf16 v[74:77], v[208:211], v[192:195], v[74:77]
	v_mfma_f32_16x16x32_bf16 v[134:137], v[204:207], v[150:153], v[134:137]
	v_mfma_f32_16x16x32_bf16 v[130:133], v[212:215], v[150:153], v[130:133]
	v_mfma_f32_16x16x32_bf16 v[118:121], v[204:207], v[180:183], v[118:121]
	v_mfma_f32_16x16x32_bf16 v[114:117], v[212:215], v[180:183], v[114:117]
	v_mfma_f32_16x16x32_bf16 v[102:105], v[204:207], v[188:191], v[102:105]
	v_mfma_f32_16x16x32_bf16 v[98:101], v[212:215], v[188:191], v[98:101]
	v_mfma_f32_16x16x32_bf16 v[78:81], v[204:207], v[196:199], v[78:81]
	v_mfma_f32_16x16x32_bf16 v[74:77], v[212:215], v[196:199], v[74:77]
	s_barrier
	s_mov_b32 m0, s39
	v_lshl_add_u64 v[168:169], s[14:15], 0, v[158:159]
	ds_read_b128 v[146:149], v238 offset:49152
	ds_read_b128 v[150:153], v238 offset:50176
	ds_read_b128 v[154:157], v238 offset:51200
	ds_read_b128 v[180:183], v238 offset:52224
	ds_read_b128 v[184:187], v238 offset:53248
	ds_read_b128 v[188:191], v238 offset:54272
	ds_read_b128 v[192:195], v238 offset:55296
	ds_read_b128 v[196:199], v238 offset:56320
	global_load_lds_dwordx4 v[168:169], off
	v_lshl_add_u64 v[168:169], s[14:15], 0, v[172:173]
	s_mov_b32 m0, s40
	s_nop 0
	global_load_lds_dwordx4 v[168:169], off
	s_barrier
	s_waitcnt lgkmcnt(0)
	v_mfma_f32_16x16x32_bf16 v[62:65], v[66:69], v[146:149], v[62:65]
	v_mfma_f32_16x16x32_bf16 v[58:61], v[90:93], v[146:149], v[58:61]
	v_mfma_f32_16x16x32_bf16 v[46:49], v[66:69], v[154:157], v[46:49]
	v_mfma_f32_16x16x32_bf16 v[42:45], v[90:93], v[154:157], v[42:45]
	v_mfma_f32_16x16x32_bf16 v[30:33], v[66:69], v[184:187], v[30:33]
	v_mfma_f32_16x16x32_bf16 v[26:29], v[90:93], v[184:187], v[26:29]
	v_mfma_f32_16x16x32_bf16 v[14:17], v[66:69], v[192:195], v[14:17]
	v_mfma_f32_16x16x32_bf16 v[10:13], v[90:93], v[192:195], v[10:13]
	v_mfma_f32_16x16x32_bf16 v[62:65], v[70:73], v[150:153], v[62:65]
	v_mfma_f32_16x16x32_bf16 v[58:61], v[94:97], v[150:153], v[58:61]
	v_mfma_f32_16x16x32_bf16 v[46:49], v[70:73], v[180:183], v[46:49]
	v_mfma_f32_16x16x32_bf16 v[42:45], v[94:97], v[180:183], v[42:45]
	v_mfma_f32_16x16x32_bf16 v[30:33], v[70:73], v[188:191], v[30:33]
	v_mfma_f32_16x16x32_bf16 v[26:29], v[94:97], v[188:191], v[26:29]
	v_mfma_f32_16x16x32_bf16 v[14:17], v[70:73], v[196:199], v[14:17]
	v_mfma_f32_16x16x32_bf16 v[10:13], v[94:97], v[196:199], v[10:13]
	s_barrier
	s_add_u32 s12, s12, 0xb0080
	s_addc_u32 s13, s13, 0
	s_add_i32 s14, s16, s21
	v_lshl_add_u64 v[66:67], s[12:13], 0, v[160:161]
	s_mov_b32 m0, s14
	s_nop 0
	global_load_lds_dwordx4 v[66:67], off
	v_lshl_add_u64 v[66:67], s[12:13], 0, v[174:175]
	s_add_i32 m0, s14, 0x2000
	s_nop 0
	global_load_lds_dwordx4 v[66:67], off
	s_waitcnt vmcnt(6)
	s_barrier
	v_mfma_f32_16x16x32_bf16 v[54:57], v[200:203], v[146:149], v[54:57]
	v_mfma_f32_16x16x32_bf16 v[50:53], v[208:211], v[146:149], v[50:53]
	v_mfma_f32_16x16x32_bf16 v[38:41], v[200:203], v[154:157], v[38:41]
	v_mfma_f32_16x16x32_bf16 v[34:37], v[208:211], v[154:157], v[34:37]
	v_mfma_f32_16x16x32_bf16 v[22:25], v[200:203], v[184:187], v[22:25]
	v_mfma_f32_16x16x32_bf16 v[18:21], v[208:211], v[184:187], v[18:21]
	v_mfma_f32_16x16x32_bf16 v[6:9], v[200:203], v[192:195], v[6:9]
	v_mfma_f32_16x16x32_bf16 v[2:5], v[208:211], v[192:195], v[2:5]
	v_mfma_f32_16x16x32_bf16 v[54:57], v[204:207], v[150:153], v[54:57]
	v_mfma_f32_16x16x32_bf16 v[50:53], v[212:215], v[150:153], v[50:53]
	v_mfma_f32_16x16x32_bf16 v[38:41], v[204:207], v[180:183], v[38:41]
	v_mfma_f32_16x16x32_bf16 v[34:37], v[212:215], v[180:183], v[34:37]
	v_mfma_f32_16x16x32_bf16 v[22:25], v[204:207], v[188:191], v[22:25]
	v_mfma_f32_16x16x32_bf16 v[18:21], v[212:215], v[188:191], v[18:21]
	v_mfma_f32_16x16x32_bf16 v[6:9], v[204:207], v[196:199], v[6:9]
	v_mfma_f32_16x16x32_bf16 v[2:5], v[212:215], v[196:199], v[2:5]
	s_barrier
	s_add_u32 s49, s49, 0x100
	s_addc_u32 s50, s50, 0
	s_add_u32 s10, s10, 0x10000
	s_addc_u32 s11, s11, 0
	s_cmp_ge_i32 s51, s34
	s_mov_b32 s12, s51
	s_cbranch_scc0 .LBB0_592

.LBB0_624:
	s_add_i32 s47, s16, 2
	s_add_u32 s17, s14, 0xfffc0080
	s_addc_u32 s18, s15, -1
	s_add_i32 s48, 0, 0x10000
	v_add_u32_e32 v102, s48, v171
	ds_read_b128 v[82:85], v102
	ds_read_b128 v[86:89], v102 offset:1024
	ds_read_b128 v[98:101], v102 offset:2048
	ds_read_b128 v[102:105], v102 offset:3072
	s_cmp_eq_u32 s39, s16
	s_cselect_b32 s16, s44, s45
	s_cselect_b32 s19, s5, s18
	s_cselect_b32 s18, s7, s17
	s_cselect_b32 s17, s43, s46
	v_lshl_add_u64 v[160:161], s[14:15], 0, v[154:155]
	s_add_i32 m0, s13, 0xc000
	ds_read_b128 v[174:177], v173
	ds_read_b128 v[178:181], v173 offset:1024
	ds_read_b128 v[182:185], v173 offset:2048
	ds_read_b128 v[186:189], v173 offset:3072
	ds_read_b128 v[190:193], v173 offset:4096
	ds_read_b128 v[194:197], v173 offset:5120
	ds_read_b128 v[198:201], v173 offset:6144
	ds_read_b128 v[202:205], v173 offset:7168
	global_load_lds_dwordx4 v[160:161], off
	v_lshl_add_u64 v[160:161], s[14:15], 0, v[156:157]
	s_add_i32 m0, s13, 0xe000
	s_nop 0
	global_load_lds_dwordx4 v[160:161], off
	s_waitcnt lgkmcnt(8)
	s_barrier
	s_waitcnt lgkmcnt(0)
	v_mfma_f32_16x16x32_bf16 v[138:141], v[82:85], v[174:177], v[138:141]
	v_mfma_f32_16x16x32_bf16 v[134:137], v[98:101], v[174:177], v[134:137]
	v_mfma_f32_16x16x32_bf16 v[126:129], v[82:85], v[182:185], v[126:129]
	v_mfma_f32_16x16x32_bf16 v[118:121], v[98:101], v[182:185], v[118:121]
	v_mfma_f32_16x16x32_bf16 v[110:113], v[82:85], v[190:193], v[110:113]
	v_mfma_f32_16x16x32_bf16 v[94:97], v[98:101], v[190:193], v[94:97]
	v_mfma_f32_16x16x32_bf16 v[78:81], v[82:85], v[198:201], v[78:81]
	v_mfma_f32_16x16x32_bf16 v[70:73], v[98:101], v[198:201], v[70:73]
	v_mfma_f32_16x16x32_bf16 v[138:141], v[86:89], v[178:181], v[138:141]
	v_mfma_f32_16x16x32_bf16 v[134:137], v[102:105], v[178:181], v[134:137]
	v_mfma_f32_16x16x32_bf16 v[126:129], v[86:89], v[186:189], v[126:129]
	v_mfma_f32_16x16x32_bf16 v[118:121], v[102:105], v[186:189], v[118:121]
	v_mfma_f32_16x16x32_bf16 v[110:113], v[86:89], v[194:197], v[110:113]
	v_mfma_f32_16x16x32_bf16 v[94:97], v[102:105], v[194:197], v[94:97]
	v_mfma_f32_16x16x32_bf16 v[78:81], v[86:89], v[202:205], v[78:81]
	v_mfma_f32_16x16x32_bf16 v[70:73], v[102:105], v[202:205], v[70:73]
	s_barrier
	s_add_i32 s50, 0, 0x14000
	s_add_i32 s48, s48, s23
	v_add_u32_e32 v158, s50, v171
	v_lshl_add_u64 v[160:161], s[16:17], 0, v[150:151]
	s_mov_b32 m0, s48
	ds_read_b128 v[206:209], v158
	ds_read_b128 v[210:213], v158 offset:1024
	ds_read_b128 v[214:217], v158 offset:2048
	ds_read_b128 v[218:221], v158 offset:3072
	global_load_lds_dwordx4 v[160:161], off
	v_lshl_add_u64 v[236:237], s[16:17], 0, v[146:147]
	s_add_i32 m0, s48, 0x2000
	s_nop 0
	global_load_lds_dwordx4 v[236:237], off
	s_barrier
	s_waitcnt lgkmcnt(0)
	v_mfma_f32_16x16x32_bf16 v[142:145], v[206:209], v[174:177], v[142:145]
	v_mfma_f32_16x16x32_bf16 v[130:133], v[214:217], v[174:177], v[130:133]
	v_mfma_f32_16x16x32_bf16 v[122:125], v[206:209], v[182:185], v[122:125]
	v_mfma_f32_16x16x32_bf16 v[114:117], v[214:217], v[182:185], v[114:117]
	v_mfma_f32_16x16x32_bf16 v[106:109], v[206:209], v[190:193], v[106:109]
	v_mfma_f32_16x16x32_bf16 v[90:93], v[214:217], v[190:193], v[90:93]
	v_mfma_f32_16x16x32_bf16 v[74:77], v[206:209], v[198:201], v[74:77]
	v_mfma_f32_16x16x32_bf16 v[66:69], v[214:217], v[198:201], v[66:69]
	v_mfma_f32_16x16x32_bf16 v[142:145], v[210:213], v[178:181], v[142:145]
	v_mfma_f32_16x16x32_bf16 v[130:133], v[218:221], v[178:181], v[130:133]
	v_mfma_f32_16x16x32_bf16 v[122:125], v[210:213], v[186:189], v[122:125]
	v_mfma_f32_16x16x32_bf16 v[114:117], v[218:221], v[186:189], v[114:117]
	v_mfma_f32_16x16x32_bf16 v[106:109], v[210:213], v[194:197], v[106:109]
	v_mfma_f32_16x16x32_bf16 v[90:93], v[218:221], v[194:197], v[90:93]
	v_mfma_f32_16x16x32_bf16 v[74:77], v[210:213], v[202:205], v[74:77]
	v_mfma_f32_16x16x32_bf16 v[66:69], v[218:221], v[202:205], v[66:69]
	s_barrier
	s_mov_b32 m0, s13
	v_lshl_add_u64 v[238:239], s[18:19], 0, v[152:153]
	ds_read_b128 v[174:177], v173 offset:16384
	ds_read_b128 v[178:181], v173 offset:17408
	ds_read_b128 v[182:185], v173 offset:18432
	ds_read_b128 v[186:189], v173 offset:19456
	ds_read_b128 v[190:193], v173 offset:20480
	ds_read_b128 v[194:197], v173 offset:21504
	ds_read_b128 v[198:201], v173 offset:22528
	ds_read_b128 v[202:205], v173 offset:23552
	global_load_lds_dwordx4 v[238:239], off
	v_lshl_add_u64 v[240:241], s[18:19], 0, v[148:149]
	s_mov_b32 m0, s25
	s_nop 0
	global_load_lds_dwordx4 v[240:241], off
	s_barrier
	s_waitcnt lgkmcnt(0)
	v_mfma_f32_16x16x32_bf16 v[62:65], v[82:85], v[174:177], v[62:65]
	v_mfma_f32_16x16x32_bf16 v[54:57], v[98:101], v[174:177], v[54:57]
	v_mfma_f32_16x16x32_bf16 v[46:49], v[82:85], v[182:185], v[46:49]
	v_mfma_f32_16x16x32_bf16 v[38:41], v[98:101], v[182:185], v[38:41]
	v_mfma_f32_16x16x32_bf16 v[30:33], v[82:85], v[190:193], v[30:33]
	v_mfma_f32_16x16x32_bf16 v[22:25], v[98:101], v[190:193], v[22:25]
	v_mfma_f32_16x16x32_bf16 v[14:17], v[82:85], v[198:201], v[14:17]
	v_mfma_f32_16x16x32_bf16 v[6:9], v[98:101], v[198:201], v[6:9]
	v_mfma_f32_16x16x32_bf16 v[62:65], v[86:89], v[178:181], v[62:65]
	v_mfma_f32_16x16x32_bf16 v[54:57], v[102:105], v[178:181], v[54:57]
	v_mfma_f32_16x16x32_bf16 v[46:49], v[86:89], v[186:189], v[46:49]
	v_mfma_f32_16x16x32_bf16 v[38:41], v[102:105], v[186:189], v[38:41]
	v_mfma_f32_16x16x32_bf16 v[30:33], v[86:89], v[194:197], v[30:33]
	v_mfma_f32_16x16x32_bf16 v[22:25], v[102:105], v[194:197], v[22:25]
	v_mfma_f32_16x16x32_bf16 v[14:17], v[86:89], v[202:205], v[14:17]
	v_mfma_f32_16x16x32_bf16 v[6:9], v[102:105], v[202:205], v[6:9]
	s_barrier
	s_add_u32 s48, s16, 0x40000
	s_addc_u32 s49, s17, 0
	s_add_i32 s50, s50, s23
	v_lshl_add_u64 v[82:83], s[48:49], 0, v[150:151]
	s_mov_b32 m0, s50
	s_nop 0
	global_load_lds_dwordx4 v[82:83], off
	v_lshl_add_u64 v[82:83], s[48:49], 0, v[146:147]
	s_add_i32 m0, s50, 0x2000
	s_nop 0
	global_load_lds_dwordx4 v[82:83], off
	s_waitcnt vmcnt(6)
	s_barrier
	v_mfma_f32_16x16x32_bf16 v[58:61], v[206:209], v[174:177], v[58:61]
	v_mfma_f32_16x16x32_bf16 v[50:53], v[214:217], v[174:177], v[50:53]
	v_mfma_f32_16x16x32_bf16 v[42:45], v[206:209], v[182:185], v[42:45]
	v_mfma_f32_16x16x32_bf16 v[34:37], v[214:217], v[182:185], v[34:37]
	v_mfma_f32_16x16x32_bf16 v[26:29], v[206:209], v[190:193], v[26:29]
	v_mfma_f32_16x16x32_bf16 v[18:21], v[214:217], v[190:193], v[18:21]
	v_mfma_f32_16x16x32_bf16 v[10:13], v[206:209], v[198:201], v[10:13]
	v_mfma_f32_16x16x32_bf16 v[2:5], v[214:217], v[198:201], v[2:5]
	v_mfma_f32_16x16x32_bf16 v[58:61], v[210:213], v[178:181], v[58:61]
	v_mfma_f32_16x16x32_bf16 v[50:53], v[218:221], v[178:181], v[50:53]
	v_mfma_f32_16x16x32_bf16 v[42:45], v[210:213], v[186:189], v[42:45]
	v_mfma_f32_16x16x32_bf16 v[34:37], v[218:221], v[186:189], v[34:37]
	v_mfma_f32_16x16x32_bf16 v[26:29], v[210:213], v[194:197], v[26:29]
	v_mfma_f32_16x16x32_bf16 v[18:21], v[218:221], v[194:197], v[18:21]
	v_mfma_f32_16x16x32_bf16 v[10:13], v[210:213], v[202:205], v[10:13]
	v_mfma_f32_16x16x32_bf16 v[2:5], v[218:221], v[202:205], v[2:5]
	s_barrier
	s_add_i32 s48, 0, 0x18000
	v_add_u32_e32 v102, s48, v171
	ds_read_b128 v[82:85], v102
	ds_read_b128 v[86:89], v102 offset:1024
	ds_read_b128 v[98:101], v102 offset:2048
	ds_read_b128 v[102:105], v102 offset:3072
	s_add_u32 s18, s18, 0x40000
	s_addc_u32 s19, s19, 0
	s_mov_b32 m0, s26
	v_lshl_add_u64 v[206:207], s[18:19], 0, v[152:153]
	ds_read_b128 v[174:177], v173 offset:32768
	ds_read_b128 v[178:181], v173 offset:33792
	ds_read_b128 v[182:185], v173 offset:34816
	ds_read_b128 v[186:189], v173 offset:35840
	ds_read_b128 v[190:193], v173 offset:36864
	ds_read_b128 v[194:197], v173 offset:37888
	ds_read_b128 v[198:201], v173 offset:38912
	ds_read_b128 v[202:205], v173 offset:39936
	global_load_lds_dwordx4 v[206:207], off
	v_lshl_add_u64 v[206:207], s[18:19], 0, v[148:149]
	s_mov_b32 m0, s27
	s_nop 0
	global_load_lds_dwordx4 v[206:207], off
	s_waitcnt lgkmcnt(8)
	s_barrier
	s_waitcnt lgkmcnt(0)
	v_mfma_f32_16x16x32_bf16 v[138:141], v[82:85], v[174:177], v[138:141]
	v_mfma_f32_16x16x32_bf16 v[134:137], v[98:101], v[174:177], v[134:137]
	v_mfma_f32_16x16x32_bf16 v[126:129], v[82:85], v[182:185], v[126:129]
	v_mfma_f32_16x16x32_bf16 v[118:121], v[98:101], v[182:185], v[118:121]
	v_mfma_f32_16x16x32_bf16 v[110:113], v[82:85], v[190:193], v[110:113]
	v_mfma_f32_16x16x32_bf16 v[94:97], v[98:101], v[190:193], v[94:97]
	v_mfma_f32_16x16x32_bf16 v[78:81], v[82:85], v[198:201], v[78:81]
	v_mfma_f32_16x16x32_bf16 v[70:73], v[98:101], v[198:201], v[70:73]
	v_mfma_f32_16x16x32_bf16 v[138:141], v[86:89], v[178:181], v[138:141]
	v_mfma_f32_16x16x32_bf16 v[134:137], v[102:105], v[178:181], v[134:137]
	v_mfma_f32_16x16x32_bf16 v[126:129], v[86:89], v[186:189], v[126:129]
	v_mfma_f32_16x16x32_bf16 v[118:121], v[102:105], v[186:189], v[118:121]
	v_mfma_f32_16x16x32_bf16 v[110:113], v[86:89], v[194:197], v[110:113]
	v_mfma_f32_16x16x32_bf16 v[94:97], v[102:105], v[194:197], v[94:97]
	v_mfma_f32_16x16x32_bf16 v[78:81], v[86:89], v[202:205], v[78:81]
	v_mfma_f32_16x16x32_bf16 v[70:73], v[102:105], v[202:205], v[70:73]
	s_barrier
	s_add_i32 s18, 0, 0x1c000
	s_add_i32 s19, s48, s23
	v_add_u32_e32 v158, s18, v171
	v_lshl_add_u64 v[160:161], v[160:161], 0, s[84:85]
	s_mov_b32 m0, s19
	ds_read_b128 v[206:209], v158
	ds_read_b128 v[210:213], v158 offset:1024
	ds_read_b128 v[214:217], v158 offset:2048
	ds_read_b128 v[218:221], v158 offset:3072
	global_load_lds_dwordx4 v[160:161], off
	v_lshl_add_u64 v[160:161], v[236:237], 0, s[84:85]
	s_add_i32 m0, s19, 0x2000
	s_nop 0
	global_load_lds_dwordx4 v[160:161], off
	s_barrier
	s_waitcnt lgkmcnt(0)
	v_mfma_f32_16x16x32_bf16 v[142:145], v[206:209], v[174:177], v[142:145]
	v_mfma_f32_16x16x32_bf16 v[130:133], v[214:217], v[174:177], v[130:133]
	v_mfma_f32_16x16x32_bf16 v[122:125], v[206:209], v[182:185], v[122:125]
	v_mfma_f32_16x16x32_bf16 v[114:117], v[214:217], v[182:185], v[114:117]
	v_mfma_f32_16x16x32_bf16 v[106:109], v[206:209], v[190:193], v[106:109]
	v_mfma_f32_16x16x32_bf16 v[90:93], v[214:217], v[190:193], v[90:93]
	v_mfma_f32_16x16x32_bf16 v[74:77], v[206:209], v[198:201], v[74:77]
	v_mfma_f32_16x16x32_bf16 v[66:69], v[214:217], v[198:201], v[66:69]
	v_mfma_f32_16x16x32_bf16 v[142:145], v[210:213], v[178:181], v[142:145]
	v_mfma_f32_16x16x32_bf16 v[130:133], v[218:221], v[178:181], v[130:133]
	v_mfma_f32_16x16x32_bf16 v[122:125], v[210:213], v[186:189], v[122:125]
	v_mfma_f32_16x16x32_bf16 v[114:117], v[218:221], v[186:189], v[114:117]
	v_mfma_f32_16x16x32_bf16 v[106:109], v[210:213], v[194:197], v[106:109]
	v_mfma_f32_16x16x32_bf16 v[90:93], v[218:221], v[194:197], v[90:93]
	v_mfma_f32_16x16x32_bf16 v[74:77], v[210:213], v[202:205], v[74:77]
	v_mfma_f32_16x16x32_bf16 v[66:69], v[218:221], v[202:205], v[66:69]
	s_barrier
	s_mov_b32 m0, s35
	v_lshl_add_u64 v[160:161], v[238:239], 0, s[84:85]
	ds_read_b128 v[174:177], v173 offset:49152
	ds_read_b128 v[178:181], v173 offset:50176
	ds_read_b128 v[182:185], v173 offset:51200
	ds_read_b128 v[186:189], v173 offset:52224
	ds_read_b128 v[190:193], v173 offset:53248
	ds_read_b128 v[194:197], v173 offset:54272
	ds_read_b128 v[198:201], v173 offset:55296
	ds_read_b128 v[202:205], v173 offset:56320
	global_load_lds_dwordx4 v[160:161], off
	v_lshl_add_u64 v[160:161], v[240:241], 0, s[84:85]
	s_mov_b32 m0, s38
	s_nop 0
	global_load_lds_dwordx4 v[160:161], off
	s_barrier
	s_waitcnt lgkmcnt(0)
	v_mfma_f32_16x16x32_bf16 v[62:65], v[82:85], v[174:177], v[62:65]
	v_mfma_f32_16x16x32_bf16 v[54:57], v[98:101], v[174:177], v[54:57]
	v_mfma_f32_16x16x32_bf16 v[46:49], v[82:85], v[182:185], v[46:49]
	v_mfma_f32_16x16x32_bf16 v[38:41], v[98:101], v[182:185], v[38:41]
	v_mfma_f32_16x16x32_bf16 v[30:33], v[82:85], v[190:193], v[30:33]
	v_mfma_f32_16x16x32_bf16 v[22:25], v[98:101], v[190:193], v[22:25]
	v_mfma_f32_16x16x32_bf16 v[14:17], v[82:85], v[198:201], v[14:17]
	v_mfma_f32_16x16x32_bf16 v[6:9], v[98:101], v[198:201], v[6:9]
	v_mfma_f32_16x16x32_bf16 v[62:65], v[86:89], v[178:181], v[62:65]
	v_mfma_f32_16x16x32_bf16 v[54:57], v[102:105], v[178:181], v[54:57]
	v_mfma_f32_16x16x32_bf16 v[46:49], v[86:89], v[186:189], v[46:49]
	v_mfma_f32_16x16x32_bf16 v[38:41], v[102:105], v[186:189], v[38:41]
	v_mfma_f32_16x16x32_bf16 v[30:33], v[86:89], v[194:197], v[30:33]
	v_mfma_f32_16x16x32_bf16 v[22:25], v[102:105], v[194:197], v[22:25]
	v_mfma_f32_16x16x32_bf16 v[14:17], v[86:89], v[202:205], v[14:17]
	v_mfma_f32_16x16x32_bf16 v[6:9], v[102:105], v[202:205], v[6:9]
	s_barrier
	s_add_u32 s16, s16, 0x40080
	s_addc_u32 s17, s17, 0
	s_add_i32 s18, s18, s23
	v_lshl_add_u64 v[82:83], s[16:17], 0, v[150:151]
	s_mov_b32 m0, s18
	s_nop 0
	global_load_lds_dwordx4 v[82:83], off
	v_lshl_add_u64 v[82:83], s[16:17], 0, v[146:147]
	s_add_i32 m0, s18, 0x2000
	s_nop 0
	global_load_lds_dwordx4 v[82:83], off
	s_waitcnt vmcnt(6)
	s_barrier
	v_mfma_f32_16x16x32_bf16 v[58:61], v[206:209], v[174:177], v[58:61]
	v_mfma_f32_16x16x32_bf16 v[50:53], v[214:217], v[174:177], v[50:53]
	v_mfma_f32_16x16x32_bf16 v[42:45], v[206:209], v[182:185], v[42:45]
	v_mfma_f32_16x16x32_bf16 v[34:37], v[214:217], v[182:185], v[34:37]
	v_mfma_f32_16x16x32_bf16 v[26:29], v[206:209], v[190:193], v[26:29]
	v_mfma_f32_16x16x32_bf16 v[18:21], v[214:217], v[190:193], v[18:21]
	v_mfma_f32_16x16x32_bf16 v[10:13], v[206:209], v[198:201], v[10:13]
	v_mfma_f32_16x16x32_bf16 v[2:5], v[214:217], v[198:201], v[2:5]
	v_mfma_f32_16x16x32_bf16 v[58:61], v[210:213], v[178:181], v[58:61]
	v_mfma_f32_16x16x32_bf16 v[50:53], v[218:221], v[178:181], v[50:53]
	v_mfma_f32_16x16x32_bf16 v[42:45], v[210:213], v[186:189], v[42:45]
	v_mfma_f32_16x16x32_bf16 v[34:37], v[218:221], v[186:189], v[34:37]
	v_mfma_f32_16x16x32_bf16 v[26:29], v[210:213], v[194:197], v[26:29]
	v_mfma_f32_16x16x32_bf16 v[18:21], v[218:221], v[194:197], v[18:21]
	v_mfma_f32_16x16x32_bf16 v[10:13], v[210:213], v[202:205], v[10:13]
	v_mfma_f32_16x16x32_bf16 v[2:5], v[218:221], v[202:205], v[2:5]
	s_barrier
	s_add_u32 s14, s14, 0x100
	s_addc_u32 s15, s15, 0
	s_add_u32 s45, s45, 0x100
	s_addc_u32 s46, s46, 0
	s_cmp_ge_i32 s47, s30
	s_mov_b32 s16, s47
	s_cbranch_scc0 .LBB0_624
	s_branch .LBB0_619

.LBB0_649:
	s_add_i32 s51, s18, 2
	s_add_u32 s19, s0, 0xfffc0080
	s_addc_u32 s20, s1, -1
	s_add_i32 s52, 0, 0x10000
	v_add_u32_e32 v122, s52, v206
	ds_read_b128 v[90:93], v122
	ds_read_b128 v[102:105], v122 offset:1024
	ds_read_b128 v[110:113], v122 offset:2048
	ds_read_b128 v[122:125], v122 offset:3072
	s_cmp_eq_u32 s43, s18
	s_cselect_b32 s18, s48, s49
	s_cselect_b32 s21, s7, s20
	s_cselect_b32 s20, s9, s19
	s_cselect_b32 s19, s47, s50
	v_lshl_add_u64 v[200:201], s[0:1], 0, v[172:173]
	s_add_i32 m0, s15, 0xc000
	ds_read_b128 v[146:149], v207
	ds_read_b128 v[150:153], v207 offset:1024
	ds_read_b128 v[176:179], v207 offset:2048
	ds_read_b128 v[180:183], v207 offset:3072
	ds_read_b128 v[184:187], v207 offset:4096
	ds_read_b128 v[188:191], v207 offset:5120
	ds_read_b128 v[192:195], v207 offset:6144
	ds_read_b128 v[196:199], v207 offset:7168
	global_load_lds_dwordx4 v[200:201], off
	v_lshl_add_u64 v[200:201], s[0:1], 0, v[174:175]
	s_add_i32 m0, s15, 0xe000
	s_nop 0
	global_load_lds_dwordx4 v[200:201], off
	s_waitcnt lgkmcnt(8)
	s_barrier
	s_waitcnt lgkmcnt(0)
	v_mfma_f32_16x16x32_bf16 v[142:145], v[90:93], v[146:149], v[142:145]
	v_mfma_f32_16x16x32_bf16 v[138:141], v[110:113], v[146:149], v[138:141]
	v_mfma_f32_16x16x32_bf16 v[126:129], v[90:93], v[176:179], v[126:129]
	v_mfma_f32_16x16x32_bf16 v[118:121], v[110:113], v[176:179], v[118:121]
	v_mfma_f32_16x16x32_bf16 v[98:101], v[90:93], v[184:187], v[98:101]
	v_mfma_f32_16x16x32_bf16 v[94:97], v[110:113], v[184:187], v[94:97]
	v_mfma_f32_16x16x32_bf16 v[78:81], v[90:93], v[192:195], v[78:81]
	v_mfma_f32_16x16x32_bf16 v[74:77], v[110:113], v[192:195], v[74:77]
	v_mfma_f32_16x16x32_bf16 v[142:145], v[102:105], v[150:153], v[142:145]
	v_mfma_f32_16x16x32_bf16 v[138:141], v[122:125], v[150:153], v[138:141]
	v_mfma_f32_16x16x32_bf16 v[126:129], v[102:105], v[180:183], v[126:129]
	v_mfma_f32_16x16x32_bf16 v[118:121], v[122:125], v[180:183], v[118:121]
	v_mfma_f32_16x16x32_bf16 v[98:101], v[102:105], v[188:191], v[98:101]
	v_mfma_f32_16x16x32_bf16 v[94:97], v[122:125], v[188:191], v[94:97]
	v_mfma_f32_16x16x32_bf16 v[78:81], v[102:105], v[196:199], v[78:81]
	v_mfma_f32_16x16x32_bf16 v[74:77], v[122:125], v[196:199], v[74:77]
	s_barrier
	s_add_i32 s54, 0, 0x14000
	s_add_i32 s52, s52, s27
	v_add_u32_e32 v168, s54, v206
	v_lshl_add_u64 v[204:205], s[18:19], 0, v[156:157]
	s_mov_b32 m0, s52
	ds_read_b128 v[200:203], v168
	ds_read_b128 v[208:211], v168 offset:1024
	ds_read_b128 v[212:215], v168 offset:2048
	ds_read_b128 v[216:219], v168 offset:3072
	global_load_lds_dwordx4 v[204:205], off
	v_lshl_add_u64 v[220:221], s[18:19], 0, v[160:161]
	s_add_i32 m0, s52, 0x2000
	s_nop 0
	global_load_lds_dwordx4 v[220:221], off
	s_barrier
	s_waitcnt lgkmcnt(0)
	v_mfma_f32_16x16x32_bf16 v[134:137], v[200:203], v[146:149], v[134:137]
	v_mfma_f32_16x16x32_bf16 v[130:133], v[212:215], v[146:149], v[130:133]
	v_mfma_f32_16x16x32_bf16 v[114:117], v[200:203], v[176:179], v[114:117]
	v_mfma_f32_16x16x32_bf16 v[106:109], v[212:215], v[176:179], v[106:109]
	v_mfma_f32_16x16x32_bf16 v[86:89], v[200:203], v[184:187], v[86:89]
	v_mfma_f32_16x16x32_bf16 v[82:85], v[212:215], v[184:187], v[82:85]
	v_mfma_f32_16x16x32_bf16 v[70:73], v[200:203], v[192:195], v[70:73]
	v_mfma_f32_16x16x32_bf16 v[66:69], v[212:215], v[192:195], v[66:69]
	v_mfma_f32_16x16x32_bf16 v[134:137], v[208:211], v[150:153], v[134:137]
	v_mfma_f32_16x16x32_bf16 v[130:133], v[216:219], v[150:153], v[130:133]
	v_mfma_f32_16x16x32_bf16 v[114:117], v[208:211], v[180:183], v[114:117]
	v_mfma_f32_16x16x32_bf16 v[106:109], v[216:219], v[180:183], v[106:109]
	v_mfma_f32_16x16x32_bf16 v[86:89], v[208:211], v[188:191], v[86:89]
	v_mfma_f32_16x16x32_bf16 v[82:85], v[216:219], v[188:191], v[82:85]
	v_mfma_f32_16x16x32_bf16 v[70:73], v[208:211], v[196:199], v[70:73]
	v_mfma_f32_16x16x32_bf16 v[66:69], v[216:219], v[196:199], v[66:69]
	s_barrier
	s_mov_b32 m0, s15
	v_lshl_add_u64 v[236:237], s[20:21], 0, v[154:155]
	ds_read_b128 v[146:149], v207 offset:16384
	ds_read_b128 v[150:153], v207 offset:17408
	ds_read_b128 v[176:179], v207 offset:18432
	ds_read_b128 v[180:183], v207 offset:19456
	ds_read_b128 v[184:187], v207 offset:20480
	ds_read_b128 v[188:191], v207 offset:21504
	ds_read_b128 v[192:195], v207 offset:22528
	ds_read_b128 v[196:199], v207 offset:23552
	global_load_lds_dwordx4 v[236:237], off
	v_lshl_add_u64 v[238:239], s[20:21], 0, v[158:159]
	s_mov_b32 m0, s17
	s_nop 0
	global_load_lds_dwordx4 v[238:239], off
	s_barrier
	s_waitcnt lgkmcnt(0)
	v_mfma_f32_16x16x32_bf16 v[62:65], v[90:93], v[146:149], v[62:65]
	v_mfma_f32_16x16x32_bf16 v[58:61], v[110:113], v[146:149], v[58:61]
	v_mfma_f32_16x16x32_bf16 v[46:49], v[90:93], v[176:179], v[46:49]
	v_mfma_f32_16x16x32_bf16 v[42:45], v[110:113], v[176:179], v[42:45]
	v_mfma_f32_16x16x32_bf16 v[30:33], v[90:93], v[184:187], v[30:33]
	v_mfma_f32_16x16x32_bf16 v[26:29], v[110:113], v[184:187], v[26:29]
	v_mfma_f32_16x16x32_bf16 v[14:17], v[90:93], v[192:195], v[14:17]
	v_mfma_f32_16x16x32_bf16 v[10:13], v[110:113], v[192:195], v[10:13]
	v_mfma_f32_16x16x32_bf16 v[62:65], v[102:105], v[150:153], v[62:65]
	v_mfma_f32_16x16x32_bf16 v[58:61], v[122:125], v[150:153], v[58:61]
	v_mfma_f32_16x16x32_bf16 v[46:49], v[102:105], v[180:183], v[46:49]
	v_mfma_f32_16x16x32_bf16 v[42:45], v[122:125], v[180:183], v[42:45]
	v_mfma_f32_16x16x32_bf16 v[30:33], v[102:105], v[188:191], v[30:33]
	v_mfma_f32_16x16x32_bf16 v[26:29], v[122:125], v[188:191], v[26:29]
	v_mfma_f32_16x16x32_bf16 v[14:17], v[102:105], v[196:199], v[14:17]
	v_mfma_f32_16x16x32_bf16 v[10:13], v[122:125], v[196:199], v[10:13]
	s_barrier
	s_add_u32 s52, s18, 0x40000
	s_addc_u32 s53, s19, 0
	s_add_i32 s54, s54, s27
	v_lshl_add_u64 v[90:91], s[52:53], 0, v[156:157]
	s_mov_b32 m0, s54
	s_nop 0
	global_load_lds_dwordx4 v[90:91], off
	v_lshl_add_u64 v[90:91], s[52:53], 0, v[160:161]
	s_add_i32 m0, s54, 0x2000
	s_nop 0
	global_load_lds_dwordx4 v[90:91], off
	s_waitcnt vmcnt(6)
	s_barrier
	v_mfma_f32_16x16x32_bf16 v[54:57], v[200:203], v[146:149], v[54:57]
	v_mfma_f32_16x16x32_bf16 v[50:53], v[212:215], v[146:149], v[50:53]
	v_mfma_f32_16x16x32_bf16 v[38:41], v[200:203], v[176:179], v[38:41]
	v_mfma_f32_16x16x32_bf16 v[34:37], v[212:215], v[176:179], v[34:37]
	v_mfma_f32_16x16x32_bf16 v[22:25], v[200:203], v[184:187], v[22:25]
	v_mfma_f32_16x16x32_bf16 v[18:21], v[212:215], v[184:187], v[18:21]
	v_mfma_f32_16x16x32_bf16 v[6:9], v[200:203], v[192:195], v[6:9]
	v_mfma_f32_16x16x32_bf16 v[2:5], v[212:215], v[192:195], v[2:5]
	v_mfma_f32_16x16x32_bf16 v[54:57], v[208:211], v[150:153], v[54:57]
	v_mfma_f32_16x16x32_bf16 v[50:53], v[216:219], v[150:153], v[50:53]
	v_mfma_f32_16x16x32_bf16 v[38:41], v[208:211], v[180:183], v[38:41]
	v_mfma_f32_16x16x32_bf16 v[34:37], v[216:219], v[180:183], v[34:37]
	v_mfma_f32_16x16x32_bf16 v[22:25], v[208:211], v[188:191], v[22:25]
	v_mfma_f32_16x16x32_bf16 v[18:21], v[216:219], v[188:191], v[18:21]
	v_mfma_f32_16x16x32_bf16 v[6:9], v[208:211], v[196:199], v[6:9]
	v_mfma_f32_16x16x32_bf16 v[2:5], v[216:219], v[196:199], v[2:5]
	s_barrier
	s_add_i32 s52, 0, 0x18000
	v_add_u32_e32 v122, s52, v206
	ds_read_b128 v[90:93], v122
	ds_read_b128 v[102:105], v122 offset:1024
	ds_read_b128 v[110:113], v122 offset:2048
	ds_read_b128 v[122:125], v122 offset:3072
	s_add_u32 s20, s20, 0x40000
	s_addc_u32 s21, s21, 0
	s_mov_b32 m0, s28
	v_lshl_add_u64 v[200:201], s[20:21], 0, v[154:155]
	ds_read_b128 v[146:149], v207 offset:32768
	ds_read_b128 v[150:153], v207 offset:33792
	ds_read_b128 v[176:179], v207 offset:34816
	ds_read_b128 v[180:183], v207 offset:35840
	ds_read_b128 v[184:187], v207 offset:36864
	ds_read_b128 v[188:191], v207 offset:37888
	ds_read_b128 v[192:195], v207 offset:38912
	ds_read_b128 v[196:199], v207 offset:39936
	global_load_lds_dwordx4 v[200:201], off
	v_lshl_add_u64 v[200:201], s[20:21], 0, v[158:159]
	s_mov_b32 m0, s29
	s_nop 0
	global_load_lds_dwordx4 v[200:201], off
	s_waitcnt lgkmcnt(8)
	s_barrier
	s_waitcnt lgkmcnt(0)
	v_mfma_f32_16x16x32_bf16 v[142:145], v[90:93], v[146:149], v[142:145]
	v_mfma_f32_16x16x32_bf16 v[138:141], v[110:113], v[146:149], v[138:141]
	v_mfma_f32_16x16x32_bf16 v[126:129], v[90:93], v[176:179], v[126:129]
	v_mfma_f32_16x16x32_bf16 v[118:121], v[110:113], v[176:179], v[118:121]
	v_mfma_f32_16x16x32_bf16 v[98:101], v[90:93], v[184:187], v[98:101]
	v_mfma_f32_16x16x32_bf16 v[94:97], v[110:113], v[184:187], v[94:97]
	v_mfma_f32_16x16x32_bf16 v[78:81], v[90:93], v[192:195], v[78:81]
	v_mfma_f32_16x16x32_bf16 v[74:77], v[110:113], v[192:195], v[74:77]
	v_mfma_f32_16x16x32_bf16 v[142:145], v[102:105], v[150:153], v[142:145]
	v_mfma_f32_16x16x32_bf16 v[138:141], v[122:125], v[150:153], v[138:141]
	v_mfma_f32_16x16x32_bf16 v[126:129], v[102:105], v[180:183], v[126:129]
	v_mfma_f32_16x16x32_bf16 v[118:121], v[122:125], v[180:183], v[118:121]
	v_mfma_f32_16x16x32_bf16 v[98:101], v[102:105], v[188:191], v[98:101]
	v_mfma_f32_16x16x32_bf16 v[94:97], v[122:125], v[188:191], v[94:97]
	v_mfma_f32_16x16x32_bf16 v[78:81], v[102:105], v[196:199], v[78:81]
	v_mfma_f32_16x16x32_bf16 v[74:77], v[122:125], v[196:199], v[74:77]
	s_barrier
	s_add_i32 s20, 0, 0x1c000
	s_add_i32 s21, s52, s27
	v_add_u32_e32 v168, s20, v206
	v_lshl_add_u64 v[204:205], v[204:205], 0, s[84:85]
	s_mov_b32 m0, s21
	ds_read_b128 v[200:203], v168
	ds_read_b128 v[208:211], v168 offset:1024
	ds_read_b128 v[212:215], v168 offset:2048
	ds_read_b128 v[216:219], v168 offset:3072
	global_load_lds_dwordx4 v[204:205], off
	v_lshl_add_u64 v[204:205], v[220:221], 0, s[84:85]
	s_add_i32 m0, s21, 0x2000
	s_nop 0
	global_load_lds_dwordx4 v[204:205], off
	s_barrier
	s_waitcnt lgkmcnt(0)
	v_mfma_f32_16x16x32_bf16 v[134:137], v[200:203], v[146:149], v[134:137]
	v_mfma_f32_16x16x32_bf16 v[130:133], v[212:215], v[146:149], v[130:133]
	v_mfma_f32_16x16x32_bf16 v[114:117], v[200:203], v[176:179], v[114:117]
	v_mfma_f32_16x16x32_bf16 v[106:109], v[212:215], v[176:179], v[106:109]
	v_mfma_f32_16x16x32_bf16 v[86:89], v[200:203], v[184:187], v[86:89]
	v_mfma_f32_16x16x32_bf16 v[82:85], v[212:215], v[184:187], v[82:85]
	v_mfma_f32_16x16x32_bf16 v[70:73], v[200:203], v[192:195], v[70:73]
	v_mfma_f32_16x16x32_bf16 v[66:69], v[212:215], v[192:195], v[66:69]
	v_mfma_f32_16x16x32_bf16 v[134:137], v[208:211], v[150:153], v[134:137]
	v_mfma_f32_16x16x32_bf16 v[130:133], v[216:219], v[150:153], v[130:133]
	v_mfma_f32_16x16x32_bf16 v[114:117], v[208:211], v[180:183], v[114:117]
	v_mfma_f32_16x16x32_bf16 v[106:109], v[216:219], v[180:183], v[106:109]
	v_mfma_f32_16x16x32_bf16 v[86:89], v[208:211], v[188:191], v[86:89]
	v_mfma_f32_16x16x32_bf16 v[82:85], v[216:219], v[188:191], v[82:85]
	v_mfma_f32_16x16x32_bf16 v[70:73], v[208:211], v[196:199], v[70:73]
	v_mfma_f32_16x16x32_bf16 v[66:69], v[216:219], v[196:199], v[66:69]
	s_barrier
	s_mov_b32 m0, s41
	v_lshl_add_u64 v[204:205], v[236:237], 0, s[84:85]
	ds_read_b128 v[146:149], v207 offset:49152
	ds_read_b128 v[150:153], v207 offset:50176
	ds_read_b128 v[176:179], v207 offset:51200
	ds_read_b128 v[180:183], v207 offset:52224
	ds_read_b128 v[184:187], v207 offset:53248
	ds_read_b128 v[188:191], v207 offset:54272
	ds_read_b128 v[192:195], v207 offset:55296
	ds_read_b128 v[196:199], v207 offset:56320
	global_load_lds_dwordx4 v[204:205], off
	v_lshl_add_u64 v[204:205], v[238:239], 0, s[84:85]
	s_mov_b32 m0, s42
	s_nop 0
	global_load_lds_dwordx4 v[204:205], off
	s_barrier
	s_waitcnt lgkmcnt(0)
	v_mfma_f32_16x16x32_bf16 v[62:65], v[90:93], v[146:149], v[62:65]
	v_mfma_f32_16x16x32_bf16 v[58:61], v[110:113], v[146:149], v[58:61]
	v_mfma_f32_16x16x32_bf16 v[46:49], v[90:93], v[176:179], v[46:49]
	v_mfma_f32_16x16x32_bf16 v[42:45], v[110:113], v[176:179], v[42:45]
	v_mfma_f32_16x16x32_bf16 v[30:33], v[90:93], v[184:187], v[30:33]
	v_mfma_f32_16x16x32_bf16 v[26:29], v[110:113], v[184:187], v[26:29]
	v_mfma_f32_16x16x32_bf16 v[14:17], v[90:93], v[192:195], v[14:17]
	v_mfma_f32_16x16x32_bf16 v[10:13], v[110:113], v[192:195], v[10:13]
	v_mfma_f32_16x16x32_bf16 v[62:65], v[102:105], v[150:153], v[62:65]
	v_mfma_f32_16x16x32_bf16 v[58:61], v[122:125], v[150:153], v[58:61]
	v_mfma_f32_16x16x32_bf16 v[46:49], v[102:105], v[180:183], v[46:49]
	v_mfma_f32_16x16x32_bf16 v[42:45], v[122:125], v[180:183], v[42:45]
	v_mfma_f32_16x16x32_bf16 v[30:33], v[102:105], v[188:191], v[30:33]
	v_mfma_f32_16x16x32_bf16 v[26:29], v[122:125], v[188:191], v[26:29]
	v_mfma_f32_16x16x32_bf16 v[14:17], v[102:105], v[196:199], v[14:17]
	v_mfma_f32_16x16x32_bf16 v[10:13], v[122:125], v[196:199], v[10:13]
	s_barrier
	s_add_u32 s18, s18, 0x40080
	s_addc_u32 s19, s19, 0
	s_add_i32 s20, s20, s27
	v_lshl_add_u64 v[90:91], s[18:19], 0, v[156:157]
	s_mov_b32 m0, s20
	s_nop 0
	global_load_lds_dwordx4 v[90:91], off
	v_lshl_add_u64 v[90:91], s[18:19], 0, v[160:161]
	s_add_i32 m0, s20, 0x2000
	s_nop 0
	global_load_lds_dwordx4 v[90:91], off
	s_waitcnt vmcnt(6)
	s_barrier
	v_mfma_f32_16x16x32_bf16 v[54:57], v[200:203], v[146:149], v[54:57]
	v_mfma_f32_16x16x32_bf16 v[50:53], v[212:215], v[146:149], v[50:53]
	v_mfma_f32_16x16x32_bf16 v[38:41], v[200:203], v[176:179], v[38:41]
	v_mfma_f32_16x16x32_bf16 v[34:37], v[212:215], v[176:179], v[34:37]
	v_mfma_f32_16x16x32_bf16 v[22:25], v[200:203], v[184:187], v[22:25]
	v_mfma_f32_16x16x32_bf16 v[18:21], v[212:215], v[184:187], v[18:21]
	v_mfma_f32_16x16x32_bf16 v[6:9], v[200:203], v[192:195], v[6:9]
	v_mfma_f32_16x16x32_bf16 v[2:5], v[212:215], v[192:195], v[2:5]
	v_mfma_f32_16x16x32_bf16 v[54:57], v[208:211], v[150:153], v[54:57]
	v_mfma_f32_16x16x32_bf16 v[50:53], v[216:219], v[150:153], v[50:53]
	v_mfma_f32_16x16x32_bf16 v[38:41], v[208:211], v[180:183], v[38:41]
	v_mfma_f32_16x16x32_bf16 v[34:37], v[216:219], v[180:183], v[34:37]
	v_mfma_f32_16x16x32_bf16 v[22:25], v[208:211], v[188:191], v[22:25]
	v_mfma_f32_16x16x32_bf16 v[18:21], v[216:219], v[188:191], v[18:21]
	v_mfma_f32_16x16x32_bf16 v[6:9], v[208:211], v[196:199], v[6:9]
	v_mfma_f32_16x16x32_bf16 v[2:5], v[216:219], v[196:199], v[2:5]
	s_barrier
	s_add_u32 s49, s49, 0x100
	s_addc_u32 s50, s50, 0
	s_add_u32 s0, s0, 0x100
	s_addc_u32 s1, s1, 0
	s_cmp_ge_i32 s51, s38
	s_mov_b32 s18, s51
	s_cbranch_scc0 .LBB0_649

.LBB0_799:
	s_add_i32 s57, s26, 2
	s_add_u32 s27, s24, 0xfffc0080
	s_addc_u32 s28, s25, -1
	s_add_i32 s58, 0, 0x10000
	v_add_u32_e32 v46, s58, v205
	ds_read_b128 v[22:25], v46
	ds_read_b128 v[34:37], v46 offset:1024
	ds_read_b128 v[42:45], v46 offset:2048
	ds_read_b128 v[46:49], v46 offset:3072
	s_cmp_eq_u32 s49, s26
	s_cselect_b32 s26, s39, s55
	s_cselect_b32 s29, s13, s28
	s_cselect_b32 s28, s15, s27
	s_cselect_b32 s27, s21, s56
	v_lshl_add_u64 v[200:201], s[24:25], 0, v[176:177]
	s_add_i32 m0, s41, 0xc000
	ds_read_b128 v[146:149], v208
	ds_read_b128 v[150:153], v208 offset:1024
	ds_read_b128 v[154:157], v208 offset:2048
	ds_read_b128 v[180:183], v208 offset:3072
	ds_read_b128 v[184:187], v208 offset:4096
	ds_read_b128 v[188:191], v208 offset:5120
	ds_read_b128 v[192:195], v208 offset:6144
	ds_read_b128 v[196:199], v208 offset:7168
	global_load_lds_dwordx4 v[200:201], off
	v_lshl_add_u64 v[200:201], s[24:25], 0, v[178:179]
	s_add_i32 m0, s41, 0xe000
	s_nop 0
	global_load_lds_dwordx4 v[200:201], off
	s_waitcnt lgkmcnt(8)
	s_barrier
	s_waitcnt lgkmcnt(0)
	v_mfma_f32_16x16x32_bf16 v[142:145], v[22:25], v[146:149], v[142:145]
	v_mfma_f32_16x16x32_bf16 v[134:137], v[42:45], v[146:149], v[134:137]
	v_mfma_f32_16x16x32_bf16 v[126:129], v[22:25], v[154:157], v[126:129]
	v_mfma_f32_16x16x32_bf16 v[118:121], v[42:45], v[154:157], v[118:121]
	v_mfma_f32_16x16x32_bf16 v[110:113], v[22:25], v[184:187], v[110:113]
	v_mfma_f32_16x16x32_bf16 v[102:105], v[42:45], v[184:187], v[102:105]
	v_mfma_f32_16x16x32_bf16 v[94:97], v[22:25], v[192:195], v[94:97]
	v_mfma_f32_16x16x32_bf16 v[86:89], v[42:45], v[192:195], v[86:89]
	v_mfma_f32_16x16x32_bf16 v[142:145], v[34:37], v[150:153], v[142:145]
	v_mfma_f32_16x16x32_bf16 v[134:137], v[46:49], v[150:153], v[134:137]
	v_mfma_f32_16x16x32_bf16 v[126:129], v[34:37], v[180:183], v[126:129]
	v_mfma_f32_16x16x32_bf16 v[118:121], v[46:49], v[180:183], v[118:121]
	v_mfma_f32_16x16x32_bf16 v[110:113], v[34:37], v[188:191], v[110:113]
	v_mfma_f32_16x16x32_bf16 v[102:105], v[46:49], v[188:191], v[102:105]
	v_mfma_f32_16x16x32_bf16 v[94:97], v[34:37], v[196:199], v[94:97]
	v_mfma_f32_16x16x32_bf16 v[86:89], v[46:49], v[196:199], v[86:89]
	s_barrier
	s_add_i32 s60, 0, 0x14000
	s_add_i32 s58, s58, s35
	v_add_u32_e32 v168, s60, v205
	v_lshl_add_u64 v[206:207], s[26:27], 0, v[172:173]
	s_mov_b32 m0, s58
	ds_read_b128 v[200:203], v168
	ds_read_b128 v[210:213], v168 offset:1024
	ds_read_b128 v[214:217], v168 offset:2048
	ds_read_b128 v[218:221], v168 offset:3072
	global_load_lds_dwordx4 v[206:207], off
	v_lshl_add_u64 v[236:237], s[26:27], 0, v[158:159]
	s_add_i32 m0, s58, 0x2000
	s_nop 0
	global_load_lds_dwordx4 v[236:237], off
	s_barrier
	s_waitcnt lgkmcnt(0)
	v_mfma_f32_16x16x32_bf16 v[138:141], v[200:203], v[146:149], v[138:141]
	v_mfma_f32_16x16x32_bf16 v[130:133], v[214:217], v[146:149], v[130:133]
	v_mfma_f32_16x16x32_bf16 v[122:125], v[200:203], v[154:157], v[122:125]
	v_mfma_f32_16x16x32_bf16 v[114:117], v[214:217], v[154:157], v[114:117]
	v_mfma_f32_16x16x32_bf16 v[106:109], v[200:203], v[184:187], v[106:109]
	v_mfma_f32_16x16x32_bf16 v[98:101], v[214:217], v[184:187], v[98:101]
	v_mfma_f32_16x16x32_bf16 v[90:93], v[200:203], v[192:195], v[90:93]
	v_mfma_f32_16x16x32_bf16 v[82:85], v[214:217], v[192:195], v[82:85]
	v_mfma_f32_16x16x32_bf16 v[138:141], v[210:213], v[150:153], v[138:141]
	v_mfma_f32_16x16x32_bf16 v[130:133], v[218:221], v[150:153], v[130:133]
	v_mfma_f32_16x16x32_bf16 v[122:125], v[210:213], v[180:183], v[122:125]
	v_mfma_f32_16x16x32_bf16 v[114:117], v[218:221], v[180:183], v[114:117]
	v_mfma_f32_16x16x32_bf16 v[106:109], v[210:213], v[188:191], v[106:109]
	v_mfma_f32_16x16x32_bf16 v[98:101], v[218:221], v[188:191], v[98:101]
	v_mfma_f32_16x16x32_bf16 v[90:93], v[210:213], v[196:199], v[90:93]
	v_mfma_f32_16x16x32_bf16 v[82:85], v[218:221], v[196:199], v[82:85]
	s_barrier
	s_mov_b32 m0, s41
	v_lshl_add_u64 v[238:239], s[28:29], 0, v[174:175]
	ds_read_b128 v[146:149], v208 offset:16384
	ds_read_b128 v[150:153], v208 offset:17408
	ds_read_b128 v[154:157], v208 offset:18432
	ds_read_b128 v[180:183], v208 offset:19456
	ds_read_b128 v[184:187], v208 offset:20480
	ds_read_b128 v[188:191], v208 offset:21504
	ds_read_b128 v[192:195], v208 offset:22528
	ds_read_b128 v[196:199], v208 offset:23552
	global_load_lds_dwordx4 v[238:239], off
	v_lshl_add_u64 v[240:241], s[28:29], 0, v[160:161]
	s_mov_b32 m0, s42
	s_nop 0
	global_load_lds_dwordx4 v[240:241], off
	s_barrier
	s_waitcnt lgkmcnt(0)
	v_mfma_f32_16x16x32_bf16 v[78:81], v[22:25], v[146:149], v[78:81]
	v_mfma_f32_16x16x32_bf16 v[70:73], v[42:45], v[146:149], v[70:73]
	v_mfma_f32_16x16x32_bf16 v[62:65], v[22:25], v[154:157], v[62:65]
	v_mfma_f32_16x16x32_bf16 v[54:57], v[42:45], v[154:157], v[54:57]
	v_mfma_f32_16x16x32_bf16 v[38:41], v[22:25], v[184:187], v[38:41]
	v_mfma_f32_16x16x32_bf16 v[26:29], v[42:45], v[184:187], v[26:29]
	v_mfma_f32_16x16x32_bf16 v[14:17], v[22:25], v[192:195], v[14:17]
	v_mfma_f32_16x16x32_bf16 v[6:9], v[42:45], v[192:195], v[6:9]
	v_mfma_f32_16x16x32_bf16 v[78:81], v[34:37], v[150:153], v[78:81]
	v_mfma_f32_16x16x32_bf16 v[70:73], v[46:49], v[150:153], v[70:73]
	v_mfma_f32_16x16x32_bf16 v[62:65], v[34:37], v[180:183], v[62:65]
	v_mfma_f32_16x16x32_bf16 v[54:57], v[46:49], v[180:183], v[54:57]
	v_mfma_f32_16x16x32_bf16 v[38:41], v[34:37], v[188:191], v[38:41]
	v_mfma_f32_16x16x32_bf16 v[26:29], v[46:49], v[188:191], v[26:29]
	v_mfma_f32_16x16x32_bf16 v[14:17], v[34:37], v[196:199], v[14:17]
	v_mfma_f32_16x16x32_bf16 v[6:9], v[46:49], v[196:199], v[6:9]
	s_barrier
	s_add_u32 s58, s26, 0x40000
	s_addc_u32 s59, s27, 0
	s_add_i32 s60, s60, s35
	v_lshl_add_u64 v[22:23], s[58:59], 0, v[172:173]
	s_mov_b32 m0, s60
	s_nop 0
	global_load_lds_dwordx4 v[22:23], off
	v_lshl_add_u64 v[22:23], s[58:59], 0, v[158:159]
	s_add_i32 m0, s60, 0x2000
	s_nop 0
	global_load_lds_dwordx4 v[22:23], off
	s_waitcnt vmcnt(6)
	s_barrier
	v_mfma_f32_16x16x32_bf16 v[30:33], v[200:203], v[184:187], v[30:33]
	v_mfma_f32_16x16x32_bf16 v[18:21], v[214:217], v[184:187], v[18:21]
	v_mfma_f32_16x16x32_bf16 v[10:13], v[200:203], v[192:195], v[10:13]
	v_mfma_f32_16x16x32_bf16 v[2:5], v[214:217], v[192:195], v[2:5]
	v_mfma_f32_16x16x32_bf16 v[22:25], v[200:203], v[146:149], v[74:77]
	v_mfma_f32_16x16x32_bf16 v[34:37], v[214:217], v[146:149], v[66:69]
	v_mfma_f32_16x16x32_bf16 v[42:45], v[200:203], v[154:157], v[58:61]
	v_mfma_f32_16x16x32_bf16 v[46:49], v[214:217], v[154:157], v[50:53]
	v_mfma_f32_16x16x32_bf16 v[30:33], v[210:213], v[188:191], v[30:33]
	v_mfma_f32_16x16x32_bf16 v[18:21], v[218:221], v[188:191], v[18:21]
	v_mfma_f32_16x16x32_bf16 v[10:13], v[210:213], v[196:199], v[10:13]
	v_mfma_f32_16x16x32_bf16 v[2:5], v[218:221], v[196:199], v[2:5]
	v_mfma_f32_16x16x32_bf16 v[22:25], v[210:213], v[150:153], v[22:25]
	v_mfma_f32_16x16x32_bf16 v[34:37], v[218:221], v[150:153], v[34:37]
	v_mfma_f32_16x16x32_bf16 v[42:45], v[210:213], v[180:183], v[42:45]
	v_mfma_f32_16x16x32_bf16 v[46:49], v[218:221], v[180:183], v[46:49]
	s_barrier
	s_add_i32 s58, 0, 0x18000
	v_add_u32_e32 v74, s58, v205
	ds_read_b128 v[50:53], v74
	ds_read_b128 v[58:61], v74 offset:1024
	ds_read_b128 v[66:69], v74 offset:2048
	ds_read_b128 v[74:77], v74 offset:3072
	s_add_u32 s28, s28, 0x40000
	s_addc_u32 s29, s29, 0
	s_mov_b32 m0, s43
	v_lshl_add_u64 v[200:201], s[28:29], 0, v[174:175]
	ds_read_b128 v[146:149], v208 offset:32768
	ds_read_b128 v[150:153], v208 offset:33792
	ds_read_b128 v[154:157], v208 offset:34816
	ds_read_b128 v[180:183], v208 offset:35840
	ds_read_b128 v[184:187], v208 offset:36864
	ds_read_b128 v[188:191], v208 offset:37888
	ds_read_b128 v[192:195], v208 offset:38912
	ds_read_b128 v[196:199], v208 offset:39936
	global_load_lds_dwordx4 v[200:201], off
	v_lshl_add_u64 v[200:201], s[28:29], 0, v[160:161]
	s_mov_b32 m0, s44
	s_nop 0
	global_load_lds_dwordx4 v[200:201], off
	s_waitcnt lgkmcnt(8)
	s_barrier
	s_waitcnt lgkmcnt(0)
	v_mfma_f32_16x16x32_bf16 v[142:145], v[50:53], v[146:149], v[142:145]
	v_mfma_f32_16x16x32_bf16 v[134:137], v[66:69], v[146:149], v[134:137]
	v_mfma_f32_16x16x32_bf16 v[126:129], v[50:53], v[154:157], v[126:129]
	v_mfma_f32_16x16x32_bf16 v[118:121], v[66:69], v[154:157], v[118:121]
	v_mfma_f32_16x16x32_bf16 v[110:113], v[50:53], v[184:187], v[110:113]
	v_mfma_f32_16x16x32_bf16 v[102:105], v[66:69], v[184:187], v[102:105]
	v_mfma_f32_16x16x32_bf16 v[94:97], v[50:53], v[192:195], v[94:97]
	v_mfma_f32_16x16x32_bf16 v[86:89], v[66:69], v[192:195], v[86:89]
	v_mfma_f32_16x16x32_bf16 v[142:145], v[58:61], v[150:153], v[142:145]
	v_mfma_f32_16x16x32_bf16 v[134:137], v[74:77], v[150:153], v[134:137]
	v_mfma_f32_16x16x32_bf16 v[126:129], v[58:61], v[180:183], v[126:129]
	v_mfma_f32_16x16x32_bf16 v[118:121], v[74:77], v[180:183], v[118:121]
	v_mfma_f32_16x16x32_bf16 v[110:113], v[58:61], v[188:191], v[110:113]
	v_mfma_f32_16x16x32_bf16 v[102:105], v[74:77], v[188:191], v[102:105]
	v_mfma_f32_16x16x32_bf16 v[94:97], v[58:61], v[196:199], v[94:97]
	v_mfma_f32_16x16x32_bf16 v[86:89], v[74:77], v[196:199], v[86:89]
	s_barrier
	s_add_i32 s28, 0, 0x1c000
	s_add_i32 s29, s58, s35
	v_add_u32_e32 v168, s28, v205
	v_lshl_add_u64 v[206:207], v[206:207], 0, s[84:85]
	s_mov_b32 m0, s29
	ds_read_b128 v[200:203], v168
	ds_read_b128 v[210:213], v168 offset:1024
	ds_read_b128 v[214:217], v168 offset:2048
	ds_read_b128 v[218:221], v168 offset:3072
	global_load_lds_dwordx4 v[206:207], off
	v_lshl_add_u64 v[206:207], v[236:237], 0, s[84:85]
	s_add_i32 m0, s29, 0x2000
	s_nop 0
	global_load_lds_dwordx4 v[206:207], off
	s_barrier
	s_waitcnt lgkmcnt(0)
	v_mfma_f32_16x16x32_bf16 v[138:141], v[200:203], v[146:149], v[138:141]
	v_mfma_f32_16x16x32_bf16 v[130:133], v[214:217], v[146:149], v[130:133]
	v_mfma_f32_16x16x32_bf16 v[122:125], v[200:203], v[154:157], v[122:125]
	v_mfma_f32_16x16x32_bf16 v[114:117], v[214:217], v[154:157], v[114:117]
	v_mfma_f32_16x16x32_bf16 v[106:109], v[200:203], v[184:187], v[106:109]
	v_mfma_f32_16x16x32_bf16 v[98:101], v[214:217], v[184:187], v[98:101]
	v_mfma_f32_16x16x32_bf16 v[90:93], v[200:203], v[192:195], v[90:93]
	v_mfma_f32_16x16x32_bf16 v[82:85], v[214:217], v[192:195], v[82:85]
	v_mfma_f32_16x16x32_bf16 v[138:141], v[210:213], v[150:153], v[138:141]
	v_mfma_f32_16x16x32_bf16 v[130:133], v[218:221], v[150:153], v[130:133]
	v_mfma_f32_16x16x32_bf16 v[122:125], v[210:213], v[180:183], v[122:125]
	v_mfma_f32_16x16x32_bf16 v[114:117], v[218:221], v[180:183], v[114:117]
	v_mfma_f32_16x16x32_bf16 v[106:109], v[210:213], v[188:191], v[106:109]
	v_mfma_f32_16x16x32_bf16 v[98:101], v[218:221], v[188:191], v[98:101]
	v_mfma_f32_16x16x32_bf16 v[90:93], v[210:213], v[196:199], v[90:93]
	v_mfma_f32_16x16x32_bf16 v[82:85], v[218:221], v[196:199], v[82:85]
	s_barrier
	s_mov_b32 m0, s47
	v_lshl_add_u64 v[206:207], v[238:239], 0, s[84:85]
	ds_read_b128 v[146:149], v208 offset:49152
	ds_read_b128 v[150:153], v208 offset:50176
	ds_read_b128 v[154:157], v208 offset:51200
	ds_read_b128 v[180:183], v208 offset:52224
	ds_read_b128 v[184:187], v208 offset:53248
	ds_read_b128 v[188:191], v208 offset:54272
	ds_read_b128 v[192:195], v208 offset:55296
	ds_read_b128 v[196:199], v208 offset:56320
	global_load_lds_dwordx4 v[206:207], off
	v_lshl_add_u64 v[206:207], v[240:241], 0, s[84:85]
	s_mov_b32 m0, s48
	s_nop 0
	global_load_lds_dwordx4 v[206:207], off
	s_barrier
	s_waitcnt lgkmcnt(0)
	v_mfma_f32_16x16x32_bf16 v[78:81], v[50:53], v[146:149], v[78:81]
	v_mfma_f32_16x16x32_bf16 v[70:73], v[66:69], v[146:149], v[70:73]
	v_mfma_f32_16x16x32_bf16 v[62:65], v[50:53], v[154:157], v[62:65]
	v_mfma_f32_16x16x32_bf16 v[54:57], v[66:69], v[154:157], v[54:57]
	v_mfma_f32_16x16x32_bf16 v[38:41], v[50:53], v[184:187], v[38:41]
	v_mfma_f32_16x16x32_bf16 v[26:29], v[66:69], v[184:187], v[26:29]
	v_mfma_f32_16x16x32_bf16 v[14:17], v[50:53], v[192:195], v[14:17]
	v_mfma_f32_16x16x32_bf16 v[6:9], v[66:69], v[192:195], v[6:9]
	v_mfma_f32_16x16x32_bf16 v[78:81], v[58:61], v[150:153], v[78:81]
	v_mfma_f32_16x16x32_bf16 v[70:73], v[74:77], v[150:153], v[70:73]
	v_mfma_f32_16x16x32_bf16 v[62:65], v[58:61], v[180:183], v[62:65]
	v_mfma_f32_16x16x32_bf16 v[54:57], v[74:77], v[180:183], v[54:57]
	v_mfma_f32_16x16x32_bf16 v[38:41], v[58:61], v[188:191], v[38:41]
	v_mfma_f32_16x16x32_bf16 v[26:29], v[74:77], v[188:191], v[26:29]
	v_mfma_f32_16x16x32_bf16 v[14:17], v[58:61], v[196:199], v[14:17]
	v_mfma_f32_16x16x32_bf16 v[6:9], v[74:77], v[196:199], v[6:9]
	s_barrier
	s_add_u32 s26, s26, 0x40080
	s_addc_u32 s27, s27, 0
	s_add_i32 s28, s28, s35
	v_lshl_add_u64 v[50:51], s[26:27], 0, v[172:173]
	s_mov_b32 m0, s28
	s_nop 0
	global_load_lds_dwordx4 v[50:51], off
	v_lshl_add_u64 v[50:51], s[26:27], 0, v[158:159]
	s_add_i32 m0, s28, 0x2000
	s_nop 0
	global_load_lds_dwordx4 v[50:51], off
	s_waitcnt vmcnt(6)
	s_barrier
	v_mfma_f32_16x16x32_bf16 v[22:25], v[200:203], v[146:149], v[22:25]
	v_mfma_f32_16x16x32_bf16 v[74:77], v[210:213], v[150:153], v[22:25]
	v_mfma_f32_16x16x32_bf16 v[22:25], v[214:217], v[146:149], v[34:37]
	v_mfma_f32_16x16x32_bf16 v[66:69], v[218:221], v[150:153], v[22:25]
	v_mfma_f32_16x16x32_bf16 v[22:25], v[200:203], v[154:157], v[42:45]
	v_mfma_f32_16x16x32_bf16 v[58:61], v[210:213], v[180:183], v[22:25]
	v_mfma_f32_16x16x32_bf16 v[22:25], v[214:217], v[154:157], v[46:49]
	v_mfma_f32_16x16x32_bf16 v[50:53], v[218:221], v[180:183], v[22:25]
	v_mfma_f32_16x16x32_bf16 v[22:25], v[200:203], v[184:187], v[30:33]
	v_mfma_f32_16x16x32_bf16 v[18:21], v[214:217], v[184:187], v[18:21]
	v_mfma_f32_16x16x32_bf16 v[10:13], v[200:203], v[192:195], v[10:13]
	v_mfma_f32_16x16x32_bf16 v[2:5], v[214:217], v[192:195], v[2:5]
	v_mfma_f32_16x16x32_bf16 v[30:33], v[210:213], v[188:191], v[22:25]
	v_mfma_f32_16x16x32_bf16 v[18:21], v[218:221], v[188:191], v[18:21]
	v_mfma_f32_16x16x32_bf16 v[10:13], v[210:213], v[196:199], v[10:13]
	v_mfma_f32_16x16x32_bf16 v[2:5], v[218:221], v[196:199], v[2:5]
	s_barrier
	s_add_u32 s24, s24, 0x100
	s_addc_u32 s25, s25, 0
	s_add_u32 s55, s55, 0x100
	s_addc_u32 s56, s56, 0
	s_cmp_ge_i32 s57, s45
	s_mov_b32 s26, s57
	s_cbranch_scc0 .LBB0_799

.LBB0_844:
	s_add_i32 s53, s14, 2
	s_add_u32 s15, s12, 0x4000
	s_addc_u32 s16, s13, 0
	s_cmp_eq_u32 s43, s14
	s_cselect_b32 s18, s0, s15
	s_cselect_b32 s19, s1, s16
	s_cselect_b32 s14, s2, s51
	s_cselect_b32 s15, s3, s52
	s_add_u32 s16, s18, 0x8000
	s_addc_u32 s17, s19, 0
	s_add_i32 s54, 0, 0x10000
	v_add_u32_e32 v142, s54, v210
	ds_read_b128 v[126:129], v142
	ds_read_b128 v[130:133], v142 offset:1024
	ds_read_b128 v[138:141], v142 offset:2048
	ds_read_b128 v[142:145], v142 offset:3072
	v_lshl_add_u64 v[200:201], s[12:13], 0, v[180:181]
	s_add_i32 m0, s26, 0xc000
	ds_read_b128 v[146:149], v211
	ds_read_b128 v[150:153], v211 offset:1024
	ds_read_b128 v[154:157], v211 offset:2048
	ds_read_b128 v[158:161], v211 offset:3072
	ds_read_b128 v[184:187], v211 offset:4096
	ds_read_b128 v[188:191], v211 offset:5120
	ds_read_b128 v[192:195], v211 offset:6144
	ds_read_b128 v[196:199], v211 offset:7168
	global_load_lds_dwordx4 v[200:201], off
	v_lshl_add_u64 v[200:201], s[12:13], 0, v[182:183]
	s_add_i32 m0, s26, 0xe000
	s_nop 0
	global_load_lds_dwordx4 v[200:201], off
	s_waitcnt lgkmcnt(8)
	s_barrier
	s_waitcnt lgkmcnt(0)
	v_mfma_f32_16x16x32_bf16 v[134:137], v[126:129], v[146:149], v[134:137]
	v_mfma_f32_16x16x32_bf16 v[122:125], v[138:141], v[146:149], v[122:125]
	v_mfma_f32_16x16x32_bf16 v[110:113], v[126:129], v[154:157], v[110:113]
	v_mfma_f32_16x16x32_bf16 v[106:109], v[138:141], v[154:157], v[106:109]
	v_mfma_f32_16x16x32_bf16 v[94:97], v[126:129], v[184:187], v[94:97]
	v_mfma_f32_16x16x32_bf16 v[90:93], v[138:141], v[184:187], v[90:93]
	v_mfma_f32_16x16x32_bf16 v[78:81], v[126:129], v[192:195], v[78:81]
	v_mfma_f32_16x16x32_bf16 v[74:77], v[138:141], v[192:195], v[74:77]
	v_mfma_f32_16x16x32_bf16 v[134:137], v[130:133], v[150:153], v[134:137]
	v_mfma_f32_16x16x32_bf16 v[122:125], v[142:145], v[150:153], v[122:125]
	v_mfma_f32_16x16x32_bf16 v[110:113], v[130:133], v[158:161], v[110:113]
	v_mfma_f32_16x16x32_bf16 v[106:109], v[142:145], v[158:161], v[106:109]
	v_mfma_f32_16x16x32_bf16 v[94:97], v[130:133], v[188:191], v[94:97]
	v_mfma_f32_16x16x32_bf16 v[90:93], v[142:145], v[188:191], v[90:93]
	v_mfma_f32_16x16x32_bf16 v[78:81], v[130:133], v[196:199], v[78:81]
	v_mfma_f32_16x16x32_bf16 v[74:77], v[142:145], v[196:199], v[74:77]
	s_barrier
	s_add_i32 s56, 0, 0x14000
	s_add_i32 s54, s54, s25
	v_add_u32_e32 v168, s56, v210
	v_lshl_add_u64 v[208:209], s[14:15], 0, v[174:175]
	s_mov_b32 m0, s54
	ds_read_b128 v[200:203], v168
	ds_read_b128 v[204:207], v168 offset:1024
	ds_read_b128 v[212:215], v168 offset:2048
	ds_read_b128 v[216:219], v168 offset:3072
	global_load_lds_dwordx4 v[208:209], off
	v_lshl_add_u64 v[220:221], s[14:15], 0, v[178:179]
	s_add_i32 m0, s54, 0x2000
	s_nop 0
	global_load_lds_dwordx4 v[220:221], off
	s_barrier
	s_waitcnt lgkmcnt(0)
	v_mfma_f32_16x16x32_bf16 v[118:121], v[200:203], v[146:149], v[118:121]
	v_mfma_f32_16x16x32_bf16 v[114:117], v[212:215], v[146:149], v[114:117]
	v_mfma_f32_16x16x32_bf16 v[102:105], v[200:203], v[154:157], v[102:105]
	v_mfma_f32_16x16x32_bf16 v[98:101], v[212:215], v[154:157], v[98:101]
	v_mfma_f32_16x16x32_bf16 v[86:89], v[200:203], v[184:187], v[86:89]
	v_mfma_f32_16x16x32_bf16 v[82:85], v[212:215], v[184:187], v[82:85]
	v_mfma_f32_16x16x32_bf16 v[70:73], v[200:203], v[192:195], v[70:73]
	v_mfma_f32_16x16x32_bf16 v[66:69], v[212:215], v[192:195], v[66:69]
	v_mfma_f32_16x16x32_bf16 v[118:121], v[204:207], v[150:153], v[118:121]
	v_mfma_f32_16x16x32_bf16 v[114:117], v[216:219], v[150:153], v[114:117]
	v_mfma_f32_16x16x32_bf16 v[102:105], v[204:207], v[158:161], v[102:105]
	v_mfma_f32_16x16x32_bf16 v[98:101], v[216:219], v[158:161], v[98:101]
	v_mfma_f32_16x16x32_bf16 v[86:89], v[204:207], v[188:191], v[86:89]
	v_mfma_f32_16x16x32_bf16 v[82:85], v[216:219], v[188:191], v[82:85]
	v_mfma_f32_16x16x32_bf16 v[70:73], v[204:207], v[196:199], v[70:73]
	v_mfma_f32_16x16x32_bf16 v[66:69], v[216:219], v[196:199], v[66:69]
	s_barrier
	s_mov_b32 m0, s26
	v_lshl_add_u64 v[236:237], s[18:19], 0, v[172:173]
	ds_read_b128 v[146:149], v211 offset:16384
	ds_read_b128 v[150:153], v211 offset:17408
	ds_read_b128 v[154:157], v211 offset:18432
	ds_read_b128 v[158:161], v211 offset:19456
	ds_read_b128 v[184:187], v211 offset:20480
	ds_read_b128 v[188:191], v211 offset:21504
	ds_read_b128 v[192:195], v211 offset:22528
	ds_read_b128 v[196:199], v211 offset:23552
	global_load_lds_dwordx4 v[236:237], off
	v_lshl_add_u64 v[236:237], s[18:19], 0, v[176:177]
	s_mov_b32 m0, s27
	s_nop 0
	global_load_lds_dwordx4 v[236:237], off
	s_barrier
	s_waitcnt lgkmcnt(0)
	v_mfma_f32_16x16x32_bf16 v[62:65], v[126:129], v[146:149], v[62:65]
	v_mfma_f32_16x16x32_bf16 v[58:61], v[138:141], v[146:149], v[58:61]
	v_mfma_f32_16x16x32_bf16 v[46:49], v[126:129], v[154:157], v[46:49]
	v_mfma_f32_16x16x32_bf16 v[42:45], v[138:141], v[154:157], v[42:45]
	v_mfma_f32_16x16x32_bf16 v[30:33], v[126:129], v[184:187], v[30:33]
	v_mfma_f32_16x16x32_bf16 v[26:29], v[138:141], v[184:187], v[26:29]
	v_mfma_f32_16x16x32_bf16 v[14:17], v[126:129], v[192:195], v[14:17]
	v_mfma_f32_16x16x32_bf16 v[10:13], v[138:141], v[192:195], v[10:13]
	v_mfma_f32_16x16x32_bf16 v[62:65], v[130:133], v[150:153], v[62:65]
	v_mfma_f32_16x16x32_bf16 v[58:61], v[142:145], v[150:153], v[58:61]
	v_mfma_f32_16x16x32_bf16 v[46:49], v[130:133], v[158:161], v[46:49]
	v_mfma_f32_16x16x32_bf16 v[42:45], v[142:145], v[158:161], v[42:45]
	v_mfma_f32_16x16x32_bf16 v[30:33], v[130:133], v[188:191], v[30:33]
	v_mfma_f32_16x16x32_bf16 v[26:29], v[142:145], v[188:191], v[26:29]
	v_mfma_f32_16x16x32_bf16 v[14:17], v[130:133], v[196:199], v[14:17]
	v_mfma_f32_16x16x32_bf16 v[10:13], v[142:145], v[196:199], v[10:13]
	s_barrier
	s_add_u32 s54, s14, 0xb0000
	s_addc_u32 s55, s15, 0
	s_add_i32 s56, s56, s25
	v_lshl_add_u64 v[126:127], s[54:55], 0, v[174:175]
	s_mov_b32 m0, s56
	s_nop 0
	global_load_lds_dwordx4 v[126:127], off
	v_lshl_add_u64 v[126:127], s[54:55], 0, v[178:179]
	s_add_i32 m0, s56, 0x2000
	s_nop 0
	global_load_lds_dwordx4 v[126:127], off
	s_waitcnt vmcnt(6)
	s_barrier
	v_mfma_f32_16x16x32_bf16 v[54:57], v[200:203], v[146:149], v[54:57]
	v_mfma_f32_16x16x32_bf16 v[50:53], v[212:215], v[146:149], v[50:53]
	v_mfma_f32_16x16x32_bf16 v[38:41], v[200:203], v[154:157], v[38:41]
	v_mfma_f32_16x16x32_bf16 v[34:37], v[212:215], v[154:157], v[34:37]
	v_mfma_f32_16x16x32_bf16 v[22:25], v[200:203], v[184:187], v[22:25]
	v_mfma_f32_16x16x32_bf16 v[18:21], v[212:215], v[184:187], v[18:21]
	v_mfma_f32_16x16x32_bf16 v[6:9], v[200:203], v[192:195], v[6:9]
	v_mfma_f32_16x16x32_bf16 v[2:5], v[212:215], v[192:195], v[2:5]
	v_mfma_f32_16x16x32_bf16 v[54:57], v[204:207], v[150:153], v[54:57]
	v_mfma_f32_16x16x32_bf16 v[50:53], v[216:219], v[150:153], v[50:53]
	v_mfma_f32_16x16x32_bf16 v[38:41], v[204:207], v[158:161], v[38:41]
	v_mfma_f32_16x16x32_bf16 v[34:37], v[216:219], v[158:161], v[34:37]
	v_mfma_f32_16x16x32_bf16 v[22:25], v[204:207], v[188:191], v[22:25]
	v_mfma_f32_16x16x32_bf16 v[18:21], v[216:219], v[188:191], v[18:21]
	v_mfma_f32_16x16x32_bf16 v[6:9], v[204:207], v[196:199], v[6:9]
	v_mfma_f32_16x16x32_bf16 v[2:5], v[216:219], v[196:199], v[2:5]
	s_barrier
	s_add_i32 s54, 0, 0x18000
	v_add_u32_e32 v142, s54, v210
	ds_read_b128 v[126:129], v142
	ds_read_b128 v[130:133], v142 offset:1024
	ds_read_b128 v[138:141], v142 offset:2048
	ds_read_b128 v[142:145], v142 offset:3072
	s_add_u32 s18, s18, 0x4000
	s_addc_u32 s19, s19, 0
	s_mov_b32 m0, s28
	v_lshl_add_u64 v[200:201], s[18:19], 0, v[172:173]
	ds_read_b128 v[146:149], v211 offset:32768
	ds_read_b128 v[150:153], v211 offset:33792
	ds_read_b128 v[154:157], v211 offset:34816
	ds_read_b128 v[158:161], v211 offset:35840
	ds_read_b128 v[184:187], v211 offset:36864
	ds_read_b128 v[188:191], v211 offset:37888
	ds_read_b128 v[192:195], v211 offset:38912
	ds_read_b128 v[196:199], v211 offset:39936
	global_load_lds_dwordx4 v[200:201], off
	v_lshl_add_u64 v[200:201], s[18:19], 0, v[176:177]
	s_mov_b32 m0, s29
	s_nop 0
	global_load_lds_dwordx4 v[200:201], off
	s_waitcnt lgkmcnt(8)
	s_barrier
	s_waitcnt lgkmcnt(0)
	v_mfma_f32_16x16x32_bf16 v[134:137], v[126:129], v[146:149], v[134:137]
	v_mfma_f32_16x16x32_bf16 v[122:125], v[138:141], v[146:149], v[122:125]
	v_mfma_f32_16x16x32_bf16 v[110:113], v[126:129], v[154:157], v[110:113]
	v_mfma_f32_16x16x32_bf16 v[106:109], v[138:141], v[154:157], v[106:109]
	v_mfma_f32_16x16x32_bf16 v[94:97], v[126:129], v[184:187], v[94:97]
	v_mfma_f32_16x16x32_bf16 v[90:93], v[138:141], v[184:187], v[90:93]
	v_mfma_f32_16x16x32_bf16 v[78:81], v[126:129], v[192:195], v[78:81]
	v_mfma_f32_16x16x32_bf16 v[74:77], v[138:141], v[192:195], v[74:77]
	v_mfma_f32_16x16x32_bf16 v[134:137], v[130:133], v[150:153], v[134:137]
	v_mfma_f32_16x16x32_bf16 v[122:125], v[142:145], v[150:153], v[122:125]
	v_mfma_f32_16x16x32_bf16 v[110:113], v[130:133], v[158:161], v[110:113]
	v_mfma_f32_16x16x32_bf16 v[106:109], v[142:145], v[158:161], v[106:109]
	v_mfma_f32_16x16x32_bf16 v[94:97], v[130:133], v[188:191], v[94:97]
	v_mfma_f32_16x16x32_bf16 v[90:93], v[142:145], v[188:191], v[90:93]
	v_mfma_f32_16x16x32_bf16 v[78:81], v[130:133], v[196:199], v[78:81]
	v_mfma_f32_16x16x32_bf16 v[74:77], v[142:145], v[196:199], v[74:77]
	s_barrier
	s_add_i32 s18, 0, 0x1c000
	s_add_i32 s19, s54, s25
	v_add_u32_e32 v168, s18, v210
	v_lshl_add_u64 v[208:209], v[208:209], 0, s[84:85]
	s_mov_b32 m0, s19
	ds_read_b128 v[200:203], v168
	ds_read_b128 v[204:207], v168 offset:1024
	ds_read_b128 v[212:215], v168 offset:2048
	ds_read_b128 v[216:219], v168 offset:3072
	global_load_lds_dwordx4 v[208:209], off
	v_lshl_add_u64 v[208:209], v[220:221], 0, s[84:85]
	s_add_i32 m0, s19, 0x2000
	s_nop 0
	global_load_lds_dwordx4 v[208:209], off
	s_barrier
	s_waitcnt lgkmcnt(0)
	v_mfma_f32_16x16x32_bf16 v[118:121], v[200:203], v[146:149], v[118:121]
	v_mfma_f32_16x16x32_bf16 v[114:117], v[212:215], v[146:149], v[114:117]
	v_mfma_f32_16x16x32_bf16 v[102:105], v[200:203], v[154:157], v[102:105]
	v_mfma_f32_16x16x32_bf16 v[98:101], v[212:215], v[154:157], v[98:101]
	v_mfma_f32_16x16x32_bf16 v[86:89], v[200:203], v[184:187], v[86:89]
	v_mfma_f32_16x16x32_bf16 v[82:85], v[212:215], v[184:187], v[82:85]
	v_mfma_f32_16x16x32_bf16 v[70:73], v[200:203], v[192:195], v[70:73]
	v_mfma_f32_16x16x32_bf16 v[66:69], v[212:215], v[192:195], v[66:69]
	v_mfma_f32_16x16x32_bf16 v[118:121], v[204:207], v[150:153], v[118:121]
	v_mfma_f32_16x16x32_bf16 v[114:117], v[216:219], v[150:153], v[114:117]
	v_mfma_f32_16x16x32_bf16 v[102:105], v[204:207], v[158:161], v[102:105]
	v_mfma_f32_16x16x32_bf16 v[98:101], v[216:219], v[158:161], v[98:101]
	v_mfma_f32_16x16x32_bf16 v[86:89], v[204:207], v[188:191], v[86:89]
	v_mfma_f32_16x16x32_bf16 v[82:85], v[216:219], v[188:191], v[82:85]
	v_mfma_f32_16x16x32_bf16 v[70:73], v[204:207], v[196:199], v[70:73]
	v_mfma_f32_16x16x32_bf16 v[66:69], v[216:219], v[196:199], v[66:69]
	s_barrier
	s_mov_b32 m0, s41
	v_lshl_add_u64 v[208:209], s[16:17], 0, v[172:173]
	ds_read_b128 v[146:149], v211 offset:49152
	ds_read_b128 v[150:153], v211 offset:50176
	ds_read_b128 v[154:157], v211 offset:51200
	ds_read_b128 v[158:161], v211 offset:52224
	ds_read_b128 v[184:187], v211 offset:53248
	ds_read_b128 v[188:191], v211 offset:54272
	ds_read_b128 v[192:195], v211 offset:55296
	ds_read_b128 v[196:199], v211 offset:56320
	global_load_lds_dwordx4 v[208:209], off
	v_lshl_add_u64 v[208:209], s[16:17], 0, v[176:177]
	s_mov_b32 m0, s42
	s_nop 0
	global_load_lds_dwordx4 v[208:209], off
	s_barrier
	s_waitcnt lgkmcnt(0)
	v_mfma_f32_16x16x32_bf16 v[62:65], v[126:129], v[146:149], v[62:65]
	v_mfma_f32_16x16x32_bf16 v[58:61], v[138:141], v[146:149], v[58:61]
	v_mfma_f32_16x16x32_bf16 v[46:49], v[126:129], v[154:157], v[46:49]
	v_mfma_f32_16x16x32_bf16 v[42:45], v[138:141], v[154:157], v[42:45]
	v_mfma_f32_16x16x32_bf16 v[30:33], v[126:129], v[184:187], v[30:33]
	v_mfma_f32_16x16x32_bf16 v[26:29], v[138:141], v[184:187], v[26:29]
	v_mfma_f32_16x16x32_bf16 v[14:17], v[126:129], v[192:195], v[14:17]
	v_mfma_f32_16x16x32_bf16 v[10:13], v[138:141], v[192:195], v[10:13]
	v_mfma_f32_16x16x32_bf16 v[62:65], v[130:133], v[150:153], v[62:65]
	v_mfma_f32_16x16x32_bf16 v[58:61], v[142:145], v[150:153], v[58:61]
	v_mfma_f32_16x16x32_bf16 v[46:49], v[130:133], v[158:161], v[46:49]
	v_mfma_f32_16x16x32_bf16 v[42:45], v[142:145], v[158:161], v[42:45]
	v_mfma_f32_16x16x32_bf16 v[30:33], v[130:133], v[188:191], v[30:33]
	v_mfma_f32_16x16x32_bf16 v[26:29], v[142:145], v[188:191], v[26:29]
	v_mfma_f32_16x16x32_bf16 v[14:17], v[130:133], v[196:199], v[14:17]
	v_mfma_f32_16x16x32_bf16 v[10:13], v[142:145], v[196:199], v[10:13]
	s_barrier
	s_add_u32 s14, s14, 0xb0080
	s_addc_u32 s15, s15, 0
	s_add_i32 s16, s18, s25
	v_lshl_add_u64 v[126:127], s[14:15], 0, v[174:175]
	s_mov_b32 m0, s16
	s_nop 0
	global_load_lds_dwordx4 v[126:127], off
	v_lshl_add_u64 v[126:127], s[14:15], 0, v[178:179]
	s_add_i32 m0, s16, 0x2000
	s_nop 0
	global_load_lds_dwordx4 v[126:127], off
	s_waitcnt vmcnt(6)
	s_barrier
	v_mfma_f32_16x16x32_bf16 v[54:57], v[200:203], v[146:149], v[54:57]
	v_mfma_f32_16x16x32_bf16 v[50:53], v[212:215], v[146:149], v[50:53]
	v_mfma_f32_16x16x32_bf16 v[38:41], v[200:203], v[154:157], v[38:41]
	v_mfma_f32_16x16x32_bf16 v[34:37], v[212:215], v[154:157], v[34:37]
	v_mfma_f32_16x16x32_bf16 v[22:25], v[200:203], v[184:187], v[22:25]
	v_mfma_f32_16x16x32_bf16 v[18:21], v[212:215], v[184:187], v[18:21]
	v_mfma_f32_16x16x32_bf16 v[6:9], v[200:203], v[192:195], v[6:9]
	v_mfma_f32_16x16x32_bf16 v[2:5], v[212:215], v[192:195], v[2:5]
	v_mfma_f32_16x16x32_bf16 v[54:57], v[204:207], v[150:153], v[54:57]
	v_mfma_f32_16x16x32_bf16 v[50:53], v[216:219], v[150:153], v[50:53]
	v_mfma_f32_16x16x32_bf16 v[38:41], v[204:207], v[158:161], v[38:41]
	v_mfma_f32_16x16x32_bf16 v[34:37], v[216:219], v[158:161], v[34:37]
	v_mfma_f32_16x16x32_bf16 v[22:25], v[204:207], v[188:191], v[22:25]
	v_mfma_f32_16x16x32_bf16 v[18:21], v[216:219], v[188:191], v[18:21]
	v_mfma_f32_16x16x32_bf16 v[6:9], v[204:207], v[196:199], v[6:9]
	v_mfma_f32_16x16x32_bf16 v[2:5], v[216:219], v[196:199], v[2:5]
	s_barrier
	s_add_u32 s51, s51, 0x100
	s_addc_u32 s52, s52, 0
	s_add_u32 s12, s12, 0x10000
	s_addc_u32 s13, s13, 0
	s_cmp_ge_i32 s53, s38
	s_mov_b32 s14, s53
	s_cbranch_scc0 .LBB0_844

.LBB0_874:
	s_add_i32 s43, s14, 2
	s_add_u32 s15, s12, 0xfffc0080
	s_addc_u32 s16, s13, -1
	s_add_i32 s44, 0, 0x10000
	v_add_u32_e32 v102, s44, v171
	ds_read_b128 v[82:85], v102
	ds_read_b128 v[86:89], v102 offset:1024
	ds_read_b128 v[98:101], v102 offset:2048
	ds_read_b128 v[102:105], v102 offset:3072
	s_cmp_eq_u32 s31, s14
	s_cselect_b32 s14, s40, s41
	s_cselect_b32 s17, s3, s16
	s_cselect_b32 s16, s5, s15
	s_cselect_b32 s15, s39, s42
	v_lshl_add_u64 v[160:161], s[12:13], 0, v[154:155]
	s_add_i32 m0, s11, 0xc000
	ds_read_b128 v[174:177], v173
	ds_read_b128 v[178:181], v173 offset:1024
	ds_read_b128 v[182:185], v173 offset:2048
	ds_read_b128 v[186:189], v173 offset:3072
	ds_read_b128 v[190:193], v173 offset:4096
	ds_read_b128 v[194:197], v173 offset:5120
	ds_read_b128 v[198:201], v173 offset:6144
	ds_read_b128 v[202:205], v173 offset:7168
	global_load_lds_dwordx4 v[160:161], off
	v_lshl_add_u64 v[160:161], s[12:13], 0, v[156:157]
	s_add_i32 m0, s11, 0xe000
	s_nop 0
	global_load_lds_dwordx4 v[160:161], off
	s_waitcnt lgkmcnt(8)
	s_barrier
	s_waitcnt lgkmcnt(0)
	v_mfma_f32_16x16x32_bf16 v[138:141], v[82:85], v[174:177], v[138:141]
	v_mfma_f32_16x16x32_bf16 v[134:137], v[98:101], v[174:177], v[134:137]
	v_mfma_f32_16x16x32_bf16 v[126:129], v[82:85], v[182:185], v[126:129]
	v_mfma_f32_16x16x32_bf16 v[118:121], v[98:101], v[182:185], v[118:121]
	v_mfma_f32_16x16x32_bf16 v[110:113], v[82:85], v[190:193], v[110:113]
	v_mfma_f32_16x16x32_bf16 v[94:97], v[98:101], v[190:193], v[94:97]
	v_mfma_f32_16x16x32_bf16 v[78:81], v[82:85], v[198:201], v[78:81]
	v_mfma_f32_16x16x32_bf16 v[70:73], v[98:101], v[198:201], v[70:73]
	v_mfma_f32_16x16x32_bf16 v[138:141], v[86:89], v[178:181], v[138:141]
	v_mfma_f32_16x16x32_bf16 v[134:137], v[102:105], v[178:181], v[134:137]
	v_mfma_f32_16x16x32_bf16 v[126:129], v[86:89], v[186:189], v[126:129]
	v_mfma_f32_16x16x32_bf16 v[118:121], v[102:105], v[186:189], v[118:121]
	v_mfma_f32_16x16x32_bf16 v[110:113], v[86:89], v[194:197], v[110:113]
	v_mfma_f32_16x16x32_bf16 v[94:97], v[102:105], v[194:197], v[94:97]
	v_mfma_f32_16x16x32_bf16 v[78:81], v[86:89], v[202:205], v[78:81]
	v_mfma_f32_16x16x32_bf16 v[70:73], v[102:105], v[202:205], v[70:73]
	s_barrier
	s_add_i32 s46, 0, 0x14000
	s_add_i32 s44, s44, s19
	v_add_u32_e32 v158, s46, v171
	v_lshl_add_u64 v[160:161], s[14:15], 0, v[150:151]
	s_mov_b32 m0, s44
	ds_read_b128 v[206:209], v158
	ds_read_b128 v[210:213], v158 offset:1024
	ds_read_b128 v[214:217], v158 offset:2048
	ds_read_b128 v[218:221], v158 offset:3072
	global_load_lds_dwordx4 v[160:161], off
	v_lshl_add_u64 v[236:237], s[14:15], 0, v[146:147]
	s_add_i32 m0, s44, 0x2000
	s_nop 0
	global_load_lds_dwordx4 v[236:237], off
	s_barrier
	s_waitcnt lgkmcnt(0)
	v_mfma_f32_16x16x32_bf16 v[142:145], v[206:209], v[174:177], v[142:145]
	v_mfma_f32_16x16x32_bf16 v[130:133], v[214:217], v[174:177], v[130:133]
	v_mfma_f32_16x16x32_bf16 v[122:125], v[206:209], v[182:185], v[122:125]
	v_mfma_f32_16x16x32_bf16 v[114:117], v[214:217], v[182:185], v[114:117]
	v_mfma_f32_16x16x32_bf16 v[106:109], v[206:209], v[190:193], v[106:109]
	v_mfma_f32_16x16x32_bf16 v[90:93], v[214:217], v[190:193], v[90:93]
	v_mfma_f32_16x16x32_bf16 v[74:77], v[206:209], v[198:201], v[74:77]
	v_mfma_f32_16x16x32_bf16 v[66:69], v[214:217], v[198:201], v[66:69]
	v_mfma_f32_16x16x32_bf16 v[142:145], v[210:213], v[178:181], v[142:145]
	v_mfma_f32_16x16x32_bf16 v[130:133], v[218:221], v[178:181], v[130:133]
	v_mfma_f32_16x16x32_bf16 v[122:125], v[210:213], v[186:189], v[122:125]
	v_mfma_f32_16x16x32_bf16 v[114:117], v[218:221], v[186:189], v[114:117]
	v_mfma_f32_16x16x32_bf16 v[106:109], v[210:213], v[194:197], v[106:109]
	v_mfma_f32_16x16x32_bf16 v[90:93], v[218:221], v[194:197], v[90:93]
	v_mfma_f32_16x16x32_bf16 v[74:77], v[210:213], v[202:205], v[74:77]
	v_mfma_f32_16x16x32_bf16 v[66:69], v[218:221], v[202:205], v[66:69]
	s_barrier
	s_mov_b32 m0, s11
	v_lshl_add_u64 v[238:239], s[16:17], 0, v[152:153]
	ds_read_b128 v[174:177], v173 offset:16384
	ds_read_b128 v[178:181], v173 offset:17408
	ds_read_b128 v[182:185], v173 offset:18432
	ds_read_b128 v[186:189], v173 offset:19456
	ds_read_b128 v[190:193], v173 offset:20480
	ds_read_b128 v[194:197], v173 offset:21504
	ds_read_b128 v[198:201], v173 offset:22528
	ds_read_b128 v[202:205], v173 offset:23552
	global_load_lds_dwordx4 v[238:239], off
	v_lshl_add_u64 v[240:241], s[16:17], 0, v[148:149]
	s_mov_b32 m0, s21
	s_nop 0
	global_load_lds_dwordx4 v[240:241], off
	s_barrier
	s_waitcnt lgkmcnt(0)
	v_mfma_f32_16x16x32_bf16 v[62:65], v[82:85], v[174:177], v[62:65]
	v_mfma_f32_16x16x32_bf16 v[54:57], v[98:101], v[174:177], v[54:57]
	v_mfma_f32_16x16x32_bf16 v[46:49], v[82:85], v[182:185], v[46:49]
	v_mfma_f32_16x16x32_bf16 v[38:41], v[98:101], v[182:185], v[38:41]
	v_mfma_f32_16x16x32_bf16 v[30:33], v[82:85], v[190:193], v[30:33]
	v_mfma_f32_16x16x32_bf16 v[22:25], v[98:101], v[190:193], v[22:25]
	v_mfma_f32_16x16x32_bf16 v[14:17], v[82:85], v[198:201], v[14:17]
	v_mfma_f32_16x16x32_bf16 v[6:9], v[98:101], v[198:201], v[6:9]
	v_mfma_f32_16x16x32_bf16 v[62:65], v[86:89], v[178:181], v[62:65]
	v_mfma_f32_16x16x32_bf16 v[54:57], v[102:105], v[178:181], v[54:57]
	v_mfma_f32_16x16x32_bf16 v[46:49], v[86:89], v[186:189], v[46:49]
	v_mfma_f32_16x16x32_bf16 v[38:41], v[102:105], v[186:189], v[38:41]
	v_mfma_f32_16x16x32_bf16 v[30:33], v[86:89], v[194:197], v[30:33]
	v_mfma_f32_16x16x32_bf16 v[22:25], v[102:105], v[194:197], v[22:25]
	v_mfma_f32_16x16x32_bf16 v[14:17], v[86:89], v[202:205], v[14:17]
	v_mfma_f32_16x16x32_bf16 v[6:9], v[102:105], v[202:205], v[6:9]
	s_barrier
	s_add_u32 s44, s14, 0x40000
	s_addc_u32 s45, s15, 0
	s_add_i32 s46, s46, s19
	v_lshl_add_u64 v[82:83], s[44:45], 0, v[150:151]
	s_mov_b32 m0, s46
	s_nop 0
	global_load_lds_dwordx4 v[82:83], off
	v_lshl_add_u64 v[82:83], s[44:45], 0, v[146:147]
	s_add_i32 m0, s46, 0x2000
	s_nop 0
	global_load_lds_dwordx4 v[82:83], off
	s_waitcnt vmcnt(6)
	s_barrier
	v_mfma_f32_16x16x32_bf16 v[58:61], v[206:209], v[174:177], v[58:61]
	v_mfma_f32_16x16x32_bf16 v[50:53], v[214:217], v[174:177], v[50:53]
	v_mfma_f32_16x16x32_bf16 v[42:45], v[206:209], v[182:185], v[42:45]
	v_mfma_f32_16x16x32_bf16 v[34:37], v[214:217], v[182:185], v[34:37]
	v_mfma_f32_16x16x32_bf16 v[26:29], v[206:209], v[190:193], v[26:29]
	v_mfma_f32_16x16x32_bf16 v[18:21], v[214:217], v[190:193], v[18:21]
	v_mfma_f32_16x16x32_bf16 v[10:13], v[206:209], v[198:201], v[10:13]
	v_mfma_f32_16x16x32_bf16 v[2:5], v[214:217], v[198:201], v[2:5]
	v_mfma_f32_16x16x32_bf16 v[58:61], v[210:213], v[178:181], v[58:61]
	v_mfma_f32_16x16x32_bf16 v[50:53], v[218:221], v[178:181], v[50:53]
	v_mfma_f32_16x16x32_bf16 v[42:45], v[210:213], v[186:189], v[42:45]
	v_mfma_f32_16x16x32_bf16 v[34:37], v[218:221], v[186:189], v[34:37]
	v_mfma_f32_16x16x32_bf16 v[26:29], v[210:213], v[194:197], v[26:29]
	v_mfma_f32_16x16x32_bf16 v[18:21], v[218:221], v[194:197], v[18:21]
	v_mfma_f32_16x16x32_bf16 v[10:13], v[210:213], v[202:205], v[10:13]
	v_mfma_f32_16x16x32_bf16 v[2:5], v[218:221], v[202:205], v[2:5]
	s_barrier
	s_add_i32 s44, 0, 0x18000
	v_add_u32_e32 v102, s44, v171
	ds_read_b128 v[82:85], v102
	ds_read_b128 v[86:89], v102 offset:1024
	ds_read_b128 v[98:101], v102 offset:2048
	ds_read_b128 v[102:105], v102 offset:3072
	s_add_u32 s16, s16, 0x40000
	s_addc_u32 s17, s17, 0
	s_mov_b32 m0, s24
	v_lshl_add_u64 v[206:207], s[16:17], 0, v[152:153]
	ds_read_b128 v[174:177], v173 offset:32768
	ds_read_b128 v[178:181], v173 offset:33792
	ds_read_b128 v[182:185], v173 offset:34816
	ds_read_b128 v[186:189], v173 offset:35840
	ds_read_b128 v[190:193], v173 offset:36864
	ds_read_b128 v[194:197], v173 offset:37888
	ds_read_b128 v[198:201], v173 offset:38912
	ds_read_b128 v[202:205], v173 offset:39936
	global_load_lds_dwordx4 v[206:207], off
	v_lshl_add_u64 v[206:207], s[16:17], 0, v[148:149]
	s_mov_b32 m0, s25
	s_nop 0
	global_load_lds_dwordx4 v[206:207], off
	s_waitcnt lgkmcnt(8)
	s_barrier
	s_waitcnt lgkmcnt(0)
	v_mfma_f32_16x16x32_bf16 v[138:141], v[82:85], v[174:177], v[138:141]
	v_mfma_f32_16x16x32_bf16 v[134:137], v[98:101], v[174:177], v[134:137]
	v_mfma_f32_16x16x32_bf16 v[126:129], v[82:85], v[182:185], v[126:129]
	v_mfma_f32_16x16x32_bf16 v[118:121], v[98:101], v[182:185], v[118:121]
	v_mfma_f32_16x16x32_bf16 v[110:113], v[82:85], v[190:193], v[110:113]
	v_mfma_f32_16x16x32_bf16 v[94:97], v[98:101], v[190:193], v[94:97]
	v_mfma_f32_16x16x32_bf16 v[78:81], v[82:85], v[198:201], v[78:81]
	v_mfma_f32_16x16x32_bf16 v[70:73], v[98:101], v[198:201], v[70:73]
	v_mfma_f32_16x16x32_bf16 v[138:141], v[86:89], v[178:181], v[138:141]
	v_mfma_f32_16x16x32_bf16 v[134:137], v[102:105], v[178:181], v[134:137]
	v_mfma_f32_16x16x32_bf16 v[126:129], v[86:89], v[186:189], v[126:129]
	v_mfma_f32_16x16x32_bf16 v[118:121], v[102:105], v[186:189], v[118:121]
	v_mfma_f32_16x16x32_bf16 v[110:113], v[86:89], v[194:197], v[110:113]
	v_mfma_f32_16x16x32_bf16 v[94:97], v[102:105], v[194:197], v[94:97]
	v_mfma_f32_16x16x32_bf16 v[78:81], v[86:89], v[202:205], v[78:81]
	v_mfma_f32_16x16x32_bf16 v[70:73], v[102:105], v[202:205], v[70:73]
	s_barrier
	s_add_i32 s16, 0, 0x1c000
	s_add_i32 s17, s44, s19
	v_add_u32_e32 v158, s16, v171
	v_lshl_add_u64 v[160:161], v[160:161], 0, s[84:85]
	s_mov_b32 m0, s17
	ds_read_b128 v[206:209], v158
	ds_read_b128 v[210:213], v158 offset:1024
	ds_read_b128 v[214:217], v158 offset:2048
	ds_read_b128 v[218:221], v158 offset:3072
	global_load_lds_dwordx4 v[160:161], off
	v_lshl_add_u64 v[160:161], v[236:237], 0, s[84:85]
	s_add_i32 m0, s17, 0x2000
	s_nop 0
	global_load_lds_dwordx4 v[160:161], off
	s_barrier
	s_waitcnt lgkmcnt(0)
	v_mfma_f32_16x16x32_bf16 v[142:145], v[206:209], v[174:177], v[142:145]
	v_mfma_f32_16x16x32_bf16 v[130:133], v[214:217], v[174:177], v[130:133]
	v_mfma_f32_16x16x32_bf16 v[122:125], v[206:209], v[182:185], v[122:125]
	v_mfma_f32_16x16x32_bf16 v[114:117], v[214:217], v[182:185], v[114:117]
	v_mfma_f32_16x16x32_bf16 v[106:109], v[206:209], v[190:193], v[106:109]
	v_mfma_f32_16x16x32_bf16 v[90:93], v[214:217], v[190:193], v[90:93]
	v_mfma_f32_16x16x32_bf16 v[74:77], v[206:209], v[198:201], v[74:77]
	v_mfma_f32_16x16x32_bf16 v[66:69], v[214:217], v[198:201], v[66:69]
	v_mfma_f32_16x16x32_bf16 v[142:145], v[210:213], v[178:181], v[142:145]
	v_mfma_f32_16x16x32_bf16 v[130:133], v[218:221], v[178:181], v[130:133]
	v_mfma_f32_16x16x32_bf16 v[122:125], v[210:213], v[186:189], v[122:125]
	v_mfma_f32_16x16x32_bf16 v[114:117], v[218:221], v[186:189], v[114:117]
	v_mfma_f32_16x16x32_bf16 v[106:109], v[210:213], v[194:197], v[106:109]
	v_mfma_f32_16x16x32_bf16 v[90:93], v[218:221], v[194:197], v[90:93]
	v_mfma_f32_16x16x32_bf16 v[74:77], v[210:213], v[202:205], v[74:77]
	v_mfma_f32_16x16x32_bf16 v[66:69], v[218:221], v[202:205], v[66:69]
	s_barrier
	s_mov_b32 m0, s29
	v_lshl_add_u64 v[160:161], v[238:239], 0, s[84:85]
	ds_read_b128 v[174:177], v173 offset:49152
	ds_read_b128 v[178:181], v173 offset:50176
	ds_read_b128 v[182:185], v173 offset:51200
	ds_read_b128 v[186:189], v173 offset:52224
	ds_read_b128 v[190:193], v173 offset:53248
	ds_read_b128 v[194:197], v173 offset:54272
	ds_read_b128 v[198:201], v173 offset:55296
	ds_read_b128 v[202:205], v173 offset:56320
	global_load_lds_dwordx4 v[160:161], off
	v_lshl_add_u64 v[160:161], v[240:241], 0, s[84:85]
	s_mov_b32 m0, s30
	s_nop 0
	global_load_lds_dwordx4 v[160:161], off
	s_barrier
	s_waitcnt lgkmcnt(0)
	v_mfma_f32_16x16x32_bf16 v[62:65], v[82:85], v[174:177], v[62:65]
	v_mfma_f32_16x16x32_bf16 v[54:57], v[98:101], v[174:177], v[54:57]
	v_mfma_f32_16x16x32_bf16 v[46:49], v[82:85], v[182:185], v[46:49]
	v_mfma_f32_16x16x32_bf16 v[38:41], v[98:101], v[182:185], v[38:41]
	v_mfma_f32_16x16x32_bf16 v[30:33], v[82:85], v[190:193], v[30:33]
	v_mfma_f32_16x16x32_bf16 v[22:25], v[98:101], v[190:193], v[22:25]
	v_mfma_f32_16x16x32_bf16 v[14:17], v[82:85], v[198:201], v[14:17]
	v_mfma_f32_16x16x32_bf16 v[6:9], v[98:101], v[198:201], v[6:9]
	v_mfma_f32_16x16x32_bf16 v[62:65], v[86:89], v[178:181], v[62:65]
	v_mfma_f32_16x16x32_bf16 v[54:57], v[102:105], v[178:181], v[54:57]
	v_mfma_f32_16x16x32_bf16 v[46:49], v[86:89], v[186:189], v[46:49]
	v_mfma_f32_16x16x32_bf16 v[38:41], v[102:105], v[186:189], v[38:41]
	v_mfma_f32_16x16x32_bf16 v[30:33], v[86:89], v[194:197], v[30:33]
	v_mfma_f32_16x16x32_bf16 v[22:25], v[102:105], v[194:197], v[22:25]
	v_mfma_f32_16x16x32_bf16 v[14:17], v[86:89], v[202:205], v[14:17]
	v_mfma_f32_16x16x32_bf16 v[6:9], v[102:105], v[202:205], v[6:9]
	s_barrier
	s_add_u32 s14, s14, 0x40080
	s_addc_u32 s15, s15, 0
	s_add_i32 s16, s16, s19
	v_lshl_add_u64 v[82:83], s[14:15], 0, v[150:151]
	s_mov_b32 m0, s16
	s_nop 0
	global_load_lds_dwordx4 v[82:83], off
	v_lshl_add_u64 v[82:83], s[14:15], 0, v[146:147]
	s_add_i32 m0, s16, 0x2000
	s_nop 0
	global_load_lds_dwordx4 v[82:83], off
	s_waitcnt vmcnt(6)
	s_barrier
	v_mfma_f32_16x16x32_bf16 v[58:61], v[206:209], v[174:177], v[58:61]
	v_mfma_f32_16x16x32_bf16 v[50:53], v[214:217], v[174:177], v[50:53]
	v_mfma_f32_16x16x32_bf16 v[42:45], v[206:209], v[182:185], v[42:45]
	v_mfma_f32_16x16x32_bf16 v[34:37], v[214:217], v[182:185], v[34:37]
	v_mfma_f32_16x16x32_bf16 v[26:29], v[206:209], v[190:193], v[26:29]
	v_mfma_f32_16x16x32_bf16 v[18:21], v[214:217], v[190:193], v[18:21]
	v_mfma_f32_16x16x32_bf16 v[10:13], v[206:209], v[198:201], v[10:13]
	v_mfma_f32_16x16x32_bf16 v[2:5], v[214:217], v[198:201], v[2:5]
	v_mfma_f32_16x16x32_bf16 v[58:61], v[210:213], v[178:181], v[58:61]
	v_mfma_f32_16x16x32_bf16 v[50:53], v[218:221], v[178:181], v[50:53]
	v_mfma_f32_16x16x32_bf16 v[42:45], v[210:213], v[186:189], v[42:45]
	v_mfma_f32_16x16x32_bf16 v[34:37], v[218:221], v[186:189], v[34:37]
	v_mfma_f32_16x16x32_bf16 v[26:29], v[210:213], v[194:197], v[26:29]
	v_mfma_f32_16x16x32_bf16 v[18:21], v[218:221], v[194:197], v[18:21]
	v_mfma_f32_16x16x32_bf16 v[10:13], v[210:213], v[202:205], v[10:13]
	v_mfma_f32_16x16x32_bf16 v[2:5], v[218:221], v[202:205], v[2:5]
	s_barrier
	s_add_u32 s12, s12, 0x100
	s_addc_u32 s13, s13, 0
	s_add_u32 s41, s41, 0x100
	s_addc_u32 s42, s42, 0
	s_cmp_ge_i32 s43, s26
	s_mov_b32 s14, s43
	s_cbranch_scc0 .LBB0_874
	s_branch .LBB0_869
